# v29 + in the GEMM K-loop load segments the address add is placed between the M0 write and its LDS-DMA load (s_nop removed, 8 per loop iteration)
# speedup vs baseline: 1.0017x; 1.0017x over previous
.LBB0_291:
	s_ashr_i32 s5, s4, 31
	s_lshl_b64 s[28:29], s[4:5], 20
	s_add_u32 s28, s14, s28
	s_addc_u32 s29, s15, s29
	s_and_b64 s[34:35], s[22:23], exec
	s_cselect_b32 s5, s29, s37
	s_cselect_b32 s8, s28, s36
	s_ashr_i32 s19, s18, 31
	s_lshl_b64 s[34:35], s[18:19], 20
	v_readlane_b32 s19, v245, 38
	s_add_u32 s34, s19, s34
	v_readlane_b32 s19, v245, 39
	s_addc_u32 s35, s19, s35
	s_and_b64 s[44:45], s[22:23], exec
	s_cselect_b32 s19, s35, s43
	s_cselect_b32 s21, s34, s42
	s_add_u32 s36, s36, 0x80080
	s_addc_u32 s37, s37, 0
	s_add_u32 s41, s42, 0x100
	s_addc_u32 s46, s43, 0
	s_mov_b32 s47, -2
	s_waitcnt vmcnt(0) lgkmcnt(0)
	s_add_u32 s42, s36, 0xfff80080
	s_addc_u32 s43, s37, -1
	s_add_i32 s48, 0, 0x10000
	s_cmp_eq_u32 s47, 28
	s_cselect_b32 s45, s5, s43
	s_cselect_b32 s44, s8, s42
	s_cselect_b32 s43, s19, s46
	s_cselect_b32 s42, s21, s41
	s_add_i32 s50, 0, 0x14000
	v_add_u32_e32 v158, s48, v147
	v_add_u32_e32 v162, s50, v147
	ds_read_b128 v[130:133], v158
	ds_read_b128 v[134:137], v158 offset:1024
	ds_read_b128 v[152:155], v158 offset:2048
	ds_read_b128 v[158:161], v158 offset:3072
	ds_read_b128 v[164:167], v162
	ds_read_b128 v[180:183], v162 offset:1024
	ds_read_b128 v[184:187], v162 offset:2048
	ds_read_b128 v[188:191], v162 offset:3072
	v_lshl_add_u64 v[168:169], s[36:37], 0, v[148:149]
	s_add_i32 m0, s11, 0xc000
	ds_read_b128 v[192:195], v157
	ds_read_b128 v[196:199], v157 offset:1024
	ds_read_b128 v[200:203], v157 offset:2048
	ds_read_b128 v[204:207], v157 offset:3072
	ds_read_b128 v[208:211], v157 offset:4096
	ds_read_b128 v[212:215], v157 offset:5120
	ds_read_b128 v[216:219], v157 offset:6144
	ds_read_b128 v[220:223], v157 offset:7168
	global_load_lds_dwordx4 v[168:169], off
	s_add_i32 m0, s11, 0xe000
	v_lshl_add_u64 v[168:169], s[36:37], 0, v[150:151]
	global_load_lds_dwordx4 v[168:169], off
	s_waitcnt vmcnt(8)
	s_waitcnt lgkmcnt(0)
	s_barrier
	s_setprio 1
	s_waitcnt lgkmcnt(0)
	v_mfma_f32_16x16x32_bf16 v[126:129], v[130:133], v[192:195], 0
	v_mfma_f32_16x16x32_bf16 v[122:125], v[152:155], v[192:195], 0
	v_mfma_f32_16x16x32_bf16 v[110:113], v[130:133], v[200:203], 0
	v_mfma_f32_16x16x32_bf16 v[106:109], v[152:155], v[200:203], 0
	v_mfma_f32_16x16x32_bf16 v[94:97], v[130:133], v[208:211], 0
	v_mfma_f32_16x16x32_bf16 v[90:93], v[152:155], v[208:211], 0
	v_mfma_f32_16x16x32_bf16 v[78:81], v[130:133], v[216:219], 0
	v_mfma_f32_16x16x32_bf16 v[74:77], v[152:155], v[216:219], 0
	v_mfma_f32_16x16x32_bf16 v[126:129], v[134:137], v[196:199], v[126:129]
	v_mfma_f32_16x16x32_bf16 v[122:125], v[158:161], v[196:199], v[122:125]
	v_mfma_f32_16x16x32_bf16 v[110:113], v[134:137], v[204:207], v[110:113]
	v_mfma_f32_16x16x32_bf16 v[106:109], v[158:161], v[204:207], v[106:109]
	v_mfma_f32_16x16x32_bf16 v[94:97], v[134:137], v[212:215], v[94:97]
	v_mfma_f32_16x16x32_bf16 v[90:93], v[158:161], v[212:215], v[90:93]
	v_mfma_f32_16x16x32_bf16 v[78:81], v[134:137], v[220:223], v[78:81]
	v_mfma_f32_16x16x32_bf16 v[74:77], v[158:161], v[220:223], v[74:77]
	s_setprio 0
	s_setprio 1
	v_mfma_f32_16x16x32_bf16 v[118:121], v[164:167], v[192:195], 0
	v_mfma_f32_16x16x32_bf16 v[114:117], v[184:187], v[192:195], 0
	v_mfma_f32_16x16x32_bf16 v[102:105], v[164:167], v[200:203], 0
	v_mfma_f32_16x16x32_bf16 v[98:101], v[184:187], v[200:203], 0
	v_mfma_f32_16x16x32_bf16 v[86:89], v[164:167], v[208:211], 0
	v_mfma_f32_16x16x32_bf16 v[82:85], v[184:187], v[208:211], 0
	v_mfma_f32_16x16x32_bf16 v[70:73], v[164:167], v[216:219], 0
	v_mfma_f32_16x16x32_bf16 v[66:69], v[184:187], v[216:219], 0
	v_mfma_f32_16x16x32_bf16 v[118:121], v[180:183], v[196:199], v[118:121]
	v_mfma_f32_16x16x32_bf16 v[114:117], v[188:191], v[196:199], v[114:117]
	v_mfma_f32_16x16x32_bf16 v[102:105], v[180:183], v[204:207], v[102:105]
	v_mfma_f32_16x16x32_bf16 v[98:101], v[188:191], v[204:207], v[98:101]
	v_mfma_f32_16x16x32_bf16 v[86:89], v[180:183], v[212:215], v[86:89]
	v_mfma_f32_16x16x32_bf16 v[82:85], v[188:191], v[212:215], v[82:85]
	s_setprio 2
	s_barrier
	v_mfma_f32_16x16x32_bf16 v[70:73], v[180:183], v[220:223], v[70:73]
	v_mfma_f32_16x16x32_bf16 v[66:69], v[188:191], v[220:223], v[66:69]
	s_setprio 0
	s_add_i32 s48, s48, s9
	v_lshl_add_u64 v[168:169], s[42:43], 0, v[140:141]
	s_mov_b32 m0, s48
	ds_read_b128 v[192:195], v157 offset:16384
	ds_read_b128 v[196:199], v157 offset:17408
	ds_read_b128 v[200:203], v157 offset:18432
	ds_read_b128 v[204:207], v157 offset:19456
	ds_read_b128 v[208:211], v157 offset:20480
	ds_read_b128 v[212:215], v157 offset:21504
	ds_read_b128 v[216:219], v157 offset:22528
	ds_read_b128 v[220:223], v157 offset:23552
	global_load_lds_dwordx4 v[168:169], off
	s_add_i32 m0, s48, 0x2000
	s_add_u32 s48, s42, 0x80000
	v_lshl_add_u64 v[224:225], s[42:43], 0, v[144:145]
	s_addc_u32 s49, s43, 0
	s_add_i32 s50, s50, s9
	global_load_lds_dwordx4 v[224:225], off
	v_lshl_add_u64 v[226:227], s[48:49], 0, v[140:141]
	s_mov_b32 m0, s50
	v_lshl_add_u64 v[228:229], s[44:45], 0, v[142:143]
	global_load_lds_dwordx4 v[226:227], off
	s_add_i32 m0, s50, 0x2000
	v_lshl_add_u64 v[226:227], s[48:49], 0, v[144:145]
	global_load_lds_dwordx4 v[226:227], off
	s_mov_b32 m0, s11
	v_lshl_add_u64 v[226:227], s[44:45], 0, v[138:139]
	global_load_lds_dwordx4 v[226:227], off
	s_mov_b32 m0, s13
	s_nop 0
	global_load_lds_dwordx4 v[228:229], off
	s_waitcnt vmcnt(8)
	s_waitcnt lgkmcnt(0)
	s_barrier
	s_setprio 1
	s_waitcnt lgkmcnt(0)
	v_mfma_f32_16x16x32_bf16 v[62:65], v[130:133], v[192:195], 0
	v_mfma_f32_16x16x32_bf16 v[58:61], v[152:155], v[192:195], 0
	v_mfma_f32_16x16x32_bf16 v[46:49], v[130:133], v[200:203], 0
	v_mfma_f32_16x16x32_bf16 v[42:45], v[152:155], v[200:203], 0
	v_mfma_f32_16x16x32_bf16 v[30:33], v[130:133], v[208:211], 0
	v_mfma_f32_16x16x32_bf16 v[26:29], v[152:155], v[208:211], 0
	v_mfma_f32_16x16x32_bf16 v[14:17], v[130:133], v[216:219], 0
	v_mfma_f32_16x16x32_bf16 v[10:13], v[152:155], v[216:219], 0
	v_mfma_f32_16x16x32_bf16 v[62:65], v[134:137], v[196:199], v[62:65]
	v_mfma_f32_16x16x32_bf16 v[58:61], v[158:161], v[196:199], v[58:61]
	v_mfma_f32_16x16x32_bf16 v[46:49], v[134:137], v[204:207], v[46:49]
	v_mfma_f32_16x16x32_bf16 v[42:45], v[158:161], v[204:207], v[42:45]
	v_mfma_f32_16x16x32_bf16 v[30:33], v[134:137], v[212:215], v[30:33]
	v_mfma_f32_16x16x32_bf16 v[26:29], v[158:161], v[212:215], v[26:29]
	v_mfma_f32_16x16x32_bf16 v[14:17], v[134:137], v[220:223], v[14:17]
	v_mfma_f32_16x16x32_bf16 v[10:13], v[158:161], v[220:223], v[10:13]
	s_setprio 0
	s_setprio 1
	v_mfma_f32_16x16x32_bf16 v[54:57], v[164:167], v[192:195], 0
	v_mfma_f32_16x16x32_bf16 v[50:53], v[184:187], v[192:195], 0
	v_mfma_f32_16x16x32_bf16 v[38:41], v[164:167], v[200:203], 0
	v_mfma_f32_16x16x32_bf16 v[34:37], v[184:187], v[200:203], 0
	v_mfma_f32_16x16x32_bf16 v[22:25], v[164:167], v[208:211], 0
	v_mfma_f32_16x16x32_bf16 v[18:21], v[184:187], v[208:211], 0
	v_mfma_f32_16x16x32_bf16 v[6:9], v[164:167], v[216:219], 0
	v_mfma_f32_16x16x32_bf16 v[2:5], v[184:187], v[216:219], 0
	v_mfma_f32_16x16x32_bf16 v[54:57], v[180:183], v[196:199], v[54:57]
	v_mfma_f32_16x16x32_bf16 v[50:53], v[188:191], v[196:199], v[50:53]
	v_mfma_f32_16x16x32_bf16 v[38:41], v[180:183], v[204:207], v[38:41]
	v_mfma_f32_16x16x32_bf16 v[34:37], v[188:191], v[204:207], v[34:37]
	v_mfma_f32_16x16x32_bf16 v[22:25], v[180:183], v[212:215], v[22:25]
	v_mfma_f32_16x16x32_bf16 v[18:21], v[188:191], v[212:215], v[18:21]
	s_setprio 2
	s_barrier
	v_mfma_f32_16x16x32_bf16 v[6:9], v[180:183], v[220:223], v[6:9]
	v_mfma_f32_16x16x32_bf16 v[2:5], v[188:191], v[220:223], v[2:5]
	s_setprio 0
	s_add_i32 s48, 0, 0x18000
	s_add_i32 s49, 0, 0x1c000
	v_add_u32_e32 v158, s48, v147
	v_add_u32_e32 v162, s49, v147
	ds_read_b128 v[130:133], v158
	ds_read_b128 v[134:137], v158 offset:1024
	ds_read_b128 v[152:155], v158 offset:2048
	ds_read_b128 v[158:161], v158 offset:3072
	ds_read_b128 v[164:167], v162
	ds_read_b128 v[180:183], v162 offset:1024
	ds_read_b128 v[184:187], v162 offset:2048
	ds_read_b128 v[188:191], v162 offset:3072
	s_add_u32 s44, s44, 0x80000
	s_addc_u32 s45, s45, 0
	s_mov_b32 m0, s20
	v_lshl_add_u64 v[230:231], s[44:45], 0, v[138:139]
	ds_read_b128 v[192:195], v157 offset:32768
	ds_read_b128 v[196:199], v157 offset:33792
	ds_read_b128 v[200:203], v157 offset:34816
	ds_read_b128 v[204:207], v157 offset:35840
	ds_read_b128 v[208:211], v157 offset:36864
	ds_read_b128 v[212:215], v157 offset:37888
	ds_read_b128 v[216:219], v157 offset:38912
	ds_read_b128 v[220:223], v157 offset:39936
	global_load_lds_dwordx4 v[230:231], off
	s_mov_b32 m0, s25
	v_lshl_add_u64 v[230:231], s[44:45], 0, v[142:143]
	global_load_lds_dwordx4 v[230:231], off
	s_waitcnt vmcnt(8)
	s_waitcnt lgkmcnt(0)
	s_barrier
	s_setprio 1
	s_waitcnt lgkmcnt(0)
	v_mfma_f32_16x16x32_bf16 v[126:129], v[130:133], v[192:195], v[126:129]
	v_mfma_f32_16x16x32_bf16 v[122:125], v[152:155], v[192:195], v[122:125]
	v_mfma_f32_16x16x32_bf16 v[110:113], v[130:133], v[200:203], v[110:113]
	v_mfma_f32_16x16x32_bf16 v[106:109], v[152:155], v[200:203], v[106:109]
	v_mfma_f32_16x16x32_bf16 v[94:97], v[130:133], v[208:211], v[94:97]
	v_mfma_f32_16x16x32_bf16 v[90:93], v[152:155], v[208:211], v[90:93]
	v_mfma_f32_16x16x32_bf16 v[78:81], v[130:133], v[216:219], v[78:81]
	v_mfma_f32_16x16x32_bf16 v[74:77], v[152:155], v[216:219], v[74:77]
	v_mfma_f32_16x16x32_bf16 v[126:129], v[134:137], v[196:199], v[126:129]
	v_mfma_f32_16x16x32_bf16 v[122:125], v[158:161], v[196:199], v[122:125]
	v_mfma_f32_16x16x32_bf16 v[110:113], v[134:137], v[204:207], v[110:113]
	v_mfma_f32_16x16x32_bf16 v[106:109], v[158:161], v[204:207], v[106:109]
	v_mfma_f32_16x16x32_bf16 v[94:97], v[134:137], v[212:215], v[94:97]
	v_mfma_f32_16x16x32_bf16 v[90:93], v[158:161], v[212:215], v[90:93]
	v_mfma_f32_16x16x32_bf16 v[78:81], v[134:137], v[220:223], v[78:81]
	v_mfma_f32_16x16x32_bf16 v[74:77], v[158:161], v[220:223], v[74:77]
	s_setprio 0
	s_setprio 1
	v_mfma_f32_16x16x32_bf16 v[118:121], v[164:167], v[192:195], v[118:121]
	v_mfma_f32_16x16x32_bf16 v[114:117], v[184:187], v[192:195], v[114:117]
	v_mfma_f32_16x16x32_bf16 v[102:105], v[164:167], v[200:203], v[102:105]
	v_mfma_f32_16x16x32_bf16 v[98:101], v[184:187], v[200:203], v[98:101]
	v_mfma_f32_16x16x32_bf16 v[86:89], v[164:167], v[208:211], v[86:89]
	v_mfma_f32_16x16x32_bf16 v[82:85], v[184:187], v[208:211], v[82:85]
	v_mfma_f32_16x16x32_bf16 v[70:73], v[164:167], v[216:219], v[70:73]
	v_mfma_f32_16x16x32_bf16 v[66:69], v[184:187], v[216:219], v[66:69]
	v_mfma_f32_16x16x32_bf16 v[118:121], v[180:183], v[196:199], v[118:121]
	v_mfma_f32_16x16x32_bf16 v[114:117], v[188:191], v[196:199], v[114:117]
	v_mfma_f32_16x16x32_bf16 v[102:105], v[180:183], v[204:207], v[102:105]
	v_mfma_f32_16x16x32_bf16 v[98:101], v[188:191], v[204:207], v[98:101]
	v_mfma_f32_16x16x32_bf16 v[86:89], v[180:183], v[212:215], v[86:89]
	v_mfma_f32_16x16x32_bf16 v[82:85], v[188:191], v[212:215], v[82:85]
	s_setprio 2
	s_barrier
	v_mfma_f32_16x16x32_bf16 v[70:73], v[180:183], v[220:223], v[70:73]
	v_mfma_f32_16x16x32_bf16 v[66:69], v[188:191], v[220:223], v[66:69]
	s_setprio 0
	s_add_i32 s44, s48, s9
	v_lshl_add_u64 v[168:169], v[168:169], 0, s[6:7]
	s_mov_b32 m0, s44
	ds_read_b128 v[192:195], v157 offset:49152
	ds_read_b128 v[196:199], v157 offset:50176
	ds_read_b128 v[200:203], v157 offset:51200
	ds_read_b128 v[204:207], v157 offset:52224
	ds_read_b128 v[208:211], v157 offset:53248
	ds_read_b128 v[212:215], v157 offset:54272
	ds_read_b128 v[216:219], v157 offset:55296
	ds_read_b128 v[220:223], v157 offset:56320
	global_load_lds_dwordx4 v[168:169], off
	s_add_i32 m0, s44, 0x2000
	s_add_u32 s42, s42, 0x80080
	v_lshl_add_u64 v[168:169], v[224:225], 0, s[6:7]
	s_addc_u32 s43, s43, 0
	s_add_i32 s44, s49, s9
	global_load_lds_dwordx4 v[168:169], off
	s_mov_b32 m0, s44
	v_lshl_add_u64 v[168:169], s[42:43], 0, v[140:141]
	global_load_lds_dwordx4 v[168:169], off
	s_add_i32 m0, s44, 0x2000
	v_lshl_add_u64 v[168:169], s[42:43], 0, v[144:145]
	global_load_lds_dwordx4 v[168:169], off
	s_mov_b32 m0, s26
	v_lshl_add_u64 v[168:169], v[226:227], 0, s[6:7]
	global_load_lds_dwordx4 v[168:169], off
	s_mov_b32 m0, s27
	v_lshl_add_u64 v[168:169], v[228:229], 0, s[6:7]
	global_load_lds_dwordx4 v[168:169], off
	s_waitcnt vmcnt(8)
	s_waitcnt lgkmcnt(0)
	s_barrier
	s_setprio 1
	s_waitcnt lgkmcnt(0)
	v_mfma_f32_16x16x32_bf16 v[62:65], v[130:133], v[192:195], v[62:65]
	v_mfma_f32_16x16x32_bf16 v[58:61], v[152:155], v[192:195], v[58:61]
	v_mfma_f32_16x16x32_bf16 v[46:49], v[130:133], v[200:203], v[46:49]
	v_mfma_f32_16x16x32_bf16 v[42:45], v[152:155], v[200:203], v[42:45]
	v_mfma_f32_16x16x32_bf16 v[30:33], v[130:133], v[208:211], v[30:33]
	v_mfma_f32_16x16x32_bf16 v[26:29], v[152:155], v[208:211], v[26:29]
	v_mfma_f32_16x16x32_bf16 v[14:17], v[130:133], v[216:219], v[14:17]
	v_mfma_f32_16x16x32_bf16 v[10:13], v[152:155], v[216:219], v[10:13]
	v_mfma_f32_16x16x32_bf16 v[62:65], v[134:137], v[196:199], v[62:65]
	v_mfma_f32_16x16x32_bf16 v[58:61], v[158:161], v[196:199], v[58:61]
	v_mfma_f32_16x16x32_bf16 v[46:49], v[134:137], v[204:207], v[46:49]
	v_mfma_f32_16x16x32_bf16 v[42:45], v[158:161], v[204:207], v[42:45]
	v_mfma_f32_16x16x32_bf16 v[30:33], v[134:137], v[212:215], v[30:33]
	v_mfma_f32_16x16x32_bf16 v[26:29], v[158:161], v[212:215], v[26:29]
	v_mfma_f32_16x16x32_bf16 v[14:17], v[134:137], v[220:223], v[14:17]
	v_mfma_f32_16x16x32_bf16 v[10:13], v[158:161], v[220:223], v[10:13]
	s_setprio 0
	s_setprio 1
	v_mfma_f32_16x16x32_bf16 v[54:57], v[164:167], v[192:195], v[54:57]
	v_mfma_f32_16x16x32_bf16 v[50:53], v[184:187], v[192:195], v[50:53]
	v_mfma_f32_16x16x32_bf16 v[38:41], v[164:167], v[200:203], v[38:41]
	v_mfma_f32_16x16x32_bf16 v[34:37], v[184:187], v[200:203], v[34:37]
	v_mfma_f32_16x16x32_bf16 v[22:25], v[164:167], v[208:211], v[22:25]
	v_mfma_f32_16x16x32_bf16 v[18:21], v[184:187], v[208:211], v[18:21]
	v_mfma_f32_16x16x32_bf16 v[6:9], v[164:167], v[216:219], v[6:9]
	v_mfma_f32_16x16x32_bf16 v[2:5], v[184:187], v[216:219], v[2:5]
	v_mfma_f32_16x16x32_bf16 v[54:57], v[180:183], v[196:199], v[54:57]
	v_mfma_f32_16x16x32_bf16 v[50:53], v[188:191], v[196:199], v[50:53]
	v_mfma_f32_16x16x32_bf16 v[38:41], v[180:183], v[204:207], v[38:41]
	v_mfma_f32_16x16x32_bf16 v[34:37], v[188:191], v[204:207], v[34:37]
	v_mfma_f32_16x16x32_bf16 v[22:25], v[180:183], v[212:215], v[22:25]
	v_mfma_f32_16x16x32_bf16 v[18:21], v[188:191], v[212:215], v[18:21]
	s_setprio 2
	s_barrier
	v_mfma_f32_16x16x32_bf16 v[6:9], v[180:183], v[220:223], v[6:9]
	v_mfma_f32_16x16x32_bf16 v[2:5], v[188:191], v[220:223], v[2:5]
	s_setprio 0
	s_add_i32 s47, s47, 2
	s_add_u32 s36, s36, 0x100
	s_addc_u32 s37, s37, 0
	s_add_u32 s41, s41, 0x100
	s_addc_u32 s46, s46, 0
	s_cmp_gt_u32 s47, 29
.LBB0_292:
	s_add_u32 s42, s36, 0xfff80080
	s_addc_u32 s43, s37, -1
	s_add_i32 s48, 0, 0x10000
	s_cmp_eq_u32 s47, 28
	s_cselect_b32 s45, s5, s43
	s_cselect_b32 s44, s8, s42
	s_cselect_b32 s43, s19, s46
	s_cselect_b32 s42, s21, s41
	s_add_i32 s50, 0, 0x14000
	v_add_u32_e32 v158, s48, v147
	v_add_u32_e32 v162, s50, v147
	ds_read_b128 v[130:133], v158
	ds_read_b128 v[134:137], v158 offset:1024
	ds_read_b128 v[152:155], v158 offset:2048
	ds_read_b128 v[158:161], v158 offset:3072
	ds_read_b128 v[164:167], v162
	ds_read_b128 v[180:183], v162 offset:1024
	ds_read_b128 v[184:187], v162 offset:2048
	ds_read_b128 v[188:191], v162 offset:3072
	v_lshl_add_u64 v[168:169], s[36:37], 0, v[148:149]
	s_add_i32 m0, s11, 0xc000
	ds_read_b128 v[192:195], v157
	ds_read_b128 v[196:199], v157 offset:1024
	ds_read_b128 v[200:203], v157 offset:2048
	ds_read_b128 v[204:207], v157 offset:3072
	ds_read_b128 v[208:211], v157 offset:4096
	ds_read_b128 v[212:215], v157 offset:5120
	ds_read_b128 v[216:219], v157 offset:6144
	ds_read_b128 v[220:223], v157 offset:7168
	global_load_lds_dwordx4 v[168:169], off
	s_add_i32 m0, s11, 0xe000
	v_lshl_add_u64 v[168:169], s[36:37], 0, v[150:151]
	global_load_lds_dwordx4 v[168:169], off
	s_waitcnt vmcnt(8)
	s_waitcnt lgkmcnt(0)
	s_barrier
	s_setprio 1
	s_waitcnt lgkmcnt(0)
	v_mfma_f32_16x16x32_bf16 v[126:129], v[130:133], v[192:195], v[126:129]
	v_mfma_f32_16x16x32_bf16 v[122:125], v[152:155], v[192:195], v[122:125]
	v_mfma_f32_16x16x32_bf16 v[110:113], v[130:133], v[200:203], v[110:113]
	v_mfma_f32_16x16x32_bf16 v[106:109], v[152:155], v[200:203], v[106:109]
	v_mfma_f32_16x16x32_bf16 v[94:97], v[130:133], v[208:211], v[94:97]
	v_mfma_f32_16x16x32_bf16 v[90:93], v[152:155], v[208:211], v[90:93]
	v_mfma_f32_16x16x32_bf16 v[78:81], v[130:133], v[216:219], v[78:81]
	v_mfma_f32_16x16x32_bf16 v[74:77], v[152:155], v[216:219], v[74:77]
	v_mfma_f32_16x16x32_bf16 v[126:129], v[134:137], v[196:199], v[126:129]
	v_mfma_f32_16x16x32_bf16 v[122:125], v[158:161], v[196:199], v[122:125]
	v_mfma_f32_16x16x32_bf16 v[110:113], v[134:137], v[204:207], v[110:113]
	v_mfma_f32_16x16x32_bf16 v[106:109], v[158:161], v[204:207], v[106:109]
	v_mfma_f32_16x16x32_bf16 v[94:97], v[134:137], v[212:215], v[94:97]
	v_mfma_f32_16x16x32_bf16 v[90:93], v[158:161], v[212:215], v[90:93]
	v_mfma_f32_16x16x32_bf16 v[78:81], v[134:137], v[220:223], v[78:81]
	v_mfma_f32_16x16x32_bf16 v[74:77], v[158:161], v[220:223], v[74:77]
	s_setprio 0
	s_setprio 1
	v_mfma_f32_16x16x32_bf16 v[118:121], v[164:167], v[192:195], v[118:121]
	v_mfma_f32_16x16x32_bf16 v[114:117], v[184:187], v[192:195], v[114:117]
	v_mfma_f32_16x16x32_bf16 v[102:105], v[164:167], v[200:203], v[102:105]
	v_mfma_f32_16x16x32_bf16 v[98:101], v[184:187], v[200:203], v[98:101]
	v_mfma_f32_16x16x32_bf16 v[86:89], v[164:167], v[208:211], v[86:89]
	v_mfma_f32_16x16x32_bf16 v[82:85], v[184:187], v[208:211], v[82:85]
	v_mfma_f32_16x16x32_bf16 v[70:73], v[164:167], v[216:219], v[70:73]
	v_mfma_f32_16x16x32_bf16 v[66:69], v[184:187], v[216:219], v[66:69]
	v_mfma_f32_16x16x32_bf16 v[118:121], v[180:183], v[196:199], v[118:121]
	v_mfma_f32_16x16x32_bf16 v[114:117], v[188:191], v[196:199], v[114:117]
	v_mfma_f32_16x16x32_bf16 v[102:105], v[180:183], v[204:207], v[102:105]
	v_mfma_f32_16x16x32_bf16 v[98:101], v[188:191], v[204:207], v[98:101]
	v_mfma_f32_16x16x32_bf16 v[86:89], v[180:183], v[212:215], v[86:89]
	v_mfma_f32_16x16x32_bf16 v[82:85], v[188:191], v[212:215], v[82:85]
	s_setprio 2
	s_barrier
	v_mfma_f32_16x16x32_bf16 v[70:73], v[180:183], v[220:223], v[70:73]
	v_mfma_f32_16x16x32_bf16 v[66:69], v[188:191], v[220:223], v[66:69]
	s_setprio 0
	s_add_i32 s48, s48, s9
	v_lshl_add_u64 v[168:169], s[42:43], 0, v[140:141]
	s_mov_b32 m0, s48
	ds_read_b128 v[192:195], v157 offset:16384
	ds_read_b128 v[196:199], v157 offset:17408
	ds_read_b128 v[200:203], v157 offset:18432
	ds_read_b128 v[204:207], v157 offset:19456
	ds_read_b128 v[208:211], v157 offset:20480
	ds_read_b128 v[212:215], v157 offset:21504
	ds_read_b128 v[216:219], v157 offset:22528
	ds_read_b128 v[220:223], v157 offset:23552
	global_load_lds_dwordx4 v[168:169], off
	s_add_i32 m0, s48, 0x2000
	s_add_u32 s48, s42, 0x80000
	v_lshl_add_u64 v[224:225], s[42:43], 0, v[144:145]
	s_addc_u32 s49, s43, 0
	s_add_i32 s50, s50, s9
	global_load_lds_dwordx4 v[224:225], off
	v_lshl_add_u64 v[226:227], s[48:49], 0, v[140:141]
	s_mov_b32 m0, s50
	v_lshl_add_u64 v[228:229], s[44:45], 0, v[142:143]
	global_load_lds_dwordx4 v[226:227], off
	s_add_i32 m0, s50, 0x2000
	v_lshl_add_u64 v[226:227], s[48:49], 0, v[144:145]
	global_load_lds_dwordx4 v[226:227], off
	s_mov_b32 m0, s11
	v_lshl_add_u64 v[226:227], s[44:45], 0, v[138:139]
	global_load_lds_dwordx4 v[226:227], off
	s_mov_b32 m0, s13
	s_nop 0
	global_load_lds_dwordx4 v[228:229], off
	s_waitcnt vmcnt(8)
	s_waitcnt lgkmcnt(0)
	s_barrier
	s_setprio 1
	s_waitcnt lgkmcnt(0)
	v_mfma_f32_16x16x32_bf16 v[62:65], v[130:133], v[192:195], v[62:65]
	v_mfma_f32_16x16x32_bf16 v[58:61], v[152:155], v[192:195], v[58:61]
	v_mfma_f32_16x16x32_bf16 v[46:49], v[130:133], v[200:203], v[46:49]
	v_mfma_f32_16x16x32_bf16 v[42:45], v[152:155], v[200:203], v[42:45]
	v_mfma_f32_16x16x32_bf16 v[30:33], v[130:133], v[208:211], v[30:33]
	v_mfma_f32_16x16x32_bf16 v[26:29], v[152:155], v[208:211], v[26:29]
	v_mfma_f32_16x16x32_bf16 v[14:17], v[130:133], v[216:219], v[14:17]
	v_mfma_f32_16x16x32_bf16 v[10:13], v[152:155], v[216:219], v[10:13]
	v_mfma_f32_16x16x32_bf16 v[62:65], v[134:137], v[196:199], v[62:65]
	v_mfma_f32_16x16x32_bf16 v[58:61], v[158:161], v[196:199], v[58:61]
	v_mfma_f32_16x16x32_bf16 v[46:49], v[134:137], v[204:207], v[46:49]
	v_mfma_f32_16x16x32_bf16 v[42:45], v[158:161], v[204:207], v[42:45]
	v_mfma_f32_16x16x32_bf16 v[30:33], v[134:137], v[212:215], v[30:33]
	v_mfma_f32_16x16x32_bf16 v[26:29], v[158:161], v[212:215], v[26:29]
	v_mfma_f32_16x16x32_bf16 v[14:17], v[134:137], v[220:223], v[14:17]
	v_mfma_f32_16x16x32_bf16 v[10:13], v[158:161], v[220:223], v[10:13]
	s_setprio 0
	s_setprio 1
	v_mfma_f32_16x16x32_bf16 v[54:57], v[164:167], v[192:195], v[54:57]
	v_mfma_f32_16x16x32_bf16 v[50:53], v[184:187], v[192:195], v[50:53]
	v_mfma_f32_16x16x32_bf16 v[38:41], v[164:167], v[200:203], v[38:41]
	v_mfma_f32_16x16x32_bf16 v[34:37], v[184:187], v[200:203], v[34:37]
	v_mfma_f32_16x16x32_bf16 v[22:25], v[164:167], v[208:211], v[22:25]
	v_mfma_f32_16x16x32_bf16 v[18:21], v[184:187], v[208:211], v[18:21]
	v_mfma_f32_16x16x32_bf16 v[6:9], v[164:167], v[216:219], v[6:9]
	v_mfma_f32_16x16x32_bf16 v[2:5], v[184:187], v[216:219], v[2:5]
	v_mfma_f32_16x16x32_bf16 v[54:57], v[180:183], v[196:199], v[54:57]
	v_mfma_f32_16x16x32_bf16 v[50:53], v[188:191], v[196:199], v[50:53]
	v_mfma_f32_16x16x32_bf16 v[38:41], v[180:183], v[204:207], v[38:41]
	v_mfma_f32_16x16x32_bf16 v[34:37], v[188:191], v[204:207], v[34:37]
	v_mfma_f32_16x16x32_bf16 v[22:25], v[180:183], v[212:215], v[22:25]
	v_mfma_f32_16x16x32_bf16 v[18:21], v[188:191], v[212:215], v[18:21]
	s_setprio 2
	s_barrier
	v_mfma_f32_16x16x32_bf16 v[6:9], v[180:183], v[220:223], v[6:9]
	v_mfma_f32_16x16x32_bf16 v[2:5], v[188:191], v[220:223], v[2:5]
	s_setprio 0
	s_add_i32 s48, 0, 0x18000
	s_add_i32 s49, 0, 0x1c000
	v_add_u32_e32 v158, s48, v147
	v_add_u32_e32 v162, s49, v147
	ds_read_b128 v[130:133], v158
	ds_read_b128 v[134:137], v158 offset:1024
	ds_read_b128 v[152:155], v158 offset:2048
	ds_read_b128 v[158:161], v158 offset:3072
	ds_read_b128 v[164:167], v162
	ds_read_b128 v[180:183], v162 offset:1024
	ds_read_b128 v[184:187], v162 offset:2048
	ds_read_b128 v[188:191], v162 offset:3072
	s_add_u32 s44, s44, 0x80000
	s_addc_u32 s45, s45, 0
	s_mov_b32 m0, s20
	v_lshl_add_u64 v[230:231], s[44:45], 0, v[138:139]
	ds_read_b128 v[192:195], v157 offset:32768
	ds_read_b128 v[196:199], v157 offset:33792
	ds_read_b128 v[200:203], v157 offset:34816
	ds_read_b128 v[204:207], v157 offset:35840
	ds_read_b128 v[208:211], v157 offset:36864
	ds_read_b128 v[212:215], v157 offset:37888
	ds_read_b128 v[216:219], v157 offset:38912
	ds_read_b128 v[220:223], v157 offset:39936
	global_load_lds_dwordx4 v[230:231], off
	s_mov_b32 m0, s25
	v_lshl_add_u64 v[230:231], s[44:45], 0, v[142:143]
	global_load_lds_dwordx4 v[230:231], off
	s_waitcnt vmcnt(8)
	s_waitcnt lgkmcnt(0)
	s_barrier
	s_setprio 1
	s_waitcnt lgkmcnt(0)
	v_mfma_f32_16x16x32_bf16 v[126:129], v[130:133], v[192:195], v[126:129]
	v_mfma_f32_16x16x32_bf16 v[122:125], v[152:155], v[192:195], v[122:125]
	v_mfma_f32_16x16x32_bf16 v[110:113], v[130:133], v[200:203], v[110:113]
	v_mfma_f32_16x16x32_bf16 v[106:109], v[152:155], v[200:203], v[106:109]
	v_mfma_f32_16x16x32_bf16 v[94:97], v[130:133], v[208:211], v[94:97]
	v_mfma_f32_16x16x32_bf16 v[90:93], v[152:155], v[208:211], v[90:93]
	v_mfma_f32_16x16x32_bf16 v[78:81], v[130:133], v[216:219], v[78:81]
	v_mfma_f32_16x16x32_bf16 v[74:77], v[152:155], v[216:219], v[74:77]
	v_mfma_f32_16x16x32_bf16 v[126:129], v[134:137], v[196:199], v[126:129]
	v_mfma_f32_16x16x32_bf16 v[122:125], v[158:161], v[196:199], v[122:125]
	v_mfma_f32_16x16x32_bf16 v[110:113], v[134:137], v[204:207], v[110:113]
	v_mfma_f32_16x16x32_bf16 v[106:109], v[158:161], v[204:207], v[106:109]
	v_mfma_f32_16x16x32_bf16 v[94:97], v[134:137], v[212:215], v[94:97]
	v_mfma_f32_16x16x32_bf16 v[90:93], v[158:161], v[212:215], v[90:93]
	v_mfma_f32_16x16x32_bf16 v[78:81], v[134:137], v[220:223], v[78:81]
	v_mfma_f32_16x16x32_bf16 v[74:77], v[158:161], v[220:223], v[74:77]
	s_setprio 0
	s_setprio 1
	v_mfma_f32_16x16x32_bf16 v[118:121], v[164:167], v[192:195], v[118:121]
	v_mfma_f32_16x16x32_bf16 v[114:117], v[184:187], v[192:195], v[114:117]
	v_mfma_f32_16x16x32_bf16 v[102:105], v[164:167], v[200:203], v[102:105]
	v_mfma_f32_16x16x32_bf16 v[98:101], v[184:187], v[200:203], v[98:101]
	v_mfma_f32_16x16x32_bf16 v[86:89], v[164:167], v[208:211], v[86:89]
	v_mfma_f32_16x16x32_bf16 v[82:85], v[184:187], v[208:211], v[82:85]
	v_mfma_f32_16x16x32_bf16 v[70:73], v[164:167], v[216:219], v[70:73]
	v_mfma_f32_16x16x32_bf16 v[66:69], v[184:187], v[216:219], v[66:69]
	v_mfma_f32_16x16x32_bf16 v[118:121], v[180:183], v[196:199], v[118:121]
	v_mfma_f32_16x16x32_bf16 v[114:117], v[188:191], v[196:199], v[114:117]
	v_mfma_f32_16x16x32_bf16 v[102:105], v[180:183], v[204:207], v[102:105]
	v_mfma_f32_16x16x32_bf16 v[98:101], v[188:191], v[204:207], v[98:101]
	v_mfma_f32_16x16x32_bf16 v[86:89], v[180:183], v[212:215], v[86:89]
	v_mfma_f32_16x16x32_bf16 v[82:85], v[188:191], v[212:215], v[82:85]
	s_setprio 2
	s_barrier
	v_mfma_f32_16x16x32_bf16 v[70:73], v[180:183], v[220:223], v[70:73]
	v_mfma_f32_16x16x32_bf16 v[66:69], v[188:191], v[220:223], v[66:69]
	s_setprio 0
	s_add_i32 s44, s48, s9
	v_lshl_add_u64 v[168:169], v[168:169], 0, s[6:7]
	s_mov_b32 m0, s44
	ds_read_b128 v[192:195], v157 offset:49152
	ds_read_b128 v[196:199], v157 offset:50176
	ds_read_b128 v[200:203], v157 offset:51200
	ds_read_b128 v[204:207], v157 offset:52224
	ds_read_b128 v[208:211], v157 offset:53248
	ds_read_b128 v[212:215], v157 offset:54272
	ds_read_b128 v[216:219], v157 offset:55296
	ds_read_b128 v[220:223], v157 offset:56320
	global_load_lds_dwordx4 v[168:169], off
	s_add_i32 m0, s44, 0x2000
	s_add_u32 s42, s42, 0x80080
	v_lshl_add_u64 v[168:169], v[224:225], 0, s[6:7]
	s_addc_u32 s43, s43, 0
	s_add_i32 s44, s49, s9
	global_load_lds_dwordx4 v[168:169], off
	s_mov_b32 m0, s44
	v_lshl_add_u64 v[168:169], s[42:43], 0, v[140:141]
	global_load_lds_dwordx4 v[168:169], off
	s_add_i32 m0, s44, 0x2000
	v_lshl_add_u64 v[168:169], s[42:43], 0, v[144:145]
	global_load_lds_dwordx4 v[168:169], off
	s_mov_b32 m0, s26
	v_lshl_add_u64 v[168:169], v[226:227], 0, s[6:7]
	global_load_lds_dwordx4 v[168:169], off
	s_mov_b32 m0, s27
	v_lshl_add_u64 v[168:169], v[228:229], 0, s[6:7]
	global_load_lds_dwordx4 v[168:169], off
	s_waitcnt vmcnt(8)
	s_waitcnt lgkmcnt(0)
	s_barrier
	s_setprio 1
	s_waitcnt lgkmcnt(0)
	v_mfma_f32_16x16x32_bf16 v[62:65], v[130:133], v[192:195], v[62:65]
	v_mfma_f32_16x16x32_bf16 v[58:61], v[152:155], v[192:195], v[58:61]
	v_mfma_f32_16x16x32_bf16 v[46:49], v[130:133], v[200:203], v[46:49]
	v_mfma_f32_16x16x32_bf16 v[42:45], v[152:155], v[200:203], v[42:45]
	v_mfma_f32_16x16x32_bf16 v[30:33], v[130:133], v[208:211], v[30:33]
	v_mfma_f32_16x16x32_bf16 v[26:29], v[152:155], v[208:211], v[26:29]
	v_mfma_f32_16x16x32_bf16 v[14:17], v[130:133], v[216:219], v[14:17]
	v_mfma_f32_16x16x32_bf16 v[10:13], v[152:155], v[216:219], v[10:13]
	v_mfma_f32_16x16x32_bf16 v[62:65], v[134:137], v[196:199], v[62:65]
	v_mfma_f32_16x16x32_bf16 v[58:61], v[158:161], v[196:199], v[58:61]
	v_mfma_f32_16x16x32_bf16 v[46:49], v[134:137], v[204:207], v[46:49]
	v_mfma_f32_16x16x32_bf16 v[42:45], v[158:161], v[204:207], v[42:45]
	v_mfma_f32_16x16x32_bf16 v[30:33], v[134:137], v[212:215], v[30:33]
	v_mfma_f32_16x16x32_bf16 v[26:29], v[158:161], v[212:215], v[26:29]
	v_mfma_f32_16x16x32_bf16 v[14:17], v[134:137], v[220:223], v[14:17]
	v_mfma_f32_16x16x32_bf16 v[10:13], v[158:161], v[220:223], v[10:13]
	s_setprio 0
	s_setprio 1
	v_mfma_f32_16x16x32_bf16 v[54:57], v[164:167], v[192:195], v[54:57]
	v_mfma_f32_16x16x32_bf16 v[50:53], v[184:187], v[192:195], v[50:53]
	v_mfma_f32_16x16x32_bf16 v[38:41], v[164:167], v[200:203], v[38:41]
	v_mfma_f32_16x16x32_bf16 v[34:37], v[184:187], v[200:203], v[34:37]
	v_mfma_f32_16x16x32_bf16 v[22:25], v[164:167], v[208:211], v[22:25]
	v_mfma_f32_16x16x32_bf16 v[18:21], v[184:187], v[208:211], v[18:21]
	v_mfma_f32_16x16x32_bf16 v[6:9], v[164:167], v[216:219], v[6:9]
	v_mfma_f32_16x16x32_bf16 v[2:5], v[184:187], v[216:219], v[2:5]
	v_mfma_f32_16x16x32_bf16 v[54:57], v[180:183], v[196:199], v[54:57]
	v_mfma_f32_16x16x32_bf16 v[50:53], v[188:191], v[196:199], v[50:53]
	v_mfma_f32_16x16x32_bf16 v[38:41], v[180:183], v[204:207], v[38:41]
	v_mfma_f32_16x16x32_bf16 v[34:37], v[188:191], v[204:207], v[34:37]
	v_mfma_f32_16x16x32_bf16 v[22:25], v[180:183], v[212:215], v[22:25]
	v_mfma_f32_16x16x32_bf16 v[18:21], v[188:191], v[212:215], v[18:21]
	s_setprio 2
	s_barrier
	v_mfma_f32_16x16x32_bf16 v[6:9], v[180:183], v[220:223], v[6:9]
	v_mfma_f32_16x16x32_bf16 v[2:5], v[188:191], v[220:223], v[2:5]
	s_setprio 0
	s_add_i32 s47, s47, 2
	s_add_u32 s36, s36, 0x100
	s_addc_u32 s37, s37, 0
	s_add_u32 s41, s41, 0x100
	s_addc_u32 s46, s46, 0
	s_cmp_gt_u32 s47, 29
	s_cbranch_scc0 .LBB0_292
	s_and_b64 vcc, exec, s[2:3]
	s_cbranch_vccz .LBB0_295
	s_barrier

.LBB0_357:
	s_ashr_i32 s19, s18, 31
	s_lshl_b64 s[8:9], s[18:19], 20
	v_readlane_b32 s5, v243, 17
	s_add_u32 s28, s5, s8
	v_readlane_b32 s5, v243, 18
	s_addc_u32 s29, s5, s9
	s_and_b64 s[8:9], s[34:35], exec
	s_cselect_b32 s8, s29, s37
	s_cselect_b32 s9, s28, s36
	s_ashr_i32 s5, s4, 31
	s_lshl_b64 s[20:21], s[4:5], 20
	s_add_u32 s38, s30, s20
	v_readlane_b32 s5, v242, 4
	s_addc_u32 s39, s5, s21
	s_and_b64 s[20:21], s[34:35], exec
	s_cselect_b32 s5, s39, s43
	s_cselect_b32 s11, s38, s42
	s_add_u32 s36, s36, 0x80080
	s_addc_u32 s37, s37, 0
	s_add_u32 s13, s42, 0x100
	s_addc_u32 s19, s43, 0
	s_mov_b32 s20, -2
	s_waitcnt vmcnt(0)
	s_add_u32 s21, s36, 0xfff80080
	s_addc_u32 s23, s37, -1
	s_add_i32 s26, 0, 0x10000
	s_cmp_eq_u32 s20, 28
	s_cselect_b32 s45, s8, s23
	s_cselect_b32 s44, s9, s21
	v_add_u32_e32 v153, s26, v179
	s_cselect_b32 s43, s5, s19
	s_cselect_b32 s42, s11, s13
	s_add_i32 s21, 0, 0x14000
	ds_read_b128 v[130:133], v153
	ds_read_b128 v[134:137], v153 offset:1024
	ds_read_b128 v[164:167], v153 offset:2048
	ds_read_b128 v[182:185], v153 offset:3072
	v_add_u32_e32 v153, s21, v179
	ds_read_b128 v[186:189], v153
	ds_read_b128 v[190:193], v153 offset:1024
	ds_read_b128 v[194:197], v153 offset:2048
	ds_read_b128 v[198:201], v153 offset:3072
	v_lshl_add_u64 v[168:169], s[36:37], 0, v[148:149]
	s_add_i32 m0, s27, 0xc000
	ds_read_b128 v[202:205], v181
	ds_read_b128 v[206:209], v181 offset:1024
	ds_read_b128 v[210:213], v181 offset:2048
	ds_read_b128 v[214:217], v181 offset:3072
	ds_read_b128 v[218:221], v181 offset:4096
	ds_read_b128 v[222:225], v181 offset:5120
	ds_read_b128 v[226:229], v181 offset:6144
	ds_read_b128 v[230:233], v181 offset:7168
	global_load_lds_dwordx4 v[168:169], off
	s_add_i32 m0, s27, 0xe000
	v_lshl_add_u64 v[168:169], s[36:37], 0, v[150:151]
	global_load_lds_dwordx4 v[168:169], off
	s_waitcnt vmcnt(8)
	s_waitcnt lgkmcnt(0)
	s_barrier
	s_setprio 1
	s_waitcnt lgkmcnt(0)
	v_mfma_f32_16x16x32_bf16 v[126:129], v[130:133], v[202:205], 0
	v_mfma_f32_16x16x32_bf16 v[122:125], v[164:167], v[202:205], 0
	v_mfma_f32_16x16x32_bf16 v[110:113], v[130:133], v[210:213], 0
	v_mfma_f32_16x16x32_bf16 v[106:109], v[164:167], v[210:213], 0
	v_mfma_f32_16x16x32_bf16 v[94:97], v[130:133], v[218:221], 0
	v_mfma_f32_16x16x32_bf16 v[90:93], v[164:167], v[218:221], 0
	v_mfma_f32_16x16x32_bf16 v[78:81], v[130:133], v[226:229], 0
	v_mfma_f32_16x16x32_bf16 v[74:77], v[164:167], v[226:229], 0
	v_mfma_f32_16x16x32_bf16 v[126:129], v[134:137], v[206:209], v[126:129]
	v_mfma_f32_16x16x32_bf16 v[122:125], v[182:185], v[206:209], v[122:125]
	v_mfma_f32_16x16x32_bf16 v[110:113], v[134:137], v[214:217], v[110:113]
	v_mfma_f32_16x16x32_bf16 v[106:109], v[182:185], v[214:217], v[106:109]
	v_mfma_f32_16x16x32_bf16 v[94:97], v[134:137], v[222:225], v[94:97]
	v_mfma_f32_16x16x32_bf16 v[90:93], v[182:185], v[222:225], v[90:93]
	v_mfma_f32_16x16x32_bf16 v[78:81], v[134:137], v[230:233], v[78:81]
	v_mfma_f32_16x16x32_bf16 v[74:77], v[182:185], v[230:233], v[74:77]
	s_setprio 0
	s_setprio 1
	v_mfma_f32_16x16x32_bf16 v[118:121], v[186:189], v[202:205], 0
	v_mfma_f32_16x16x32_bf16 v[114:117], v[194:197], v[202:205], 0
	v_mfma_f32_16x16x32_bf16 v[102:105], v[186:189], v[210:213], 0
	v_mfma_f32_16x16x32_bf16 v[98:101], v[194:197], v[210:213], 0
	v_mfma_f32_16x16x32_bf16 v[86:89], v[186:189], v[218:221], 0
	v_mfma_f32_16x16x32_bf16 v[82:85], v[194:197], v[218:221], 0
	v_mfma_f32_16x16x32_bf16 v[70:73], v[186:189], v[226:229], 0
	v_mfma_f32_16x16x32_bf16 v[66:69], v[194:197], v[226:229], 0
	v_mfma_f32_16x16x32_bf16 v[118:121], v[190:193], v[206:209], v[118:121]
	v_mfma_f32_16x16x32_bf16 v[114:117], v[198:201], v[206:209], v[114:117]
	v_mfma_f32_16x16x32_bf16 v[102:105], v[190:193], v[214:217], v[102:105]
	v_mfma_f32_16x16x32_bf16 v[98:101], v[198:201], v[214:217], v[98:101]
	v_mfma_f32_16x16x32_bf16 v[86:89], v[190:193], v[222:225], v[86:89]
	v_mfma_f32_16x16x32_bf16 v[82:85], v[198:201], v[222:225], v[82:85]
	s_setprio 2
	s_barrier
	v_mfma_f32_16x16x32_bf16 v[70:73], v[190:193], v[230:233], v[70:73]
	v_mfma_f32_16x16x32_bf16 v[66:69], v[198:201], v[230:233], v[66:69]
	s_setprio 0
	s_add_i32 s23, s26, s25
	v_lshl_add_u64 v[168:169], s[42:43], 0, v[162:163]
	s_mov_b32 m0, s23
	ds_read_b128 v[202:205], v181 offset:16384
	ds_read_b128 v[206:209], v181 offset:17408
	ds_read_b128 v[210:213], v181 offset:18432
	ds_read_b128 v[214:217], v181 offset:19456
	ds_read_b128 v[218:221], v181 offset:20480
	ds_read_b128 v[222:225], v181 offset:21504
	ds_read_b128 v[226:229], v181 offset:22528
	ds_read_b128 v[230:233], v181 offset:23552
	global_load_lds_dwordx4 v[168:169], off
	s_add_i32 m0, s23, 0x2000
	s_add_u32 s52, s42, 0x80000
	v_lshl_add_u64 v[234:235], s[42:43], 0, v[142:143]
	s_addc_u32 s53, s43, 0
	s_add_i32 s21, s21, s25
	global_load_lds_dwordx4 v[234:235], off
	v_lshl_add_u64 v[236:237], s[52:53], 0, v[162:163]
	s_mov_b32 m0, s21
	v_lshl_add_u64 v[238:239], s[44:45], 0, v[140:141]
	global_load_lds_dwordx4 v[236:237], off
	s_add_i32 m0, s21, 0x2000
	v_lshl_add_u64 v[236:237], s[52:53], 0, v[142:143]
	global_load_lds_dwordx4 v[236:237], off
	s_mov_b32 m0, s27
	v_lshl_add_u64 v[236:237], s[44:45], 0, v[138:139]
	global_load_lds_dwordx4 v[236:237], off
	s_mov_b32 m0, s46
	s_nop 0
	global_load_lds_dwordx4 v[238:239], off
	s_waitcnt vmcnt(8)
	s_waitcnt lgkmcnt(0)
	s_barrier
	s_setprio 1
	s_waitcnt lgkmcnt(0)
	v_mfma_f32_16x16x32_bf16 v[62:65], v[130:133], v[202:205], 0
	v_mfma_f32_16x16x32_bf16 v[58:61], v[164:167], v[202:205], 0
	v_mfma_f32_16x16x32_bf16 v[46:49], v[130:133], v[210:213], 0
	v_mfma_f32_16x16x32_bf16 v[42:45], v[164:167], v[210:213], 0
	v_mfma_f32_16x16x32_bf16 v[30:33], v[130:133], v[218:221], 0
	v_mfma_f32_16x16x32_bf16 v[26:29], v[164:167], v[218:221], 0
	v_mfma_f32_16x16x32_bf16 v[14:17], v[130:133], v[226:229], 0
	v_mfma_f32_16x16x32_bf16 v[10:13], v[164:167], v[226:229], 0
	v_mfma_f32_16x16x32_bf16 v[62:65], v[134:137], v[206:209], v[62:65]
	v_mfma_f32_16x16x32_bf16 v[58:61], v[182:185], v[206:209], v[58:61]
	v_mfma_f32_16x16x32_bf16 v[46:49], v[134:137], v[214:217], v[46:49]
	v_mfma_f32_16x16x32_bf16 v[42:45], v[182:185], v[214:217], v[42:45]
	v_mfma_f32_16x16x32_bf16 v[30:33], v[134:137], v[222:225], v[30:33]
	v_mfma_f32_16x16x32_bf16 v[26:29], v[182:185], v[222:225], v[26:29]
	v_mfma_f32_16x16x32_bf16 v[14:17], v[134:137], v[230:233], v[14:17]
	v_mfma_f32_16x16x32_bf16 v[10:13], v[182:185], v[230:233], v[10:13]
	s_setprio 0
	s_setprio 1
	v_mfma_f32_16x16x32_bf16 v[54:57], v[186:189], v[202:205], 0
	v_mfma_f32_16x16x32_bf16 v[50:53], v[194:197], v[202:205], 0
	v_mfma_f32_16x16x32_bf16 v[38:41], v[186:189], v[210:213], 0
	v_mfma_f32_16x16x32_bf16 v[34:37], v[194:197], v[210:213], 0
	v_mfma_f32_16x16x32_bf16 v[22:25], v[186:189], v[218:221], 0
	v_mfma_f32_16x16x32_bf16 v[18:21], v[194:197], v[218:221], 0
	v_mfma_f32_16x16x32_bf16 v[6:9], v[186:189], v[226:229], 0
	v_mfma_f32_16x16x32_bf16 v[2:5], v[194:197], v[226:229], 0
	v_mfma_f32_16x16x32_bf16 v[54:57], v[190:193], v[206:209], v[54:57]
	v_mfma_f32_16x16x32_bf16 v[50:53], v[198:201], v[206:209], v[50:53]
	v_mfma_f32_16x16x32_bf16 v[38:41], v[190:193], v[214:217], v[38:41]
	v_mfma_f32_16x16x32_bf16 v[34:37], v[198:201], v[214:217], v[34:37]
	v_mfma_f32_16x16x32_bf16 v[22:25], v[190:193], v[222:225], v[22:25]
	v_mfma_f32_16x16x32_bf16 v[18:21], v[198:201], v[222:225], v[18:21]
	s_setprio 2
	s_barrier
	v_mfma_f32_16x16x32_bf16 v[6:9], v[190:193], v[230:233], v[6:9]
	v_mfma_f32_16x16x32_bf16 v[2:5], v[198:201], v[230:233], v[2:5]
	s_setprio 0
	s_add_i32 s21, 0, 0x18000
	v_add_u32_e32 v153, s21, v179
	s_add_i32 s23, 0, 0x1c000
	ds_read_b128 v[130:133], v153
	ds_read_b128 v[134:137], v153 offset:1024
	ds_read_b128 v[164:167], v153 offset:2048
	ds_read_b128 v[182:185], v153 offset:3072
	v_add_u32_e32 v153, s23, v179
	ds_read_b128 v[186:189], v153
	ds_read_b128 v[190:193], v153 offset:1024
	ds_read_b128 v[194:197], v153 offset:2048
	ds_read_b128 v[198:201], v153 offset:3072
	s_add_u32 s44, s44, 0x80000
	s_addc_u32 s45, s45, 0
	s_mov_b32 m0, s47
	v_lshl_add_u64 v[240:241], s[44:45], 0, v[138:139]
	ds_read_b128 v[202:205], v181 offset:32768
	ds_read_b128 v[206:209], v181 offset:33792
	ds_read_b128 v[210:213], v181 offset:34816
	ds_read_b128 v[214:217], v181 offset:35840
	ds_read_b128 v[218:221], v181 offset:36864
	ds_read_b128 v[222:225], v181 offset:37888
	ds_read_b128 v[226:229], v181 offset:38912
	ds_read_b128 v[230:233], v181 offset:39936
	global_load_lds_dwordx4 v[240:241], off
	s_mov_b32 m0, s48
	v_lshl_add_u64 v[240:241], s[44:45], 0, v[140:141]
	global_load_lds_dwordx4 v[240:241], off
	s_waitcnt vmcnt(8)
	s_waitcnt lgkmcnt(0)
	s_barrier
	s_setprio 1
	s_waitcnt lgkmcnt(0)
	v_mfma_f32_16x16x32_bf16 v[126:129], v[130:133], v[202:205], v[126:129]
	v_mfma_f32_16x16x32_bf16 v[122:125], v[164:167], v[202:205], v[122:125]
	v_mfma_f32_16x16x32_bf16 v[110:113], v[130:133], v[210:213], v[110:113]
	v_mfma_f32_16x16x32_bf16 v[106:109], v[164:167], v[210:213], v[106:109]
	v_mfma_f32_16x16x32_bf16 v[94:97], v[130:133], v[218:221], v[94:97]
	v_mfma_f32_16x16x32_bf16 v[90:93], v[164:167], v[218:221], v[90:93]
	v_mfma_f32_16x16x32_bf16 v[78:81], v[130:133], v[226:229], v[78:81]
	v_mfma_f32_16x16x32_bf16 v[74:77], v[164:167], v[226:229], v[74:77]
	v_mfma_f32_16x16x32_bf16 v[126:129], v[134:137], v[206:209], v[126:129]
	v_mfma_f32_16x16x32_bf16 v[122:125], v[182:185], v[206:209], v[122:125]
	v_mfma_f32_16x16x32_bf16 v[110:113], v[134:137], v[214:217], v[110:113]
	v_mfma_f32_16x16x32_bf16 v[106:109], v[182:185], v[214:217], v[106:109]
	v_mfma_f32_16x16x32_bf16 v[94:97], v[134:137], v[222:225], v[94:97]
	v_mfma_f32_16x16x32_bf16 v[90:93], v[182:185], v[222:225], v[90:93]
	v_mfma_f32_16x16x32_bf16 v[78:81], v[134:137], v[230:233], v[78:81]
	v_mfma_f32_16x16x32_bf16 v[74:77], v[182:185], v[230:233], v[74:77]
	s_setprio 0
	s_setprio 1
	v_mfma_f32_16x16x32_bf16 v[118:121], v[186:189], v[202:205], v[118:121]
	v_mfma_f32_16x16x32_bf16 v[114:117], v[194:197], v[202:205], v[114:117]
	v_mfma_f32_16x16x32_bf16 v[102:105], v[186:189], v[210:213], v[102:105]
	v_mfma_f32_16x16x32_bf16 v[98:101], v[194:197], v[210:213], v[98:101]
	v_mfma_f32_16x16x32_bf16 v[86:89], v[186:189], v[218:221], v[86:89]
	v_mfma_f32_16x16x32_bf16 v[82:85], v[194:197], v[218:221], v[82:85]
	v_mfma_f32_16x16x32_bf16 v[70:73], v[186:189], v[226:229], v[70:73]
	v_mfma_f32_16x16x32_bf16 v[66:69], v[194:197], v[226:229], v[66:69]
	v_mfma_f32_16x16x32_bf16 v[118:121], v[190:193], v[206:209], v[118:121]
	v_mfma_f32_16x16x32_bf16 v[114:117], v[198:201], v[206:209], v[114:117]
	v_mfma_f32_16x16x32_bf16 v[102:105], v[190:193], v[214:217], v[102:105]
	v_mfma_f32_16x16x32_bf16 v[98:101], v[198:201], v[214:217], v[98:101]
	v_mfma_f32_16x16x32_bf16 v[86:89], v[190:193], v[222:225], v[86:89]
	v_mfma_f32_16x16x32_bf16 v[82:85], v[198:201], v[222:225], v[82:85]
	s_setprio 2
	s_barrier
	v_mfma_f32_16x16x32_bf16 v[70:73], v[190:193], v[230:233], v[70:73]
	v_mfma_f32_16x16x32_bf16 v[66:69], v[198:201], v[230:233], v[66:69]
	s_setprio 0
	s_add_i32 s21, s21, s25
	v_lshl_add_u64 v[168:169], v[168:169], 0, s[6:7]
	s_mov_b32 m0, s21
	ds_read_b128 v[202:205], v181 offset:49152
	ds_read_b128 v[206:209], v181 offset:50176
	ds_read_b128 v[210:213], v181 offset:51200
	ds_read_b128 v[214:217], v181 offset:52224
	ds_read_b128 v[218:221], v181 offset:53248
	ds_read_b128 v[222:225], v181 offset:54272
	ds_read_b128 v[226:229], v181 offset:55296
	ds_read_b128 v[230:233], v181 offset:56320
	global_load_lds_dwordx4 v[168:169], off
	s_add_i32 m0, s21, 0x2000
	s_add_u32 s42, s42, 0x80080
	v_lshl_add_u64 v[168:169], v[234:235], 0, s[6:7]
	s_addc_u32 s43, s43, 0
	s_add_i32 s21, s23, s25
	global_load_lds_dwordx4 v[168:169], off
	s_mov_b32 m0, s21
	v_lshl_add_u64 v[168:169], s[42:43], 0, v[162:163]
	global_load_lds_dwordx4 v[168:169], off
	s_add_i32 m0, s21, 0x2000
	v_lshl_add_u64 v[168:169], s[42:43], 0, v[142:143]
	global_load_lds_dwordx4 v[168:169], off
	s_mov_b32 m0, s49
	v_lshl_add_u64 v[168:169], v[236:237], 0, s[6:7]
	global_load_lds_dwordx4 v[168:169], off
	s_mov_b32 m0, s50
	v_lshl_add_u64 v[168:169], v[238:239], 0, s[6:7]
	global_load_lds_dwordx4 v[168:169], off
	s_waitcnt vmcnt(8)
	s_waitcnt lgkmcnt(0)
	s_barrier
	s_setprio 1
	s_waitcnt lgkmcnt(0)
	v_mfma_f32_16x16x32_bf16 v[62:65], v[130:133], v[202:205], v[62:65]
	v_mfma_f32_16x16x32_bf16 v[58:61], v[164:167], v[202:205], v[58:61]
	v_mfma_f32_16x16x32_bf16 v[46:49], v[130:133], v[210:213], v[46:49]
	v_mfma_f32_16x16x32_bf16 v[42:45], v[164:167], v[210:213], v[42:45]
	v_mfma_f32_16x16x32_bf16 v[30:33], v[130:133], v[218:221], v[30:33]
	v_mfma_f32_16x16x32_bf16 v[26:29], v[164:167], v[218:221], v[26:29]
	v_mfma_f32_16x16x32_bf16 v[14:17], v[130:133], v[226:229], v[14:17]
	v_mfma_f32_16x16x32_bf16 v[10:13], v[164:167], v[226:229], v[10:13]
	v_mfma_f32_16x16x32_bf16 v[62:65], v[134:137], v[206:209], v[62:65]
	v_mfma_f32_16x16x32_bf16 v[58:61], v[182:185], v[206:209], v[58:61]
	v_mfma_f32_16x16x32_bf16 v[46:49], v[134:137], v[214:217], v[46:49]
	v_mfma_f32_16x16x32_bf16 v[42:45], v[182:185], v[214:217], v[42:45]
	v_mfma_f32_16x16x32_bf16 v[30:33], v[134:137], v[222:225], v[30:33]
	v_mfma_f32_16x16x32_bf16 v[26:29], v[182:185], v[222:225], v[26:29]
	v_mfma_f32_16x16x32_bf16 v[14:17], v[134:137], v[230:233], v[14:17]
	v_mfma_f32_16x16x32_bf16 v[10:13], v[182:185], v[230:233], v[10:13]
	s_setprio 0
	s_setprio 1
	v_mfma_f32_16x16x32_bf16 v[54:57], v[186:189], v[202:205], v[54:57]
	v_mfma_f32_16x16x32_bf16 v[50:53], v[194:197], v[202:205], v[50:53]
	v_mfma_f32_16x16x32_bf16 v[38:41], v[186:189], v[210:213], v[38:41]
	v_mfma_f32_16x16x32_bf16 v[34:37], v[194:197], v[210:213], v[34:37]
	v_mfma_f32_16x16x32_bf16 v[22:25], v[186:189], v[218:221], v[22:25]
	v_mfma_f32_16x16x32_bf16 v[18:21], v[194:197], v[218:221], v[18:21]
	v_mfma_f32_16x16x32_bf16 v[6:9], v[186:189], v[226:229], v[6:9]
	v_mfma_f32_16x16x32_bf16 v[2:5], v[194:197], v[226:229], v[2:5]
	v_mfma_f32_16x16x32_bf16 v[54:57], v[190:193], v[206:209], v[54:57]
	v_mfma_f32_16x16x32_bf16 v[50:53], v[198:201], v[206:209], v[50:53]
	v_mfma_f32_16x16x32_bf16 v[38:41], v[190:193], v[214:217], v[38:41]
	v_mfma_f32_16x16x32_bf16 v[34:37], v[198:201], v[214:217], v[34:37]
	v_mfma_f32_16x16x32_bf16 v[22:25], v[190:193], v[222:225], v[22:25]
	v_mfma_f32_16x16x32_bf16 v[18:21], v[198:201], v[222:225], v[18:21]
	s_setprio 2
	s_barrier
	v_mfma_f32_16x16x32_bf16 v[6:9], v[190:193], v[230:233], v[6:9]
	v_mfma_f32_16x16x32_bf16 v[2:5], v[198:201], v[230:233], v[2:5]
	s_setprio 0
	s_add_i32 s20, s20, 2
	s_add_u32 s36, s36, 0x100
	s_addc_u32 s37, s37, 0
	s_add_u32 s13, s13, 0x100
	s_addc_u32 s19, s19, 0
	s_cmp_gt_u32 s20, 29
.LBB0_358:
	s_add_u32 s21, s36, 0xfff80080
	s_addc_u32 s23, s37, -1
	s_add_i32 s26, 0, 0x10000
	s_cmp_eq_u32 s20, 28
	s_cselect_b32 s45, s8, s23
	s_cselect_b32 s44, s9, s21
	v_add_u32_e32 v153, s26, v179
	s_cselect_b32 s43, s5, s19
	s_cselect_b32 s42, s11, s13
	s_add_i32 s21, 0, 0x14000
	ds_read_b128 v[130:133], v153
	ds_read_b128 v[134:137], v153 offset:1024
	ds_read_b128 v[164:167], v153 offset:2048
	ds_read_b128 v[182:185], v153 offset:3072
	v_add_u32_e32 v153, s21, v179
	ds_read_b128 v[186:189], v153
	ds_read_b128 v[190:193], v153 offset:1024
	ds_read_b128 v[194:197], v153 offset:2048
	ds_read_b128 v[198:201], v153 offset:3072
	v_lshl_add_u64 v[168:169], s[36:37], 0, v[148:149]
	s_add_i32 m0, s27, 0xc000
	ds_read_b128 v[202:205], v181
	ds_read_b128 v[206:209], v181 offset:1024
	ds_read_b128 v[210:213], v181 offset:2048
	ds_read_b128 v[214:217], v181 offset:3072
	ds_read_b128 v[218:221], v181 offset:4096
	ds_read_b128 v[222:225], v181 offset:5120
	ds_read_b128 v[226:229], v181 offset:6144
	ds_read_b128 v[230:233], v181 offset:7168
	global_load_lds_dwordx4 v[168:169], off
	s_add_i32 m0, s27, 0xe000
	v_lshl_add_u64 v[168:169], s[36:37], 0, v[150:151]
	global_load_lds_dwordx4 v[168:169], off
	s_waitcnt vmcnt(8)
	s_waitcnt lgkmcnt(0)
	s_barrier
	s_setprio 1
	s_waitcnt lgkmcnt(0)
	v_mfma_f32_16x16x32_bf16 v[126:129], v[130:133], v[202:205], v[126:129]
	v_mfma_f32_16x16x32_bf16 v[122:125], v[164:167], v[202:205], v[122:125]
	v_mfma_f32_16x16x32_bf16 v[110:113], v[130:133], v[210:213], v[110:113]
	v_mfma_f32_16x16x32_bf16 v[106:109], v[164:167], v[210:213], v[106:109]
	v_mfma_f32_16x16x32_bf16 v[94:97], v[130:133], v[218:221], v[94:97]
	v_mfma_f32_16x16x32_bf16 v[90:93], v[164:167], v[218:221], v[90:93]
	v_mfma_f32_16x16x32_bf16 v[78:81], v[130:133], v[226:229], v[78:81]
	v_mfma_f32_16x16x32_bf16 v[74:77], v[164:167], v[226:229], v[74:77]
	v_mfma_f32_16x16x32_bf16 v[126:129], v[134:137], v[206:209], v[126:129]
	v_mfma_f32_16x16x32_bf16 v[122:125], v[182:185], v[206:209], v[122:125]
	v_mfma_f32_16x16x32_bf16 v[110:113], v[134:137], v[214:217], v[110:113]
	v_mfma_f32_16x16x32_bf16 v[106:109], v[182:185], v[214:217], v[106:109]
	v_mfma_f32_16x16x32_bf16 v[94:97], v[134:137], v[222:225], v[94:97]
	v_mfma_f32_16x16x32_bf16 v[90:93], v[182:185], v[222:225], v[90:93]
	v_mfma_f32_16x16x32_bf16 v[78:81], v[134:137], v[230:233], v[78:81]
	v_mfma_f32_16x16x32_bf16 v[74:77], v[182:185], v[230:233], v[74:77]
	s_setprio 0
	s_setprio 1
	v_mfma_f32_16x16x32_bf16 v[118:121], v[186:189], v[202:205], v[118:121]
	v_mfma_f32_16x16x32_bf16 v[114:117], v[194:197], v[202:205], v[114:117]
	v_mfma_f32_16x16x32_bf16 v[102:105], v[186:189], v[210:213], v[102:105]
	v_mfma_f32_16x16x32_bf16 v[98:101], v[194:197], v[210:213], v[98:101]
	v_mfma_f32_16x16x32_bf16 v[86:89], v[186:189], v[218:221], v[86:89]
	v_mfma_f32_16x16x32_bf16 v[82:85], v[194:197], v[218:221], v[82:85]
	v_mfma_f32_16x16x32_bf16 v[70:73], v[186:189], v[226:229], v[70:73]
	v_mfma_f32_16x16x32_bf16 v[66:69], v[194:197], v[226:229], v[66:69]
	v_mfma_f32_16x16x32_bf16 v[118:121], v[190:193], v[206:209], v[118:121]
	v_mfma_f32_16x16x32_bf16 v[114:117], v[198:201], v[206:209], v[114:117]
	v_mfma_f32_16x16x32_bf16 v[102:105], v[190:193], v[214:217], v[102:105]
	v_mfma_f32_16x16x32_bf16 v[98:101], v[198:201], v[214:217], v[98:101]
	v_mfma_f32_16x16x32_bf16 v[86:89], v[190:193], v[222:225], v[86:89]
	v_mfma_f32_16x16x32_bf16 v[82:85], v[198:201], v[222:225], v[82:85]
	s_setprio 2
	s_barrier
	v_mfma_f32_16x16x32_bf16 v[70:73], v[190:193], v[230:233], v[70:73]
	v_mfma_f32_16x16x32_bf16 v[66:69], v[198:201], v[230:233], v[66:69]
	s_setprio 0
	s_add_i32 s23, s26, s25
	v_lshl_add_u64 v[168:169], s[42:43], 0, v[162:163]
	s_mov_b32 m0, s23
	ds_read_b128 v[202:205], v181 offset:16384
	ds_read_b128 v[206:209], v181 offset:17408
	ds_read_b128 v[210:213], v181 offset:18432
	ds_read_b128 v[214:217], v181 offset:19456
	ds_read_b128 v[218:221], v181 offset:20480
	ds_read_b128 v[222:225], v181 offset:21504
	ds_read_b128 v[226:229], v181 offset:22528
	ds_read_b128 v[230:233], v181 offset:23552
	global_load_lds_dwordx4 v[168:169], off
	s_add_i32 m0, s23, 0x2000
	s_add_u32 s52, s42, 0x80000
	v_lshl_add_u64 v[234:235], s[42:43], 0, v[142:143]
	s_addc_u32 s53, s43, 0
	s_add_i32 s21, s21, s25
	global_load_lds_dwordx4 v[234:235], off
	v_lshl_add_u64 v[236:237], s[52:53], 0, v[162:163]
	s_mov_b32 m0, s21
	v_lshl_add_u64 v[238:239], s[44:45], 0, v[140:141]
	global_load_lds_dwordx4 v[236:237], off
	s_add_i32 m0, s21, 0x2000
	v_lshl_add_u64 v[236:237], s[52:53], 0, v[142:143]
	global_load_lds_dwordx4 v[236:237], off
	s_mov_b32 m0, s27
	v_lshl_add_u64 v[236:237], s[44:45], 0, v[138:139]
	global_load_lds_dwordx4 v[236:237], off
	s_mov_b32 m0, s46
	s_nop 0
	global_load_lds_dwordx4 v[238:239], off
	s_waitcnt vmcnt(8)
	s_waitcnt lgkmcnt(0)
	s_barrier
	s_setprio 1
	s_waitcnt lgkmcnt(0)
	v_mfma_f32_16x16x32_bf16 v[62:65], v[130:133], v[202:205], v[62:65]
	v_mfma_f32_16x16x32_bf16 v[58:61], v[164:167], v[202:205], v[58:61]
	v_mfma_f32_16x16x32_bf16 v[46:49], v[130:133], v[210:213], v[46:49]
	v_mfma_f32_16x16x32_bf16 v[42:45], v[164:167], v[210:213], v[42:45]
	v_mfma_f32_16x16x32_bf16 v[30:33], v[130:133], v[218:221], v[30:33]
	v_mfma_f32_16x16x32_bf16 v[26:29], v[164:167], v[218:221], v[26:29]
	v_mfma_f32_16x16x32_bf16 v[14:17], v[130:133], v[226:229], v[14:17]
	v_mfma_f32_16x16x32_bf16 v[10:13], v[164:167], v[226:229], v[10:13]
	v_mfma_f32_16x16x32_bf16 v[62:65], v[134:137], v[206:209], v[62:65]
	v_mfma_f32_16x16x32_bf16 v[58:61], v[182:185], v[206:209], v[58:61]
	v_mfma_f32_16x16x32_bf16 v[46:49], v[134:137], v[214:217], v[46:49]
	v_mfma_f32_16x16x32_bf16 v[42:45], v[182:185], v[214:217], v[42:45]
	v_mfma_f32_16x16x32_bf16 v[30:33], v[134:137], v[222:225], v[30:33]
	v_mfma_f32_16x16x32_bf16 v[26:29], v[182:185], v[222:225], v[26:29]
	v_mfma_f32_16x16x32_bf16 v[14:17], v[134:137], v[230:233], v[14:17]
	v_mfma_f32_16x16x32_bf16 v[10:13], v[182:185], v[230:233], v[10:13]
	s_setprio 0
	s_setprio 1
	v_mfma_f32_16x16x32_bf16 v[54:57], v[186:189], v[202:205], v[54:57]
	v_mfma_f32_16x16x32_bf16 v[50:53], v[194:197], v[202:205], v[50:53]
	v_mfma_f32_16x16x32_bf16 v[38:41], v[186:189], v[210:213], v[38:41]
	v_mfma_f32_16x16x32_bf16 v[34:37], v[194:197], v[210:213], v[34:37]
	v_mfma_f32_16x16x32_bf16 v[22:25], v[186:189], v[218:221], v[22:25]
	v_mfma_f32_16x16x32_bf16 v[18:21], v[194:197], v[218:221], v[18:21]
	v_mfma_f32_16x16x32_bf16 v[6:9], v[186:189], v[226:229], v[6:9]
	v_mfma_f32_16x16x32_bf16 v[2:5], v[194:197], v[226:229], v[2:5]
	v_mfma_f32_16x16x32_bf16 v[54:57], v[190:193], v[206:209], v[54:57]
	v_mfma_f32_16x16x32_bf16 v[50:53], v[198:201], v[206:209], v[50:53]
	v_mfma_f32_16x16x32_bf16 v[38:41], v[190:193], v[214:217], v[38:41]
	v_mfma_f32_16x16x32_bf16 v[34:37], v[198:201], v[214:217], v[34:37]
	v_mfma_f32_16x16x32_bf16 v[22:25], v[190:193], v[222:225], v[22:25]
	v_mfma_f32_16x16x32_bf16 v[18:21], v[198:201], v[222:225], v[18:21]
	s_setprio 2
	s_barrier
	v_mfma_f32_16x16x32_bf16 v[6:9], v[190:193], v[230:233], v[6:9]
	v_mfma_f32_16x16x32_bf16 v[2:5], v[198:201], v[230:233], v[2:5]
	s_setprio 0
	s_add_i32 s21, 0, 0x18000
	v_add_u32_e32 v153, s21, v179
	s_add_i32 s23, 0, 0x1c000
	ds_read_b128 v[130:133], v153
	ds_read_b128 v[134:137], v153 offset:1024
	ds_read_b128 v[164:167], v153 offset:2048
	ds_read_b128 v[182:185], v153 offset:3072
	v_add_u32_e32 v153, s23, v179
	ds_read_b128 v[186:189], v153
	ds_read_b128 v[190:193], v153 offset:1024
	ds_read_b128 v[194:197], v153 offset:2048
	ds_read_b128 v[198:201], v153 offset:3072
	s_add_u32 s44, s44, 0x80000
	s_addc_u32 s45, s45, 0
	s_mov_b32 m0, s47
	v_lshl_add_u64 v[240:241], s[44:45], 0, v[138:139]
	ds_read_b128 v[202:205], v181 offset:32768
	ds_read_b128 v[206:209], v181 offset:33792
	ds_read_b128 v[210:213], v181 offset:34816
	ds_read_b128 v[214:217], v181 offset:35840
	ds_read_b128 v[218:221], v181 offset:36864
	ds_read_b128 v[222:225], v181 offset:37888
	ds_read_b128 v[226:229], v181 offset:38912
	ds_read_b128 v[230:233], v181 offset:39936
	global_load_lds_dwordx4 v[240:241], off
	s_mov_b32 m0, s48
	v_lshl_add_u64 v[240:241], s[44:45], 0, v[140:141]
	global_load_lds_dwordx4 v[240:241], off
	s_waitcnt vmcnt(8)
	s_waitcnt lgkmcnt(0)
	s_barrier
	s_setprio 1
	s_waitcnt lgkmcnt(0)
	v_mfma_f32_16x16x32_bf16 v[126:129], v[130:133], v[202:205], v[126:129]
	v_mfma_f32_16x16x32_bf16 v[122:125], v[164:167], v[202:205], v[122:125]
	v_mfma_f32_16x16x32_bf16 v[110:113], v[130:133], v[210:213], v[110:113]
	v_mfma_f32_16x16x32_bf16 v[106:109], v[164:167], v[210:213], v[106:109]
	v_mfma_f32_16x16x32_bf16 v[94:97], v[130:133], v[218:221], v[94:97]
	v_mfma_f32_16x16x32_bf16 v[90:93], v[164:167], v[218:221], v[90:93]
	v_mfma_f32_16x16x32_bf16 v[78:81], v[130:133], v[226:229], v[78:81]
	v_mfma_f32_16x16x32_bf16 v[74:77], v[164:167], v[226:229], v[74:77]
	v_mfma_f32_16x16x32_bf16 v[126:129], v[134:137], v[206:209], v[126:129]
	v_mfma_f32_16x16x32_bf16 v[122:125], v[182:185], v[206:209], v[122:125]
	v_mfma_f32_16x16x32_bf16 v[110:113], v[134:137], v[214:217], v[110:113]
	v_mfma_f32_16x16x32_bf16 v[106:109], v[182:185], v[214:217], v[106:109]
	v_mfma_f32_16x16x32_bf16 v[94:97], v[134:137], v[222:225], v[94:97]
	v_mfma_f32_16x16x32_bf16 v[90:93], v[182:185], v[222:225], v[90:93]
	v_mfma_f32_16x16x32_bf16 v[78:81], v[134:137], v[230:233], v[78:81]
	v_mfma_f32_16x16x32_bf16 v[74:77], v[182:185], v[230:233], v[74:77]
	s_setprio 0
	s_setprio 1
	v_mfma_f32_16x16x32_bf16 v[118:121], v[186:189], v[202:205], v[118:121]
	v_mfma_f32_16x16x32_bf16 v[114:117], v[194:197], v[202:205], v[114:117]
	v_mfma_f32_16x16x32_bf16 v[102:105], v[186:189], v[210:213], v[102:105]
	v_mfma_f32_16x16x32_bf16 v[98:101], v[194:197], v[210:213], v[98:101]
	v_mfma_f32_16x16x32_bf16 v[86:89], v[186:189], v[218:221], v[86:89]
	v_mfma_f32_16x16x32_bf16 v[82:85], v[194:197], v[218:221], v[82:85]
	v_mfma_f32_16x16x32_bf16 v[70:73], v[186:189], v[226:229], v[70:73]
	v_mfma_f32_16x16x32_bf16 v[66:69], v[194:197], v[226:229], v[66:69]
	v_mfma_f32_16x16x32_bf16 v[118:121], v[190:193], v[206:209], v[118:121]
	v_mfma_f32_16x16x32_bf16 v[114:117], v[198:201], v[206:209], v[114:117]
	v_mfma_f32_16x16x32_bf16 v[102:105], v[190:193], v[214:217], v[102:105]
	v_mfma_f32_16x16x32_bf16 v[98:101], v[198:201], v[214:217], v[98:101]
	v_mfma_f32_16x16x32_bf16 v[86:89], v[190:193], v[222:225], v[86:89]
	v_mfma_f32_16x16x32_bf16 v[82:85], v[198:201], v[222:225], v[82:85]
	s_setprio 2
	s_barrier
	v_mfma_f32_16x16x32_bf16 v[70:73], v[190:193], v[230:233], v[70:73]
	v_mfma_f32_16x16x32_bf16 v[66:69], v[198:201], v[230:233], v[66:69]
	s_setprio 0
	s_add_i32 s21, s21, s25
	v_lshl_add_u64 v[168:169], v[168:169], 0, s[6:7]
	s_mov_b32 m0, s21
	ds_read_b128 v[202:205], v181 offset:49152
	ds_read_b128 v[206:209], v181 offset:50176
	ds_read_b128 v[210:213], v181 offset:51200
	ds_read_b128 v[214:217], v181 offset:52224
	ds_read_b128 v[218:221], v181 offset:53248
	ds_read_b128 v[222:225], v181 offset:54272
	ds_read_b128 v[226:229], v181 offset:55296
	ds_read_b128 v[230:233], v181 offset:56320
	global_load_lds_dwordx4 v[168:169], off
	s_add_i32 m0, s21, 0x2000
	s_add_u32 s42, s42, 0x80080
	v_lshl_add_u64 v[168:169], v[234:235], 0, s[6:7]
	s_addc_u32 s43, s43, 0
	s_add_i32 s21, s23, s25
	global_load_lds_dwordx4 v[168:169], off
	s_mov_b32 m0, s21
	v_lshl_add_u64 v[168:169], s[42:43], 0, v[162:163]
	global_load_lds_dwordx4 v[168:169], off
	s_add_i32 m0, s21, 0x2000
	v_lshl_add_u64 v[168:169], s[42:43], 0, v[142:143]
	global_load_lds_dwordx4 v[168:169], off
	s_mov_b32 m0, s49
	v_lshl_add_u64 v[168:169], v[236:237], 0, s[6:7]
	global_load_lds_dwordx4 v[168:169], off
	s_mov_b32 m0, s50
	v_lshl_add_u64 v[168:169], v[238:239], 0, s[6:7]
	global_load_lds_dwordx4 v[168:169], off
	s_waitcnt vmcnt(8)
	s_waitcnt lgkmcnt(0)
	s_barrier
	s_setprio 1
	s_waitcnt lgkmcnt(0)
	v_mfma_f32_16x16x32_bf16 v[62:65], v[130:133], v[202:205], v[62:65]
	v_mfma_f32_16x16x32_bf16 v[58:61], v[164:167], v[202:205], v[58:61]
	v_mfma_f32_16x16x32_bf16 v[46:49], v[130:133], v[210:213], v[46:49]
	v_mfma_f32_16x16x32_bf16 v[42:45], v[164:167], v[210:213], v[42:45]
	v_mfma_f32_16x16x32_bf16 v[30:33], v[130:133], v[218:221], v[30:33]
	v_mfma_f32_16x16x32_bf16 v[26:29], v[164:167], v[218:221], v[26:29]
	v_mfma_f32_16x16x32_bf16 v[14:17], v[130:133], v[226:229], v[14:17]
	v_mfma_f32_16x16x32_bf16 v[10:13], v[164:167], v[226:229], v[10:13]
	v_mfma_f32_16x16x32_bf16 v[62:65], v[134:137], v[206:209], v[62:65]
	v_mfma_f32_16x16x32_bf16 v[58:61], v[182:185], v[206:209], v[58:61]
	v_mfma_f32_16x16x32_bf16 v[46:49], v[134:137], v[214:217], v[46:49]
	v_mfma_f32_16x16x32_bf16 v[42:45], v[182:185], v[214:217], v[42:45]
	v_mfma_f32_16x16x32_bf16 v[30:33], v[134:137], v[222:225], v[30:33]
	v_mfma_f32_16x16x32_bf16 v[26:29], v[182:185], v[222:225], v[26:29]
	v_mfma_f32_16x16x32_bf16 v[14:17], v[134:137], v[230:233], v[14:17]
	v_mfma_f32_16x16x32_bf16 v[10:13], v[182:185], v[230:233], v[10:13]
	s_setprio 0
	s_setprio 1
	v_mfma_f32_16x16x32_bf16 v[54:57], v[186:189], v[202:205], v[54:57]
	v_mfma_f32_16x16x32_bf16 v[50:53], v[194:197], v[202:205], v[50:53]
	v_mfma_f32_16x16x32_bf16 v[38:41], v[186:189], v[210:213], v[38:41]
	v_mfma_f32_16x16x32_bf16 v[34:37], v[194:197], v[210:213], v[34:37]
	v_mfma_f32_16x16x32_bf16 v[22:25], v[186:189], v[218:221], v[22:25]
	v_mfma_f32_16x16x32_bf16 v[18:21], v[194:197], v[218:221], v[18:21]
	v_mfma_f32_16x16x32_bf16 v[6:9], v[186:189], v[226:229], v[6:9]
	v_mfma_f32_16x16x32_bf16 v[2:5], v[194:197], v[226:229], v[2:5]
	v_mfma_f32_16x16x32_bf16 v[54:57], v[190:193], v[206:209], v[54:57]
	v_mfma_f32_16x16x32_bf16 v[50:53], v[198:201], v[206:209], v[50:53]
	v_mfma_f32_16x16x32_bf16 v[38:41], v[190:193], v[214:217], v[38:41]
	v_mfma_f32_16x16x32_bf16 v[34:37], v[198:201], v[214:217], v[34:37]
	v_mfma_f32_16x16x32_bf16 v[22:25], v[190:193], v[222:225], v[22:25]
	v_mfma_f32_16x16x32_bf16 v[18:21], v[198:201], v[222:225], v[18:21]
	s_setprio 2
	s_barrier
	v_mfma_f32_16x16x32_bf16 v[6:9], v[190:193], v[230:233], v[6:9]
	v_mfma_f32_16x16x32_bf16 v[2:5], v[198:201], v[230:233], v[2:5]
	s_setprio 0
	s_add_i32 s20, s20, 2
	s_add_u32 s36, s36, 0x100
	s_addc_u32 s37, s37, 0
	s_add_u32 s13, s13, 0x100
	s_addc_u32 s19, s19, 0
	s_cmp_gt_u32 s20, 29
	s_cbranch_scc0 .LBB0_358
	s_and_b64 vcc, exec, s[2:3]
	s_cbranch_vccz .LBB0_361
	s_barrier

.LBB0_1114:
	s_ashr_i32 s19, s18, 31
	s_lshl_b64 s[28:29], s[18:19], 20
	v_readlane_b32 s5, v245, 28
	s_add_u32 s28, s5, s28
	v_readlane_b32 s5, v245, 29
	s_addc_u32 s29, s5, s29
	s_and_b64 s[34:35], s[22:23], exec
	s_cselect_b32 s8, s29, s37
	s_cselect_b32 s19, s28, s36
	s_ashr_i32 s5, s4, 31
	s_lshl_b64 s[34:35], s[4:5], 20
	s_add_u32 s34, s11, s34
	s_addc_u32 s35, s13, s35
	s_and_b64 s[44:45], s[22:23], exec
	s_cselect_b32 s5, s35, s43
	s_cselect_b32 s21, s34, s42
	s_add_u32 s36, s36, 0x80080
	s_addc_u32 s37, s37, 0
	s_add_u32 s41, s42, 0x100
	s_addc_u32 s48, s43, 0
	s_mov_b32 s49, -2
	s_waitcnt vmcnt(0) lgkmcnt(0)
	s_add_u32 s42, s36, 0xfff80080
	s_addc_u32 s43, s37, -1
	s_add_i32 s50, 0, 0x10000
	s_cmp_eq_u32 s49, 28
	s_cselect_b32 s45, s8, s43
	s_cselect_b32 s44, s19, s42
	v_add_u32_e32 v154, s50, v145
	s_cselect_b32 s43, s5, s48
	s_cselect_b32 s42, s21, s41
	s_add_i32 s52, 0, 0x14000
	ds_read_b128 v[130:133], v154
	ds_read_b128 v[134:137], v154 offset:1024
	ds_read_b128 v[150:153], v154 offset:2048
	ds_read_b128 v[158:161], v154 offset:3072
	v_add_u32_e32 v154, s52, v145
	ds_read_b128 v[164:167], v154
	ds_read_b128 v[180:183], v154 offset:1024
	ds_read_b128 v[184:187], v154 offset:2048
	ds_read_b128 v[188:191], v154 offset:3072
	v_lshl_add_u64 v[154:155], s[36:37], 0, v[146:147]
	s_add_i32 m0, s20, 0xc000
	ds_read_b128 v[192:195], v157
	ds_read_b128 v[196:199], v157 offset:1024
	ds_read_b128 v[200:203], v157 offset:2048
	ds_read_b128 v[204:207], v157 offset:3072
	ds_read_b128 v[208:211], v157 offset:4096
	ds_read_b128 v[212:215], v157 offset:5120
	ds_read_b128 v[216:219], v157 offset:6144
	ds_read_b128 v[220:223], v157 offset:7168
	global_load_lds_dwordx4 v[154:155], off
	s_add_i32 m0, s20, 0xe000
	v_lshl_add_u64 v[154:155], s[36:37], 0, v[148:149]
	global_load_lds_dwordx4 v[154:155], off
	s_waitcnt vmcnt(8)
	s_waitcnt lgkmcnt(0)
	s_barrier
	s_setprio 1
	s_waitcnt lgkmcnt(0)
	v_mfma_f32_16x16x32_bf16 v[126:129], v[130:133], v[192:195], 0
	v_mfma_f32_16x16x32_bf16 v[122:125], v[150:153], v[192:195], 0
	v_mfma_f32_16x16x32_bf16 v[110:113], v[130:133], v[200:203], 0
	v_mfma_f32_16x16x32_bf16 v[106:109], v[150:153], v[200:203], 0
	v_mfma_f32_16x16x32_bf16 v[94:97], v[130:133], v[208:211], 0
	v_mfma_f32_16x16x32_bf16 v[90:93], v[150:153], v[208:211], 0
	v_mfma_f32_16x16x32_bf16 v[78:81], v[130:133], v[216:219], 0
	v_mfma_f32_16x16x32_bf16 v[74:77], v[150:153], v[216:219], 0
	v_mfma_f32_16x16x32_bf16 v[126:129], v[134:137], v[196:199], v[126:129]
	v_mfma_f32_16x16x32_bf16 v[122:125], v[158:161], v[196:199], v[122:125]
	v_mfma_f32_16x16x32_bf16 v[110:113], v[134:137], v[204:207], v[110:113]
	v_mfma_f32_16x16x32_bf16 v[106:109], v[158:161], v[204:207], v[106:109]
	v_mfma_f32_16x16x32_bf16 v[94:97], v[134:137], v[212:215], v[94:97]
	v_mfma_f32_16x16x32_bf16 v[90:93], v[158:161], v[212:215], v[90:93]
	v_mfma_f32_16x16x32_bf16 v[78:81], v[134:137], v[220:223], v[78:81]
	v_mfma_f32_16x16x32_bf16 v[74:77], v[158:161], v[220:223], v[74:77]
	s_setprio 0
	s_setprio 1
	v_mfma_f32_16x16x32_bf16 v[118:121], v[164:167], v[192:195], 0
	v_mfma_f32_16x16x32_bf16 v[114:117], v[184:187], v[192:195], 0
	v_mfma_f32_16x16x32_bf16 v[102:105], v[164:167], v[200:203], 0
	v_mfma_f32_16x16x32_bf16 v[98:101], v[184:187], v[200:203], 0
	v_mfma_f32_16x16x32_bf16 v[86:89], v[164:167], v[208:211], 0
	v_mfma_f32_16x16x32_bf16 v[82:85], v[184:187], v[208:211], 0
	v_mfma_f32_16x16x32_bf16 v[70:73], v[164:167], v[216:219], 0
	v_mfma_f32_16x16x32_bf16 v[66:69], v[184:187], v[216:219], 0
	v_mfma_f32_16x16x32_bf16 v[118:121], v[180:183], v[196:199], v[118:121]
	v_mfma_f32_16x16x32_bf16 v[114:117], v[188:191], v[196:199], v[114:117]
	v_mfma_f32_16x16x32_bf16 v[102:105], v[180:183], v[204:207], v[102:105]
	v_mfma_f32_16x16x32_bf16 v[98:101], v[188:191], v[204:207], v[98:101]
	v_mfma_f32_16x16x32_bf16 v[86:89], v[180:183], v[212:215], v[86:89]
	v_mfma_f32_16x16x32_bf16 v[82:85], v[188:191], v[212:215], v[82:85]
	s_setprio 2
	s_barrier
	v_mfma_f32_16x16x32_bf16 v[70:73], v[180:183], v[220:223], v[70:73]
	v_mfma_f32_16x16x32_bf16 v[66:69], v[188:191], v[220:223], v[66:69]
	s_setprio 0
	s_add_i32 s50, s50, s9
	v_lshl_add_u64 v[154:155], s[42:43], 0, v[162:163]
	s_mov_b32 m0, s50
	ds_read_b128 v[192:195], v157 offset:16384
	ds_read_b128 v[196:199], v157 offset:17408
	ds_read_b128 v[200:203], v157 offset:18432
	ds_read_b128 v[204:207], v157 offset:19456
	ds_read_b128 v[208:211], v157 offset:20480
	ds_read_b128 v[212:215], v157 offset:21504
	ds_read_b128 v[216:219], v157 offset:22528
	ds_read_b128 v[220:223], v157 offset:23552
	global_load_lds_dwordx4 v[154:155], off
	s_add_i32 m0, s50, 0x2000
	s_add_u32 s50, s42, 0x80000
	v_lshl_add_u64 v[168:169], s[42:43], 0, v[142:143]
	s_addc_u32 s51, s43, 0
	s_add_i32 s52, s52, s9
	global_load_lds_dwordx4 v[168:169], off
	v_lshl_add_u64 v[224:225], s[50:51], 0, v[162:163]
	s_mov_b32 m0, s52
	v_lshl_add_u64 v[226:227], s[44:45], 0, v[140:141]
	global_load_lds_dwordx4 v[224:225], off
	s_add_i32 m0, s52, 0x2000
	v_lshl_add_u64 v[224:225], s[50:51], 0, v[142:143]
	global_load_lds_dwordx4 v[224:225], off
	s_mov_b32 m0, s20
	v_lshl_add_u64 v[224:225], s[44:45], 0, v[138:139]
	global_load_lds_dwordx4 v[224:225], off
	s_mov_b32 m0, s25
	s_nop 0
	global_load_lds_dwordx4 v[226:227], off
	s_waitcnt vmcnt(8)
	s_waitcnt lgkmcnt(0)
	s_barrier
	s_setprio 1
	s_waitcnt lgkmcnt(0)
	v_mfma_f32_16x16x32_bf16 v[62:65], v[130:133], v[192:195], 0
	v_mfma_f32_16x16x32_bf16 v[58:61], v[150:153], v[192:195], 0
	v_mfma_f32_16x16x32_bf16 v[46:49], v[130:133], v[200:203], 0
	v_mfma_f32_16x16x32_bf16 v[42:45], v[150:153], v[200:203], 0
	v_mfma_f32_16x16x32_bf16 v[30:33], v[130:133], v[208:211], 0
	v_mfma_f32_16x16x32_bf16 v[26:29], v[150:153], v[208:211], 0
	v_mfma_f32_16x16x32_bf16 v[14:17], v[130:133], v[216:219], 0
	v_mfma_f32_16x16x32_bf16 v[10:13], v[150:153], v[216:219], 0
	v_mfma_f32_16x16x32_bf16 v[62:65], v[134:137], v[196:199], v[62:65]
	v_mfma_f32_16x16x32_bf16 v[58:61], v[158:161], v[196:199], v[58:61]
	v_mfma_f32_16x16x32_bf16 v[46:49], v[134:137], v[204:207], v[46:49]
	v_mfma_f32_16x16x32_bf16 v[42:45], v[158:161], v[204:207], v[42:45]
	v_mfma_f32_16x16x32_bf16 v[30:33], v[134:137], v[212:215], v[30:33]
	v_mfma_f32_16x16x32_bf16 v[26:29], v[158:161], v[212:215], v[26:29]
	v_mfma_f32_16x16x32_bf16 v[14:17], v[134:137], v[220:223], v[14:17]
	v_mfma_f32_16x16x32_bf16 v[10:13], v[158:161], v[220:223], v[10:13]
	s_setprio 0
	s_setprio 1
	v_mfma_f32_16x16x32_bf16 v[54:57], v[164:167], v[192:195], 0
	v_mfma_f32_16x16x32_bf16 v[50:53], v[184:187], v[192:195], 0
	v_mfma_f32_16x16x32_bf16 v[38:41], v[164:167], v[200:203], 0
	v_mfma_f32_16x16x32_bf16 v[34:37], v[184:187], v[200:203], 0
	v_mfma_f32_16x16x32_bf16 v[22:25], v[164:167], v[208:211], 0
	v_mfma_f32_16x16x32_bf16 v[18:21], v[184:187], v[208:211], 0
	v_mfma_f32_16x16x32_bf16 v[6:9], v[164:167], v[216:219], 0
	v_mfma_f32_16x16x32_bf16 v[2:5], v[184:187], v[216:219], 0
	v_mfma_f32_16x16x32_bf16 v[54:57], v[180:183], v[196:199], v[54:57]
	v_mfma_f32_16x16x32_bf16 v[50:53], v[188:191], v[196:199], v[50:53]
	v_mfma_f32_16x16x32_bf16 v[38:41], v[180:183], v[204:207], v[38:41]
	v_mfma_f32_16x16x32_bf16 v[34:37], v[188:191], v[204:207], v[34:37]
	v_mfma_f32_16x16x32_bf16 v[22:25], v[180:183], v[212:215], v[22:25]
	v_mfma_f32_16x16x32_bf16 v[18:21], v[188:191], v[212:215], v[18:21]
	s_setprio 2
	s_barrier
	v_mfma_f32_16x16x32_bf16 v[6:9], v[180:183], v[220:223], v[6:9]
	v_mfma_f32_16x16x32_bf16 v[2:5], v[188:191], v[220:223], v[2:5]
	s_setprio 0
	s_add_i32 s50, 0, 0x18000
	s_add_i32 s51, 0, 0x1c000
	v_add_u32_e32 v158, s50, v145
	v_add_u32_e32 v179, s51, v145
	ds_read_b128 v[130:133], v158
	ds_read_b128 v[134:137], v158 offset:1024
	ds_read_b128 v[150:153], v158 offset:2048
	ds_read_b128 v[158:161], v158 offset:3072
	ds_read_b128 v[164:167], v179
	ds_read_b128 v[180:183], v179 offset:1024
	ds_read_b128 v[184:187], v179 offset:2048
	ds_read_b128 v[188:191], v179 offset:3072
	s_add_u32 s44, s44, 0x80000
	s_addc_u32 s45, s45, 0
	s_mov_b32 m0, s26
	v_lshl_add_u64 v[228:229], s[44:45], 0, v[138:139]
	ds_read_b128 v[192:195], v157 offset:32768
	ds_read_b128 v[196:199], v157 offset:33792
	ds_read_b128 v[200:203], v157 offset:34816
	ds_read_b128 v[204:207], v157 offset:35840
	ds_read_b128 v[208:211], v157 offset:36864
	ds_read_b128 v[212:215], v157 offset:37888
	ds_read_b128 v[216:219], v157 offset:38912
	ds_read_b128 v[220:223], v157 offset:39936
	global_load_lds_dwordx4 v[228:229], off
	s_mov_b32 m0, s27
	v_lshl_add_u64 v[228:229], s[44:45], 0, v[140:141]
	global_load_lds_dwordx4 v[228:229], off
	s_waitcnt vmcnt(8)
	s_waitcnt lgkmcnt(0)
	s_barrier
	s_setprio 1
	s_waitcnt lgkmcnt(0)
	v_mfma_f32_16x16x32_bf16 v[126:129], v[130:133], v[192:195], v[126:129]
	v_mfma_f32_16x16x32_bf16 v[122:125], v[150:153], v[192:195], v[122:125]
	v_mfma_f32_16x16x32_bf16 v[110:113], v[130:133], v[200:203], v[110:113]
	v_mfma_f32_16x16x32_bf16 v[106:109], v[150:153], v[200:203], v[106:109]
	v_mfma_f32_16x16x32_bf16 v[94:97], v[130:133], v[208:211], v[94:97]
	v_mfma_f32_16x16x32_bf16 v[90:93], v[150:153], v[208:211], v[90:93]
	v_mfma_f32_16x16x32_bf16 v[78:81], v[130:133], v[216:219], v[78:81]
	v_mfma_f32_16x16x32_bf16 v[74:77], v[150:153], v[216:219], v[74:77]
	v_mfma_f32_16x16x32_bf16 v[126:129], v[134:137], v[196:199], v[126:129]
	v_mfma_f32_16x16x32_bf16 v[122:125], v[158:161], v[196:199], v[122:125]
	v_mfma_f32_16x16x32_bf16 v[110:113], v[134:137], v[204:207], v[110:113]
	v_mfma_f32_16x16x32_bf16 v[106:109], v[158:161], v[204:207], v[106:109]
	v_mfma_f32_16x16x32_bf16 v[94:97], v[134:137], v[212:215], v[94:97]
	v_mfma_f32_16x16x32_bf16 v[90:93], v[158:161], v[212:215], v[90:93]
	v_mfma_f32_16x16x32_bf16 v[78:81], v[134:137], v[220:223], v[78:81]
	v_mfma_f32_16x16x32_bf16 v[74:77], v[158:161], v[220:223], v[74:77]
	s_setprio 0
	s_setprio 1
	v_mfma_f32_16x16x32_bf16 v[118:121], v[164:167], v[192:195], v[118:121]
	v_mfma_f32_16x16x32_bf16 v[114:117], v[184:187], v[192:195], v[114:117]
	v_mfma_f32_16x16x32_bf16 v[102:105], v[164:167], v[200:203], v[102:105]
	v_mfma_f32_16x16x32_bf16 v[98:101], v[184:187], v[200:203], v[98:101]
	v_mfma_f32_16x16x32_bf16 v[86:89], v[164:167], v[208:211], v[86:89]
	v_mfma_f32_16x16x32_bf16 v[82:85], v[184:187], v[208:211], v[82:85]
	v_mfma_f32_16x16x32_bf16 v[70:73], v[164:167], v[216:219], v[70:73]
	v_mfma_f32_16x16x32_bf16 v[66:69], v[184:187], v[216:219], v[66:69]
	v_mfma_f32_16x16x32_bf16 v[118:121], v[180:183], v[196:199], v[118:121]
	v_mfma_f32_16x16x32_bf16 v[114:117], v[188:191], v[196:199], v[114:117]
	v_mfma_f32_16x16x32_bf16 v[102:105], v[180:183], v[204:207], v[102:105]
	v_mfma_f32_16x16x32_bf16 v[98:101], v[188:191], v[204:207], v[98:101]
	v_mfma_f32_16x16x32_bf16 v[86:89], v[180:183], v[212:215], v[86:89]
	v_mfma_f32_16x16x32_bf16 v[82:85], v[188:191], v[212:215], v[82:85]
	s_setprio 2
	s_barrier
	v_mfma_f32_16x16x32_bf16 v[70:73], v[180:183], v[220:223], v[70:73]
	v_mfma_f32_16x16x32_bf16 v[66:69], v[188:191], v[220:223], v[66:69]
	s_setprio 0
	s_add_i32 s44, s50, s9
	v_lshl_add_u64 v[154:155], v[154:155], 0, s[6:7]
	s_mov_b32 m0, s44
	ds_read_b128 v[192:195], v157 offset:49152
	ds_read_b128 v[196:199], v157 offset:50176
	ds_read_b128 v[200:203], v157 offset:51200
	ds_read_b128 v[204:207], v157 offset:52224
	ds_read_b128 v[208:211], v157 offset:53248
	ds_read_b128 v[212:215], v157 offset:54272
	ds_read_b128 v[216:219], v157 offset:55296
	ds_read_b128 v[220:223], v157 offset:56320
	global_load_lds_dwordx4 v[154:155], off
	s_add_i32 m0, s44, 0x2000
	s_add_u32 s42, s42, 0x80080
	v_lshl_add_u64 v[154:155], v[168:169], 0, s[6:7]
	s_addc_u32 s43, s43, 0
	s_add_i32 s44, s51, s9
	global_load_lds_dwordx4 v[154:155], off
	s_mov_b32 m0, s44
	v_lshl_add_u64 v[154:155], s[42:43], 0, v[162:163]
	global_load_lds_dwordx4 v[154:155], off
	s_add_i32 m0, s44, 0x2000
	v_lshl_add_u64 v[154:155], s[42:43], 0, v[142:143]
	global_load_lds_dwordx4 v[154:155], off
	s_mov_b32 m0, s39
	v_lshl_add_u64 v[154:155], v[224:225], 0, s[6:7]
	global_load_lds_dwordx4 v[154:155], off
	s_mov_b32 m0, s46
	v_lshl_add_u64 v[154:155], v[226:227], 0, s[6:7]
	global_load_lds_dwordx4 v[154:155], off
	s_waitcnt vmcnt(8)
	s_waitcnt lgkmcnt(0)
	s_barrier
	s_setprio 1
	s_waitcnt lgkmcnt(0)
	v_mfma_f32_16x16x32_bf16 v[62:65], v[130:133], v[192:195], v[62:65]
	v_mfma_f32_16x16x32_bf16 v[58:61], v[150:153], v[192:195], v[58:61]
	v_mfma_f32_16x16x32_bf16 v[46:49], v[130:133], v[200:203], v[46:49]
	v_mfma_f32_16x16x32_bf16 v[42:45], v[150:153], v[200:203], v[42:45]
	v_mfma_f32_16x16x32_bf16 v[30:33], v[130:133], v[208:211], v[30:33]
	v_mfma_f32_16x16x32_bf16 v[26:29], v[150:153], v[208:211], v[26:29]
	v_mfma_f32_16x16x32_bf16 v[14:17], v[130:133], v[216:219], v[14:17]
	v_mfma_f32_16x16x32_bf16 v[10:13], v[150:153], v[216:219], v[10:13]
	v_mfma_f32_16x16x32_bf16 v[62:65], v[134:137], v[196:199], v[62:65]
	v_mfma_f32_16x16x32_bf16 v[58:61], v[158:161], v[196:199], v[58:61]
	v_mfma_f32_16x16x32_bf16 v[46:49], v[134:137], v[204:207], v[46:49]
	v_mfma_f32_16x16x32_bf16 v[42:45], v[158:161], v[204:207], v[42:45]
	v_mfma_f32_16x16x32_bf16 v[30:33], v[134:137], v[212:215], v[30:33]
	v_mfma_f32_16x16x32_bf16 v[26:29], v[158:161], v[212:215], v[26:29]
	v_mfma_f32_16x16x32_bf16 v[14:17], v[134:137], v[220:223], v[14:17]
	v_mfma_f32_16x16x32_bf16 v[10:13], v[158:161], v[220:223], v[10:13]
	s_setprio 0
	s_setprio 1
	v_mfma_f32_16x16x32_bf16 v[54:57], v[164:167], v[192:195], v[54:57]
	v_mfma_f32_16x16x32_bf16 v[50:53], v[184:187], v[192:195], v[50:53]
	v_mfma_f32_16x16x32_bf16 v[38:41], v[164:167], v[200:203], v[38:41]
	v_mfma_f32_16x16x32_bf16 v[34:37], v[184:187], v[200:203], v[34:37]
	v_mfma_f32_16x16x32_bf16 v[22:25], v[164:167], v[208:211], v[22:25]
	v_mfma_f32_16x16x32_bf16 v[18:21], v[184:187], v[208:211], v[18:21]
	v_mfma_f32_16x16x32_bf16 v[6:9], v[164:167], v[216:219], v[6:9]
	v_mfma_f32_16x16x32_bf16 v[2:5], v[184:187], v[216:219], v[2:5]
	v_mfma_f32_16x16x32_bf16 v[54:57], v[180:183], v[196:199], v[54:57]
	v_mfma_f32_16x16x32_bf16 v[50:53], v[188:191], v[196:199], v[50:53]
	v_mfma_f32_16x16x32_bf16 v[38:41], v[180:183], v[204:207], v[38:41]
	v_mfma_f32_16x16x32_bf16 v[34:37], v[188:191], v[204:207], v[34:37]
	v_mfma_f32_16x16x32_bf16 v[22:25], v[180:183], v[212:215], v[22:25]
	v_mfma_f32_16x16x32_bf16 v[18:21], v[188:191], v[212:215], v[18:21]
	s_setprio 2
	s_barrier
	v_mfma_f32_16x16x32_bf16 v[6:9], v[180:183], v[220:223], v[6:9]
	v_mfma_f32_16x16x32_bf16 v[2:5], v[188:191], v[220:223], v[2:5]
	s_setprio 0
	s_add_i32 s49, s49, 2
	s_add_u32 s36, s36, 0x100
	s_addc_u32 s37, s37, 0
	s_add_u32 s41, s41, 0x100
	s_addc_u32 s48, s48, 0
	s_cmp_gt_u32 s49, 29
.LBB0_1115:
	s_add_u32 s42, s36, 0xfff80080
	s_addc_u32 s43, s37, -1
	s_add_i32 s50, 0, 0x10000
	s_cmp_eq_u32 s49, 28
	s_cselect_b32 s45, s8, s43
	s_cselect_b32 s44, s19, s42
	v_add_u32_e32 v154, s50, v145
	s_cselect_b32 s43, s5, s48
	s_cselect_b32 s42, s21, s41
	s_add_i32 s52, 0, 0x14000
	ds_read_b128 v[130:133], v154
	ds_read_b128 v[134:137], v154 offset:1024
	ds_read_b128 v[150:153], v154 offset:2048
	ds_read_b128 v[158:161], v154 offset:3072
	v_add_u32_e32 v154, s52, v145
	ds_read_b128 v[164:167], v154
	ds_read_b128 v[180:183], v154 offset:1024
	ds_read_b128 v[184:187], v154 offset:2048
	ds_read_b128 v[188:191], v154 offset:3072
	v_lshl_add_u64 v[154:155], s[36:37], 0, v[146:147]
	s_add_i32 m0, s20, 0xc000
	ds_read_b128 v[192:195], v157
	ds_read_b128 v[196:199], v157 offset:1024
	ds_read_b128 v[200:203], v157 offset:2048
	ds_read_b128 v[204:207], v157 offset:3072
	ds_read_b128 v[208:211], v157 offset:4096
	ds_read_b128 v[212:215], v157 offset:5120
	ds_read_b128 v[216:219], v157 offset:6144
	ds_read_b128 v[220:223], v157 offset:7168
	global_load_lds_dwordx4 v[154:155], off
	s_add_i32 m0, s20, 0xe000
	v_lshl_add_u64 v[154:155], s[36:37], 0, v[148:149]
	global_load_lds_dwordx4 v[154:155], off
	s_waitcnt vmcnt(8)
	s_waitcnt lgkmcnt(0)
	s_barrier
	s_setprio 1
	s_waitcnt lgkmcnt(0)
	v_mfma_f32_16x16x32_bf16 v[126:129], v[130:133], v[192:195], v[126:129]
	v_mfma_f32_16x16x32_bf16 v[122:125], v[150:153], v[192:195], v[122:125]
	v_mfma_f32_16x16x32_bf16 v[110:113], v[130:133], v[200:203], v[110:113]
	v_mfma_f32_16x16x32_bf16 v[106:109], v[150:153], v[200:203], v[106:109]
	v_mfma_f32_16x16x32_bf16 v[94:97], v[130:133], v[208:211], v[94:97]
	v_mfma_f32_16x16x32_bf16 v[90:93], v[150:153], v[208:211], v[90:93]
	v_mfma_f32_16x16x32_bf16 v[78:81], v[130:133], v[216:219], v[78:81]
	v_mfma_f32_16x16x32_bf16 v[74:77], v[150:153], v[216:219], v[74:77]
	v_mfma_f32_16x16x32_bf16 v[126:129], v[134:137], v[196:199], v[126:129]
	v_mfma_f32_16x16x32_bf16 v[122:125], v[158:161], v[196:199], v[122:125]
	v_mfma_f32_16x16x32_bf16 v[110:113], v[134:137], v[204:207], v[110:113]
	v_mfma_f32_16x16x32_bf16 v[106:109], v[158:161], v[204:207], v[106:109]
	v_mfma_f32_16x16x32_bf16 v[94:97], v[134:137], v[212:215], v[94:97]
	v_mfma_f32_16x16x32_bf16 v[90:93], v[158:161], v[212:215], v[90:93]
	v_mfma_f32_16x16x32_bf16 v[78:81], v[134:137], v[220:223], v[78:81]
	v_mfma_f32_16x16x32_bf16 v[74:77], v[158:161], v[220:223], v[74:77]
	s_setprio 0
	s_setprio 1
	v_mfma_f32_16x16x32_bf16 v[118:121], v[164:167], v[192:195], v[118:121]
	v_mfma_f32_16x16x32_bf16 v[114:117], v[184:187], v[192:195], v[114:117]
	v_mfma_f32_16x16x32_bf16 v[102:105], v[164:167], v[200:203], v[102:105]
	v_mfma_f32_16x16x32_bf16 v[98:101], v[184:187], v[200:203], v[98:101]
	v_mfma_f32_16x16x32_bf16 v[86:89], v[164:167], v[208:211], v[86:89]
	v_mfma_f32_16x16x32_bf16 v[82:85], v[184:187], v[208:211], v[82:85]
	v_mfma_f32_16x16x32_bf16 v[70:73], v[164:167], v[216:219], v[70:73]
	v_mfma_f32_16x16x32_bf16 v[66:69], v[184:187], v[216:219], v[66:69]
	v_mfma_f32_16x16x32_bf16 v[118:121], v[180:183], v[196:199], v[118:121]
	v_mfma_f32_16x16x32_bf16 v[114:117], v[188:191], v[196:199], v[114:117]
	v_mfma_f32_16x16x32_bf16 v[102:105], v[180:183], v[204:207], v[102:105]
	v_mfma_f32_16x16x32_bf16 v[98:101], v[188:191], v[204:207], v[98:101]
	v_mfma_f32_16x16x32_bf16 v[86:89], v[180:183], v[212:215], v[86:89]
	v_mfma_f32_16x16x32_bf16 v[82:85], v[188:191], v[212:215], v[82:85]
	s_setprio 2
	s_barrier
	v_mfma_f32_16x16x32_bf16 v[70:73], v[180:183], v[220:223], v[70:73]
	v_mfma_f32_16x16x32_bf16 v[66:69], v[188:191], v[220:223], v[66:69]
	s_setprio 0
	s_add_i32 s50, s50, s9
	v_lshl_add_u64 v[154:155], s[42:43], 0, v[162:163]
	s_mov_b32 m0, s50
	ds_read_b128 v[192:195], v157 offset:16384
	ds_read_b128 v[196:199], v157 offset:17408
	ds_read_b128 v[200:203], v157 offset:18432
	ds_read_b128 v[204:207], v157 offset:19456
	ds_read_b128 v[208:211], v157 offset:20480
	ds_read_b128 v[212:215], v157 offset:21504
	ds_read_b128 v[216:219], v157 offset:22528
	ds_read_b128 v[220:223], v157 offset:23552
	global_load_lds_dwordx4 v[154:155], off
	s_add_i32 m0, s50, 0x2000
	s_add_u32 s50, s42, 0x80000
	v_lshl_add_u64 v[168:169], s[42:43], 0, v[142:143]
	s_addc_u32 s51, s43, 0
	s_add_i32 s52, s52, s9
	global_load_lds_dwordx4 v[168:169], off
	v_lshl_add_u64 v[224:225], s[50:51], 0, v[162:163]
	s_mov_b32 m0, s52
	v_lshl_add_u64 v[226:227], s[44:45], 0, v[140:141]
	global_load_lds_dwordx4 v[224:225], off
	s_add_i32 m0, s52, 0x2000
	v_lshl_add_u64 v[224:225], s[50:51], 0, v[142:143]
	global_load_lds_dwordx4 v[224:225], off
	s_mov_b32 m0, s20
	v_lshl_add_u64 v[224:225], s[44:45], 0, v[138:139]
	global_load_lds_dwordx4 v[224:225], off
	s_mov_b32 m0, s25
	s_nop 0
	global_load_lds_dwordx4 v[226:227], off
	s_waitcnt vmcnt(8)
	s_waitcnt lgkmcnt(0)
	s_barrier
	s_setprio 1
	s_waitcnt lgkmcnt(0)
	v_mfma_f32_16x16x32_bf16 v[62:65], v[130:133], v[192:195], v[62:65]
	v_mfma_f32_16x16x32_bf16 v[58:61], v[150:153], v[192:195], v[58:61]
	v_mfma_f32_16x16x32_bf16 v[46:49], v[130:133], v[200:203], v[46:49]
	v_mfma_f32_16x16x32_bf16 v[42:45], v[150:153], v[200:203], v[42:45]
	v_mfma_f32_16x16x32_bf16 v[30:33], v[130:133], v[208:211], v[30:33]
	v_mfma_f32_16x16x32_bf16 v[26:29], v[150:153], v[208:211], v[26:29]
	v_mfma_f32_16x16x32_bf16 v[14:17], v[130:133], v[216:219], v[14:17]
	v_mfma_f32_16x16x32_bf16 v[10:13], v[150:153], v[216:219], v[10:13]
	v_mfma_f32_16x16x32_bf16 v[62:65], v[134:137], v[196:199], v[62:65]
	v_mfma_f32_16x16x32_bf16 v[58:61], v[158:161], v[196:199], v[58:61]
	v_mfma_f32_16x16x32_bf16 v[46:49], v[134:137], v[204:207], v[46:49]
	v_mfma_f32_16x16x32_bf16 v[42:45], v[158:161], v[204:207], v[42:45]
	v_mfma_f32_16x16x32_bf16 v[30:33], v[134:137], v[212:215], v[30:33]
	v_mfma_f32_16x16x32_bf16 v[26:29], v[158:161], v[212:215], v[26:29]
	v_mfma_f32_16x16x32_bf16 v[14:17], v[134:137], v[220:223], v[14:17]
	v_mfma_f32_16x16x32_bf16 v[10:13], v[158:161], v[220:223], v[10:13]
	s_setprio 0
	s_setprio 1
	v_mfma_f32_16x16x32_bf16 v[54:57], v[164:167], v[192:195], v[54:57]
	v_mfma_f32_16x16x32_bf16 v[50:53], v[184:187], v[192:195], v[50:53]
	v_mfma_f32_16x16x32_bf16 v[38:41], v[164:167], v[200:203], v[38:41]
	v_mfma_f32_16x16x32_bf16 v[34:37], v[184:187], v[200:203], v[34:37]
	v_mfma_f32_16x16x32_bf16 v[22:25], v[164:167], v[208:211], v[22:25]
	v_mfma_f32_16x16x32_bf16 v[18:21], v[184:187], v[208:211], v[18:21]
	v_mfma_f32_16x16x32_bf16 v[6:9], v[164:167], v[216:219], v[6:9]
	v_mfma_f32_16x16x32_bf16 v[2:5], v[184:187], v[216:219], v[2:5]
	v_mfma_f32_16x16x32_bf16 v[54:57], v[180:183], v[196:199], v[54:57]
	v_mfma_f32_16x16x32_bf16 v[50:53], v[188:191], v[196:199], v[50:53]
	v_mfma_f32_16x16x32_bf16 v[38:41], v[180:183], v[204:207], v[38:41]
	v_mfma_f32_16x16x32_bf16 v[34:37], v[188:191], v[204:207], v[34:37]
	v_mfma_f32_16x16x32_bf16 v[22:25], v[180:183], v[212:215], v[22:25]
	v_mfma_f32_16x16x32_bf16 v[18:21], v[188:191], v[212:215], v[18:21]
	s_setprio 2
	s_barrier
	v_mfma_f32_16x16x32_bf16 v[6:9], v[180:183], v[220:223], v[6:9]
	v_mfma_f32_16x16x32_bf16 v[2:5], v[188:191], v[220:223], v[2:5]
	s_setprio 0
	s_add_i32 s50, 0, 0x18000
	s_add_i32 s51, 0, 0x1c000
	v_add_u32_e32 v158, s50, v145
	v_add_u32_e32 v179, s51, v145
	ds_read_b128 v[130:133], v158
	ds_read_b128 v[134:137], v158 offset:1024
	ds_read_b128 v[150:153], v158 offset:2048
	ds_read_b128 v[158:161], v158 offset:3072
	ds_read_b128 v[164:167], v179
	ds_read_b128 v[180:183], v179 offset:1024
	ds_read_b128 v[184:187], v179 offset:2048
	ds_read_b128 v[188:191], v179 offset:3072
	s_add_u32 s44, s44, 0x80000
	s_addc_u32 s45, s45, 0
	s_mov_b32 m0, s26
	v_lshl_add_u64 v[228:229], s[44:45], 0, v[138:139]
	ds_read_b128 v[192:195], v157 offset:32768
	ds_read_b128 v[196:199], v157 offset:33792
	ds_read_b128 v[200:203], v157 offset:34816
	ds_read_b128 v[204:207], v157 offset:35840
	ds_read_b128 v[208:211], v157 offset:36864
	ds_read_b128 v[212:215], v157 offset:37888
	ds_read_b128 v[216:219], v157 offset:38912
	ds_read_b128 v[220:223], v157 offset:39936
	global_load_lds_dwordx4 v[228:229], off
	s_mov_b32 m0, s27
	v_lshl_add_u64 v[228:229], s[44:45], 0, v[140:141]
	global_load_lds_dwordx4 v[228:229], off
	s_waitcnt vmcnt(8)
	s_waitcnt lgkmcnt(0)
	s_barrier
	s_setprio 1
	s_waitcnt lgkmcnt(0)
	v_mfma_f32_16x16x32_bf16 v[126:129], v[130:133], v[192:195], v[126:129]
	v_mfma_f32_16x16x32_bf16 v[122:125], v[150:153], v[192:195], v[122:125]
	v_mfma_f32_16x16x32_bf16 v[110:113], v[130:133], v[200:203], v[110:113]
	v_mfma_f32_16x16x32_bf16 v[106:109], v[150:153], v[200:203], v[106:109]
	v_mfma_f32_16x16x32_bf16 v[94:97], v[130:133], v[208:211], v[94:97]
	v_mfma_f32_16x16x32_bf16 v[90:93], v[150:153], v[208:211], v[90:93]
	v_mfma_f32_16x16x32_bf16 v[78:81], v[130:133], v[216:219], v[78:81]
	v_mfma_f32_16x16x32_bf16 v[74:77], v[150:153], v[216:219], v[74:77]
	v_mfma_f32_16x16x32_bf16 v[126:129], v[134:137], v[196:199], v[126:129]
	v_mfma_f32_16x16x32_bf16 v[122:125], v[158:161], v[196:199], v[122:125]
	v_mfma_f32_16x16x32_bf16 v[110:113], v[134:137], v[204:207], v[110:113]
	v_mfma_f32_16x16x32_bf16 v[106:109], v[158:161], v[204:207], v[106:109]
	v_mfma_f32_16x16x32_bf16 v[94:97], v[134:137], v[212:215], v[94:97]
	v_mfma_f32_16x16x32_bf16 v[90:93], v[158:161], v[212:215], v[90:93]
	v_mfma_f32_16x16x32_bf16 v[78:81], v[134:137], v[220:223], v[78:81]
	v_mfma_f32_16x16x32_bf16 v[74:77], v[158:161], v[220:223], v[74:77]
	s_setprio 0
	s_setprio 1
	v_mfma_f32_16x16x32_bf16 v[118:121], v[164:167], v[192:195], v[118:121]
	v_mfma_f32_16x16x32_bf16 v[114:117], v[184:187], v[192:195], v[114:117]
	v_mfma_f32_16x16x32_bf16 v[102:105], v[164:167], v[200:203], v[102:105]
	v_mfma_f32_16x16x32_bf16 v[98:101], v[184:187], v[200:203], v[98:101]
	v_mfma_f32_16x16x32_bf16 v[86:89], v[164:167], v[208:211], v[86:89]
	v_mfma_f32_16x16x32_bf16 v[82:85], v[184:187], v[208:211], v[82:85]
	v_mfma_f32_16x16x32_bf16 v[70:73], v[164:167], v[216:219], v[70:73]
	v_mfma_f32_16x16x32_bf16 v[66:69], v[184:187], v[216:219], v[66:69]
	v_mfma_f32_16x16x32_bf16 v[118:121], v[180:183], v[196:199], v[118:121]
	v_mfma_f32_16x16x32_bf16 v[114:117], v[188:191], v[196:199], v[114:117]
	v_mfma_f32_16x16x32_bf16 v[102:105], v[180:183], v[204:207], v[102:105]
	v_mfma_f32_16x16x32_bf16 v[98:101], v[188:191], v[204:207], v[98:101]
	v_mfma_f32_16x16x32_bf16 v[86:89], v[180:183], v[212:215], v[86:89]
	v_mfma_f32_16x16x32_bf16 v[82:85], v[188:191], v[212:215], v[82:85]
	s_setprio 2
	s_barrier
	v_mfma_f32_16x16x32_bf16 v[70:73], v[180:183], v[220:223], v[70:73]
	v_mfma_f32_16x16x32_bf16 v[66:69], v[188:191], v[220:223], v[66:69]
	s_setprio 0
	s_add_i32 s44, s50, s9
	v_lshl_add_u64 v[154:155], v[154:155], 0, s[6:7]
	s_mov_b32 m0, s44
	ds_read_b128 v[192:195], v157 offset:49152
	ds_read_b128 v[196:199], v157 offset:50176
	ds_read_b128 v[200:203], v157 offset:51200
	ds_read_b128 v[204:207], v157 offset:52224
	ds_read_b128 v[208:211], v157 offset:53248
	ds_read_b128 v[212:215], v157 offset:54272
	ds_read_b128 v[216:219], v157 offset:55296
	ds_read_b128 v[220:223], v157 offset:56320
	global_load_lds_dwordx4 v[154:155], off
	s_add_i32 m0, s44, 0x2000
	s_add_u32 s42, s42, 0x80080
	v_lshl_add_u64 v[154:155], v[168:169], 0, s[6:7]
	s_addc_u32 s43, s43, 0
	s_add_i32 s44, s51, s9
	global_load_lds_dwordx4 v[154:155], off
	s_mov_b32 m0, s44
	v_lshl_add_u64 v[154:155], s[42:43], 0, v[162:163]
	global_load_lds_dwordx4 v[154:155], off
	s_add_i32 m0, s44, 0x2000
	v_lshl_add_u64 v[154:155], s[42:43], 0, v[142:143]
	global_load_lds_dwordx4 v[154:155], off
	s_mov_b32 m0, s39
	v_lshl_add_u64 v[154:155], v[224:225], 0, s[6:7]
	global_load_lds_dwordx4 v[154:155], off
	s_mov_b32 m0, s46
	v_lshl_add_u64 v[154:155], v[226:227], 0, s[6:7]
	global_load_lds_dwordx4 v[154:155], off
	s_waitcnt vmcnt(8)
	s_waitcnt lgkmcnt(0)
	s_barrier
	s_setprio 1
	s_waitcnt lgkmcnt(0)
	v_mfma_f32_16x16x32_bf16 v[62:65], v[130:133], v[192:195], v[62:65]
	v_mfma_f32_16x16x32_bf16 v[58:61], v[150:153], v[192:195], v[58:61]
	v_mfma_f32_16x16x32_bf16 v[46:49], v[130:133], v[200:203], v[46:49]
	v_mfma_f32_16x16x32_bf16 v[42:45], v[150:153], v[200:203], v[42:45]
	v_mfma_f32_16x16x32_bf16 v[30:33], v[130:133], v[208:211], v[30:33]
	v_mfma_f32_16x16x32_bf16 v[26:29], v[150:153], v[208:211], v[26:29]
	v_mfma_f32_16x16x32_bf16 v[14:17], v[130:133], v[216:219], v[14:17]
	v_mfma_f32_16x16x32_bf16 v[10:13], v[150:153], v[216:219], v[10:13]
	v_mfma_f32_16x16x32_bf16 v[62:65], v[134:137], v[196:199], v[62:65]
	v_mfma_f32_16x16x32_bf16 v[58:61], v[158:161], v[196:199], v[58:61]
	v_mfma_f32_16x16x32_bf16 v[46:49], v[134:137], v[204:207], v[46:49]
	v_mfma_f32_16x16x32_bf16 v[42:45], v[158:161], v[204:207], v[42:45]
	v_mfma_f32_16x16x32_bf16 v[30:33], v[134:137], v[212:215], v[30:33]
	v_mfma_f32_16x16x32_bf16 v[26:29], v[158:161], v[212:215], v[26:29]
	v_mfma_f32_16x16x32_bf16 v[14:17], v[134:137], v[220:223], v[14:17]
	v_mfma_f32_16x16x32_bf16 v[10:13], v[158:161], v[220:223], v[10:13]
	s_setprio 0
	s_setprio 1
	v_mfma_f32_16x16x32_bf16 v[54:57], v[164:167], v[192:195], v[54:57]
	v_mfma_f32_16x16x32_bf16 v[50:53], v[184:187], v[192:195], v[50:53]
	v_mfma_f32_16x16x32_bf16 v[38:41], v[164:167], v[200:203], v[38:41]
	v_mfma_f32_16x16x32_bf16 v[34:37], v[184:187], v[200:203], v[34:37]
	v_mfma_f32_16x16x32_bf16 v[22:25], v[164:167], v[208:211], v[22:25]
	v_mfma_f32_16x16x32_bf16 v[18:21], v[184:187], v[208:211], v[18:21]
	v_mfma_f32_16x16x32_bf16 v[6:9], v[164:167], v[216:219], v[6:9]
	v_mfma_f32_16x16x32_bf16 v[2:5], v[184:187], v[216:219], v[2:5]
	v_mfma_f32_16x16x32_bf16 v[54:57], v[180:183], v[196:199], v[54:57]
	v_mfma_f32_16x16x32_bf16 v[50:53], v[188:191], v[196:199], v[50:53]
	v_mfma_f32_16x16x32_bf16 v[38:41], v[180:183], v[204:207], v[38:41]
	v_mfma_f32_16x16x32_bf16 v[34:37], v[188:191], v[204:207], v[34:37]
	v_mfma_f32_16x16x32_bf16 v[22:25], v[180:183], v[212:215], v[22:25]
	v_mfma_f32_16x16x32_bf16 v[18:21], v[188:191], v[212:215], v[18:21]
	s_setprio 2
	s_barrier
	v_mfma_f32_16x16x32_bf16 v[6:9], v[180:183], v[220:223], v[6:9]
	v_mfma_f32_16x16x32_bf16 v[2:5], v[188:191], v[220:223], v[2:5]
	s_setprio 0
	s_add_i32 s49, s49, 2
	s_add_u32 s36, s36, 0x100
	s_addc_u32 s37, s37, 0
	s_add_u32 s41, s41, 0x100
	s_addc_u32 s48, s48, 0
	s_cmp_gt_u32 s49, 29
	s_cbranch_scc0 .LBB0_1115
	s_and_b64 vcc, exec, s[2:3]
	s_cbranch_vccz .LBB0_1118
	s_barrier

.LBB0_1293:
	s_ashr_i32 s19, s18, 31
	s_lshl_b64 s[8:9], s[18:19], 20
	v_readlane_b32 s5, v243, 17
	s_add_u32 s28, s5, s8
	v_readlane_b32 s5, v243, 18
	s_addc_u32 s29, s5, s9
	s_and_b64 s[8:9], s[34:35], exec
	s_cselect_b32 s8, s29, s37
	s_cselect_b32 s9, s28, s36
	s_ashr_i32 s5, s4, 31
	s_lshl_b64 s[20:21], s[4:5], 20
	s_add_u32 s38, s25, s20
	s_addc_u32 s39, s27, s21
	s_and_b64 s[20:21], s[34:35], exec
	s_cselect_b32 s5, s39, s43
	s_cselect_b32 s11, s38, s42
	s_add_u32 s36, s36, 0x80080
	s_addc_u32 s37, s37, 0
	s_add_u32 s13, s42, 0x100
	s_addc_u32 s19, s43, 0
	s_mov_b32 s20, -2
	s_waitcnt vmcnt(0) lgkmcnt(0)
	s_add_u32 s21, s36, 0xfff80080
	s_addc_u32 s23, s37, -1
	s_add_i32 s26, 0, 0x10000
	s_cmp_eq_u32 s20, 28
	s_cselect_b32 s45, s8, s23
	s_cselect_b32 s44, s9, s21
	v_add_u32_e32 v153, s26, v147
	s_cselect_b32 s43, s5, s19
	s_cselect_b32 s42, s11, s13
	s_add_i32 s21, 0, 0x14000
	ds_read_b128 v[130:133], v153
	ds_read_b128 v[134:137], v153 offset:1024
	ds_read_b128 v[164:167], v153 offset:2048
	ds_read_b128 v[182:185], v153 offset:3072
	v_add_u32_e32 v153, s21, v147
	ds_read_b128 v[186:189], v153
	ds_read_b128 v[190:193], v153 offset:1024
	ds_read_b128 v[194:197], v153 offset:2048
	ds_read_b128 v[198:201], v153 offset:3072
	v_lshl_add_u64 v[168:169], s[36:37], 0, v[148:149]
	s_add_i32 m0, s47, 0xc000
	ds_read_b128 v[202:205], v180
	ds_read_b128 v[206:209], v180 offset:1024
	ds_read_b128 v[210:213], v180 offset:2048
	ds_read_b128 v[214:217], v180 offset:3072
	ds_read_b128 v[218:221], v180 offset:4096
	ds_read_b128 v[222:225], v180 offset:5120
	ds_read_b128 v[226:229], v180 offset:6144
	ds_read_b128 v[230:233], v180 offset:7168
	global_load_lds_dwordx4 v[168:169], off
	s_add_i32 m0, s47, 0xe000
	v_lshl_add_u64 v[168:169], s[36:37], 0, v[150:151]
	global_load_lds_dwordx4 v[168:169], off
	s_waitcnt vmcnt(8)
	s_waitcnt lgkmcnt(0)
	s_barrier
	s_setprio 1
	s_waitcnt lgkmcnt(0)
	v_mfma_f32_16x16x32_bf16 v[126:129], v[130:133], v[202:205], 0
	v_mfma_f32_16x16x32_bf16 v[122:125], v[164:167], v[202:205], 0
	v_mfma_f32_16x16x32_bf16 v[110:113], v[130:133], v[210:213], 0
	v_mfma_f32_16x16x32_bf16 v[106:109], v[164:167], v[210:213], 0
	v_mfma_f32_16x16x32_bf16 v[94:97], v[130:133], v[218:221], 0
	v_mfma_f32_16x16x32_bf16 v[90:93], v[164:167], v[218:221], 0
	v_mfma_f32_16x16x32_bf16 v[78:81], v[130:133], v[226:229], 0
	v_mfma_f32_16x16x32_bf16 v[74:77], v[164:167], v[226:229], 0
	v_mfma_f32_16x16x32_bf16 v[126:129], v[134:137], v[206:209], v[126:129]
	v_mfma_f32_16x16x32_bf16 v[122:125], v[182:185], v[206:209], v[122:125]
	v_mfma_f32_16x16x32_bf16 v[110:113], v[134:137], v[214:217], v[110:113]
	v_mfma_f32_16x16x32_bf16 v[106:109], v[182:185], v[214:217], v[106:109]
	v_mfma_f32_16x16x32_bf16 v[94:97], v[134:137], v[222:225], v[94:97]
	v_mfma_f32_16x16x32_bf16 v[90:93], v[182:185], v[222:225], v[90:93]
	v_mfma_f32_16x16x32_bf16 v[78:81], v[134:137], v[230:233], v[78:81]
	v_mfma_f32_16x16x32_bf16 v[74:77], v[182:185], v[230:233], v[74:77]
	s_setprio 0
	s_setprio 1
	v_mfma_f32_16x16x32_bf16 v[118:121], v[186:189], v[202:205], 0
	v_mfma_f32_16x16x32_bf16 v[114:117], v[194:197], v[202:205], 0
	v_mfma_f32_16x16x32_bf16 v[102:105], v[186:189], v[210:213], 0
	v_mfma_f32_16x16x32_bf16 v[98:101], v[194:197], v[210:213], 0
	v_mfma_f32_16x16x32_bf16 v[86:89], v[186:189], v[218:221], 0
	v_mfma_f32_16x16x32_bf16 v[82:85], v[194:197], v[218:221], 0
	v_mfma_f32_16x16x32_bf16 v[70:73], v[186:189], v[226:229], 0
	v_mfma_f32_16x16x32_bf16 v[66:69], v[194:197], v[226:229], 0
	v_mfma_f32_16x16x32_bf16 v[118:121], v[190:193], v[206:209], v[118:121]
	v_mfma_f32_16x16x32_bf16 v[114:117], v[198:201], v[206:209], v[114:117]
	v_mfma_f32_16x16x32_bf16 v[102:105], v[190:193], v[214:217], v[102:105]
	v_mfma_f32_16x16x32_bf16 v[98:101], v[198:201], v[214:217], v[98:101]
	v_mfma_f32_16x16x32_bf16 v[86:89], v[190:193], v[222:225], v[86:89]
	v_mfma_f32_16x16x32_bf16 v[82:85], v[198:201], v[222:225], v[82:85]
	s_setprio 2
	s_barrier
	v_mfma_f32_16x16x32_bf16 v[70:73], v[190:193], v[230:233], v[70:73]
	v_mfma_f32_16x16x32_bf16 v[66:69], v[198:201], v[230:233], v[66:69]
	s_setprio 0
	s_add_i32 s23, s26, s46
	v_lshl_add_u64 v[168:169], s[42:43], 0, v[162:163]
	s_mov_b32 m0, s23
	ds_read_b128 v[202:205], v180 offset:16384
	ds_read_b128 v[206:209], v180 offset:17408
	ds_read_b128 v[210:213], v180 offset:18432
	ds_read_b128 v[214:217], v180 offset:19456
	ds_read_b128 v[218:221], v180 offset:20480
	ds_read_b128 v[222:225], v180 offset:21504
	ds_read_b128 v[226:229], v180 offset:22528
	ds_read_b128 v[230:233], v180 offset:23552
	global_load_lds_dwordx4 v[168:169], off
	s_add_i32 m0, s23, 0x2000
	s_add_u32 s54, s42, 0x80000
	v_lshl_add_u64 v[234:235], s[42:43], 0, v[142:143]
	s_addc_u32 s55, s43, 0
	s_add_i32 s21, s21, s46
	global_load_lds_dwordx4 v[234:235], off
	v_lshl_add_u64 v[236:237], s[54:55], 0, v[162:163]
	s_mov_b32 m0, s21
	v_lshl_add_u64 v[238:239], s[44:45], 0, v[140:141]
	global_load_lds_dwordx4 v[236:237], off
	s_add_i32 m0, s21, 0x2000
	v_lshl_add_u64 v[236:237], s[54:55], 0, v[142:143]
	global_load_lds_dwordx4 v[236:237], off
	s_mov_b32 m0, s47
	v_lshl_add_u64 v[236:237], s[44:45], 0, v[138:139]
	global_load_lds_dwordx4 v[236:237], off
	s_mov_b32 m0, s48
	s_nop 0
	global_load_lds_dwordx4 v[238:239], off
	s_waitcnt vmcnt(8)
	s_waitcnt lgkmcnt(0)
	s_barrier
	s_setprio 1
	s_waitcnt lgkmcnt(0)
	v_mfma_f32_16x16x32_bf16 v[62:65], v[130:133], v[202:205], 0
	v_mfma_f32_16x16x32_bf16 v[58:61], v[164:167], v[202:205], 0
	v_mfma_f32_16x16x32_bf16 v[46:49], v[130:133], v[210:213], 0
	v_mfma_f32_16x16x32_bf16 v[42:45], v[164:167], v[210:213], 0
	v_mfma_f32_16x16x32_bf16 v[30:33], v[130:133], v[218:221], 0
	v_mfma_f32_16x16x32_bf16 v[26:29], v[164:167], v[218:221], 0
	v_mfma_f32_16x16x32_bf16 v[14:17], v[130:133], v[226:229], 0
	v_mfma_f32_16x16x32_bf16 v[10:13], v[164:167], v[226:229], 0
	v_mfma_f32_16x16x32_bf16 v[62:65], v[134:137], v[206:209], v[62:65]
	v_mfma_f32_16x16x32_bf16 v[58:61], v[182:185], v[206:209], v[58:61]
	v_mfma_f32_16x16x32_bf16 v[46:49], v[134:137], v[214:217], v[46:49]
	v_mfma_f32_16x16x32_bf16 v[42:45], v[182:185], v[214:217], v[42:45]
	v_mfma_f32_16x16x32_bf16 v[30:33], v[134:137], v[222:225], v[30:33]
	v_mfma_f32_16x16x32_bf16 v[26:29], v[182:185], v[222:225], v[26:29]
	v_mfma_f32_16x16x32_bf16 v[14:17], v[134:137], v[230:233], v[14:17]
	v_mfma_f32_16x16x32_bf16 v[10:13], v[182:185], v[230:233], v[10:13]
	s_setprio 0
	s_setprio 1
	v_mfma_f32_16x16x32_bf16 v[54:57], v[186:189], v[202:205], 0
	v_mfma_f32_16x16x32_bf16 v[50:53], v[194:197], v[202:205], 0
	v_mfma_f32_16x16x32_bf16 v[38:41], v[186:189], v[210:213], 0
	v_mfma_f32_16x16x32_bf16 v[34:37], v[194:197], v[210:213], 0
	v_mfma_f32_16x16x32_bf16 v[22:25], v[186:189], v[218:221], 0
	v_mfma_f32_16x16x32_bf16 v[18:21], v[194:197], v[218:221], 0
	v_mfma_f32_16x16x32_bf16 v[6:9], v[186:189], v[226:229], 0
	v_mfma_f32_16x16x32_bf16 v[2:5], v[194:197], v[226:229], 0
	v_mfma_f32_16x16x32_bf16 v[54:57], v[190:193], v[206:209], v[54:57]
	v_mfma_f32_16x16x32_bf16 v[50:53], v[198:201], v[206:209], v[50:53]
	v_mfma_f32_16x16x32_bf16 v[38:41], v[190:193], v[214:217], v[38:41]
	v_mfma_f32_16x16x32_bf16 v[34:37], v[198:201], v[214:217], v[34:37]
	v_mfma_f32_16x16x32_bf16 v[22:25], v[190:193], v[222:225], v[22:25]
	v_mfma_f32_16x16x32_bf16 v[18:21], v[198:201], v[222:225], v[18:21]
	s_setprio 2
	s_barrier
	v_mfma_f32_16x16x32_bf16 v[6:9], v[190:193], v[230:233], v[6:9]
	v_mfma_f32_16x16x32_bf16 v[2:5], v[198:201], v[230:233], v[2:5]
	s_setprio 0
	s_add_i32 s21, 0, 0x18000
	v_add_u32_e32 v153, s21, v147
	s_add_i32 s23, 0, 0x1c000
	ds_read_b128 v[130:133], v153
	ds_read_b128 v[134:137], v153 offset:1024
	ds_read_b128 v[164:167], v153 offset:2048
	ds_read_b128 v[182:185], v153 offset:3072
	v_add_u32_e32 v153, s23, v147
	ds_read_b128 v[186:189], v153
	ds_read_b128 v[190:193], v153 offset:1024
	ds_read_b128 v[194:197], v153 offset:2048
	ds_read_b128 v[198:201], v153 offset:3072
	s_add_u32 s44, s44, 0x80000
	s_addc_u32 s45, s45, 0
	s_mov_b32 m0, s49
	v_lshl_add_u64 v[240:241], s[44:45], 0, v[138:139]
	ds_read_b128 v[202:205], v180 offset:32768
	ds_read_b128 v[206:209], v180 offset:33792
	ds_read_b128 v[210:213], v180 offset:34816
	ds_read_b128 v[214:217], v180 offset:35840
	ds_read_b128 v[218:221], v180 offset:36864
	ds_read_b128 v[222:225], v180 offset:37888
	ds_read_b128 v[226:229], v180 offset:38912
	ds_read_b128 v[230:233], v180 offset:39936
	global_load_lds_dwordx4 v[240:241], off
	s_mov_b32 m0, s50
	v_lshl_add_u64 v[240:241], s[44:45], 0, v[140:141]
	global_load_lds_dwordx4 v[240:241], off
	s_waitcnt vmcnt(8)
	s_waitcnt lgkmcnt(0)
	s_barrier
	s_setprio 1
	s_waitcnt lgkmcnt(0)
	v_mfma_f32_16x16x32_bf16 v[126:129], v[130:133], v[202:205], v[126:129]
	v_mfma_f32_16x16x32_bf16 v[122:125], v[164:167], v[202:205], v[122:125]
	v_mfma_f32_16x16x32_bf16 v[110:113], v[130:133], v[210:213], v[110:113]
	v_mfma_f32_16x16x32_bf16 v[106:109], v[164:167], v[210:213], v[106:109]
	v_mfma_f32_16x16x32_bf16 v[94:97], v[130:133], v[218:221], v[94:97]
	v_mfma_f32_16x16x32_bf16 v[90:93], v[164:167], v[218:221], v[90:93]
	v_mfma_f32_16x16x32_bf16 v[78:81], v[130:133], v[226:229], v[78:81]
	v_mfma_f32_16x16x32_bf16 v[74:77], v[164:167], v[226:229], v[74:77]
	v_mfma_f32_16x16x32_bf16 v[126:129], v[134:137], v[206:209], v[126:129]
	v_mfma_f32_16x16x32_bf16 v[122:125], v[182:185], v[206:209], v[122:125]
	v_mfma_f32_16x16x32_bf16 v[110:113], v[134:137], v[214:217], v[110:113]
	v_mfma_f32_16x16x32_bf16 v[106:109], v[182:185], v[214:217], v[106:109]
	v_mfma_f32_16x16x32_bf16 v[94:97], v[134:137], v[222:225], v[94:97]
	v_mfma_f32_16x16x32_bf16 v[90:93], v[182:185], v[222:225], v[90:93]
	v_mfma_f32_16x16x32_bf16 v[78:81], v[134:137], v[230:233], v[78:81]
	v_mfma_f32_16x16x32_bf16 v[74:77], v[182:185], v[230:233], v[74:77]
	s_setprio 0
	s_setprio 1
	v_mfma_f32_16x16x32_bf16 v[118:121], v[186:189], v[202:205], v[118:121]
	v_mfma_f32_16x16x32_bf16 v[114:117], v[194:197], v[202:205], v[114:117]
	v_mfma_f32_16x16x32_bf16 v[102:105], v[186:189], v[210:213], v[102:105]
	v_mfma_f32_16x16x32_bf16 v[98:101], v[194:197], v[210:213], v[98:101]
	v_mfma_f32_16x16x32_bf16 v[86:89], v[186:189], v[218:221], v[86:89]
	v_mfma_f32_16x16x32_bf16 v[82:85], v[194:197], v[218:221], v[82:85]
	v_mfma_f32_16x16x32_bf16 v[70:73], v[186:189], v[226:229], v[70:73]
	v_mfma_f32_16x16x32_bf16 v[66:69], v[194:197], v[226:229], v[66:69]
	v_mfma_f32_16x16x32_bf16 v[118:121], v[190:193], v[206:209], v[118:121]
	v_mfma_f32_16x16x32_bf16 v[114:117], v[198:201], v[206:209], v[114:117]
	v_mfma_f32_16x16x32_bf16 v[102:105], v[190:193], v[214:217], v[102:105]
	v_mfma_f32_16x16x32_bf16 v[98:101], v[198:201], v[214:217], v[98:101]
	v_mfma_f32_16x16x32_bf16 v[86:89], v[190:193], v[222:225], v[86:89]
	v_mfma_f32_16x16x32_bf16 v[82:85], v[198:201], v[222:225], v[82:85]
	s_setprio 2
	s_barrier
	v_mfma_f32_16x16x32_bf16 v[70:73], v[190:193], v[230:233], v[70:73]
	v_mfma_f32_16x16x32_bf16 v[66:69], v[198:201], v[230:233], v[66:69]
	s_setprio 0
	s_add_i32 s21, s21, s46
	v_lshl_add_u64 v[168:169], v[168:169], 0, s[6:7]
	s_mov_b32 m0, s21
	ds_read_b128 v[202:205], v180 offset:49152
	ds_read_b128 v[206:209], v180 offset:50176
	ds_read_b128 v[210:213], v180 offset:51200
	ds_read_b128 v[214:217], v180 offset:52224
	ds_read_b128 v[218:221], v180 offset:53248
	ds_read_b128 v[222:225], v180 offset:54272
	ds_read_b128 v[226:229], v180 offset:55296
	ds_read_b128 v[230:233], v180 offset:56320
	global_load_lds_dwordx4 v[168:169], off
	s_add_i32 m0, s21, 0x2000
	s_add_u32 s42, s42, 0x80080
	v_lshl_add_u64 v[168:169], v[234:235], 0, s[6:7]
	s_addc_u32 s43, s43, 0
	s_add_i32 s21, s23, s46
	global_load_lds_dwordx4 v[168:169], off
	s_mov_b32 m0, s21
	v_lshl_add_u64 v[168:169], s[42:43], 0, v[162:163]
	global_load_lds_dwordx4 v[168:169], off
	s_add_i32 m0, s21, 0x2000
	v_lshl_add_u64 v[168:169], s[42:43], 0, v[142:143]
	global_load_lds_dwordx4 v[168:169], off
	s_mov_b32 m0, s51
	v_lshl_add_u64 v[168:169], v[236:237], 0, s[6:7]
	global_load_lds_dwordx4 v[168:169], off
	s_mov_b32 m0, s52
	v_lshl_add_u64 v[168:169], v[238:239], 0, s[6:7]
	global_load_lds_dwordx4 v[168:169], off
	s_waitcnt vmcnt(8)
	s_waitcnt lgkmcnt(0)
	s_barrier
	s_setprio 1
	s_waitcnt lgkmcnt(0)
	v_mfma_f32_16x16x32_bf16 v[62:65], v[130:133], v[202:205], v[62:65]
	v_mfma_f32_16x16x32_bf16 v[58:61], v[164:167], v[202:205], v[58:61]
	v_mfma_f32_16x16x32_bf16 v[46:49], v[130:133], v[210:213], v[46:49]
	v_mfma_f32_16x16x32_bf16 v[42:45], v[164:167], v[210:213], v[42:45]
	v_mfma_f32_16x16x32_bf16 v[30:33], v[130:133], v[218:221], v[30:33]
	v_mfma_f32_16x16x32_bf16 v[26:29], v[164:167], v[218:221], v[26:29]
	v_mfma_f32_16x16x32_bf16 v[14:17], v[130:133], v[226:229], v[14:17]
	v_mfma_f32_16x16x32_bf16 v[10:13], v[164:167], v[226:229], v[10:13]
	v_mfma_f32_16x16x32_bf16 v[62:65], v[134:137], v[206:209], v[62:65]
	v_mfma_f32_16x16x32_bf16 v[58:61], v[182:185], v[206:209], v[58:61]
	v_mfma_f32_16x16x32_bf16 v[46:49], v[134:137], v[214:217], v[46:49]
	v_mfma_f32_16x16x32_bf16 v[42:45], v[182:185], v[214:217], v[42:45]
	v_mfma_f32_16x16x32_bf16 v[30:33], v[134:137], v[222:225], v[30:33]
	v_mfma_f32_16x16x32_bf16 v[26:29], v[182:185], v[222:225], v[26:29]
	v_mfma_f32_16x16x32_bf16 v[14:17], v[134:137], v[230:233], v[14:17]
	v_mfma_f32_16x16x32_bf16 v[10:13], v[182:185], v[230:233], v[10:13]
	s_setprio 0
	s_setprio 1
	v_mfma_f32_16x16x32_bf16 v[54:57], v[186:189], v[202:205], v[54:57]
	v_mfma_f32_16x16x32_bf16 v[50:53], v[194:197], v[202:205], v[50:53]
	v_mfma_f32_16x16x32_bf16 v[38:41], v[186:189], v[210:213], v[38:41]
	v_mfma_f32_16x16x32_bf16 v[34:37], v[194:197], v[210:213], v[34:37]
	v_mfma_f32_16x16x32_bf16 v[22:25], v[186:189], v[218:221], v[22:25]
	v_mfma_f32_16x16x32_bf16 v[18:21], v[194:197], v[218:221], v[18:21]
	v_mfma_f32_16x16x32_bf16 v[6:9], v[186:189], v[226:229], v[6:9]
	v_mfma_f32_16x16x32_bf16 v[2:5], v[194:197], v[226:229], v[2:5]
	v_mfma_f32_16x16x32_bf16 v[54:57], v[190:193], v[206:209], v[54:57]
	v_mfma_f32_16x16x32_bf16 v[50:53], v[198:201], v[206:209], v[50:53]
	v_mfma_f32_16x16x32_bf16 v[38:41], v[190:193], v[214:217], v[38:41]
	v_mfma_f32_16x16x32_bf16 v[34:37], v[198:201], v[214:217], v[34:37]
	v_mfma_f32_16x16x32_bf16 v[22:25], v[190:193], v[222:225], v[22:25]
	v_mfma_f32_16x16x32_bf16 v[18:21], v[198:201], v[222:225], v[18:21]
	s_setprio 2
	s_barrier
	v_mfma_f32_16x16x32_bf16 v[6:9], v[190:193], v[230:233], v[6:9]
	v_mfma_f32_16x16x32_bf16 v[2:5], v[198:201], v[230:233], v[2:5]
	s_setprio 0
	s_add_i32 s20, s20, 2
	s_add_u32 s36, s36, 0x100
	s_addc_u32 s37, s37, 0
	s_add_u32 s13, s13, 0x100
	s_addc_u32 s19, s19, 0
	s_cmp_gt_u32 s20, 29
.LBB0_1294:
	s_add_u32 s21, s36, 0xfff80080
	s_addc_u32 s23, s37, -1
	s_add_i32 s26, 0, 0x10000
	s_cmp_eq_u32 s20, 28
	s_cselect_b32 s45, s8, s23
	s_cselect_b32 s44, s9, s21
	v_add_u32_e32 v153, s26, v147
	s_cselect_b32 s43, s5, s19
	s_cselect_b32 s42, s11, s13
	s_add_i32 s21, 0, 0x14000
	ds_read_b128 v[130:133], v153
	ds_read_b128 v[134:137], v153 offset:1024
	ds_read_b128 v[164:167], v153 offset:2048
	ds_read_b128 v[182:185], v153 offset:3072
	v_add_u32_e32 v153, s21, v147
	ds_read_b128 v[186:189], v153
	ds_read_b128 v[190:193], v153 offset:1024
	ds_read_b128 v[194:197], v153 offset:2048
	ds_read_b128 v[198:201], v153 offset:3072
	v_lshl_add_u64 v[168:169], s[36:37], 0, v[148:149]
	s_add_i32 m0, s47, 0xc000
	ds_read_b128 v[202:205], v180
	ds_read_b128 v[206:209], v180 offset:1024
	ds_read_b128 v[210:213], v180 offset:2048
	ds_read_b128 v[214:217], v180 offset:3072
	ds_read_b128 v[218:221], v180 offset:4096
	ds_read_b128 v[222:225], v180 offset:5120
	ds_read_b128 v[226:229], v180 offset:6144
	ds_read_b128 v[230:233], v180 offset:7168
	global_load_lds_dwordx4 v[168:169], off
	s_add_i32 m0, s47, 0xe000
	v_lshl_add_u64 v[168:169], s[36:37], 0, v[150:151]
	global_load_lds_dwordx4 v[168:169], off
	s_waitcnt vmcnt(8)
	s_waitcnt lgkmcnt(0)
	s_barrier
	s_setprio 1
	s_waitcnt lgkmcnt(0)
	v_mfma_f32_16x16x32_bf16 v[126:129], v[130:133], v[202:205], v[126:129]
	v_mfma_f32_16x16x32_bf16 v[122:125], v[164:167], v[202:205], v[122:125]
	v_mfma_f32_16x16x32_bf16 v[110:113], v[130:133], v[210:213], v[110:113]
	v_mfma_f32_16x16x32_bf16 v[106:109], v[164:167], v[210:213], v[106:109]
	v_mfma_f32_16x16x32_bf16 v[94:97], v[130:133], v[218:221], v[94:97]
	v_mfma_f32_16x16x32_bf16 v[90:93], v[164:167], v[218:221], v[90:93]
	v_mfma_f32_16x16x32_bf16 v[78:81], v[130:133], v[226:229], v[78:81]
	v_mfma_f32_16x16x32_bf16 v[74:77], v[164:167], v[226:229], v[74:77]
	v_mfma_f32_16x16x32_bf16 v[126:129], v[134:137], v[206:209], v[126:129]
	v_mfma_f32_16x16x32_bf16 v[122:125], v[182:185], v[206:209], v[122:125]
	v_mfma_f32_16x16x32_bf16 v[110:113], v[134:137], v[214:217], v[110:113]
	v_mfma_f32_16x16x32_bf16 v[106:109], v[182:185], v[214:217], v[106:109]
	v_mfma_f32_16x16x32_bf16 v[94:97], v[134:137], v[222:225], v[94:97]
	v_mfma_f32_16x16x32_bf16 v[90:93], v[182:185], v[222:225], v[90:93]
	v_mfma_f32_16x16x32_bf16 v[78:81], v[134:137], v[230:233], v[78:81]
	v_mfma_f32_16x16x32_bf16 v[74:77], v[182:185], v[230:233], v[74:77]
	s_setprio 0
	s_setprio 1
	v_mfma_f32_16x16x32_bf16 v[118:121], v[186:189], v[202:205], v[118:121]
	v_mfma_f32_16x16x32_bf16 v[114:117], v[194:197], v[202:205], v[114:117]
	v_mfma_f32_16x16x32_bf16 v[102:105], v[186:189], v[210:213], v[102:105]
	v_mfma_f32_16x16x32_bf16 v[98:101], v[194:197], v[210:213], v[98:101]
	v_mfma_f32_16x16x32_bf16 v[86:89], v[186:189], v[218:221], v[86:89]
	v_mfma_f32_16x16x32_bf16 v[82:85], v[194:197], v[218:221], v[82:85]
	v_mfma_f32_16x16x32_bf16 v[70:73], v[186:189], v[226:229], v[70:73]
	v_mfma_f32_16x16x32_bf16 v[66:69], v[194:197], v[226:229], v[66:69]
	v_mfma_f32_16x16x32_bf16 v[118:121], v[190:193], v[206:209], v[118:121]
	v_mfma_f32_16x16x32_bf16 v[114:117], v[198:201], v[206:209], v[114:117]
	v_mfma_f32_16x16x32_bf16 v[102:105], v[190:193], v[214:217], v[102:105]
	v_mfma_f32_16x16x32_bf16 v[98:101], v[198:201], v[214:217], v[98:101]
	v_mfma_f32_16x16x32_bf16 v[86:89], v[190:193], v[222:225], v[86:89]
	v_mfma_f32_16x16x32_bf16 v[82:85], v[198:201], v[222:225], v[82:85]
	s_setprio 2
	s_barrier
	v_mfma_f32_16x16x32_bf16 v[70:73], v[190:193], v[230:233], v[70:73]
	v_mfma_f32_16x16x32_bf16 v[66:69], v[198:201], v[230:233], v[66:69]
	s_setprio 0
	s_add_i32 s23, s26, s46
	v_lshl_add_u64 v[168:169], s[42:43], 0, v[162:163]
	s_mov_b32 m0, s23
	ds_read_b128 v[202:205], v180 offset:16384
	ds_read_b128 v[206:209], v180 offset:17408
	ds_read_b128 v[210:213], v180 offset:18432
	ds_read_b128 v[214:217], v180 offset:19456
	ds_read_b128 v[218:221], v180 offset:20480
	ds_read_b128 v[222:225], v180 offset:21504
	ds_read_b128 v[226:229], v180 offset:22528
	ds_read_b128 v[230:233], v180 offset:23552
	global_load_lds_dwordx4 v[168:169], off
	s_add_i32 m0, s23, 0x2000
	s_add_u32 s54, s42, 0x80000
	v_lshl_add_u64 v[234:235], s[42:43], 0, v[142:143]
	s_addc_u32 s55, s43, 0
	s_add_i32 s21, s21, s46
	global_load_lds_dwordx4 v[234:235], off
	v_lshl_add_u64 v[236:237], s[54:55], 0, v[162:163]
	s_mov_b32 m0, s21
	v_lshl_add_u64 v[238:239], s[44:45], 0, v[140:141]
	global_load_lds_dwordx4 v[236:237], off
	s_add_i32 m0, s21, 0x2000
	v_lshl_add_u64 v[236:237], s[54:55], 0, v[142:143]
	global_load_lds_dwordx4 v[236:237], off
	s_mov_b32 m0, s47
	v_lshl_add_u64 v[236:237], s[44:45], 0, v[138:139]
	global_load_lds_dwordx4 v[236:237], off
	s_mov_b32 m0, s48
	s_nop 0
	global_load_lds_dwordx4 v[238:239], off
	s_waitcnt vmcnt(8)
	s_waitcnt lgkmcnt(0)
	s_barrier
	s_setprio 1
	s_waitcnt lgkmcnt(0)
	v_mfma_f32_16x16x32_bf16 v[62:65], v[130:133], v[202:205], v[62:65]
	v_mfma_f32_16x16x32_bf16 v[58:61], v[164:167], v[202:205], v[58:61]
	v_mfma_f32_16x16x32_bf16 v[46:49], v[130:133], v[210:213], v[46:49]
	v_mfma_f32_16x16x32_bf16 v[42:45], v[164:167], v[210:213], v[42:45]
	v_mfma_f32_16x16x32_bf16 v[30:33], v[130:133], v[218:221], v[30:33]
	v_mfma_f32_16x16x32_bf16 v[26:29], v[164:167], v[218:221], v[26:29]
	v_mfma_f32_16x16x32_bf16 v[14:17], v[130:133], v[226:229], v[14:17]
	v_mfma_f32_16x16x32_bf16 v[10:13], v[164:167], v[226:229], v[10:13]
	v_mfma_f32_16x16x32_bf16 v[62:65], v[134:137], v[206:209], v[62:65]
	v_mfma_f32_16x16x32_bf16 v[58:61], v[182:185], v[206:209], v[58:61]
	v_mfma_f32_16x16x32_bf16 v[46:49], v[134:137], v[214:217], v[46:49]
	v_mfma_f32_16x16x32_bf16 v[42:45], v[182:185], v[214:217], v[42:45]
	v_mfma_f32_16x16x32_bf16 v[30:33], v[134:137], v[222:225], v[30:33]
	v_mfma_f32_16x16x32_bf16 v[26:29], v[182:185], v[222:225], v[26:29]
	v_mfma_f32_16x16x32_bf16 v[14:17], v[134:137], v[230:233], v[14:17]
	v_mfma_f32_16x16x32_bf16 v[10:13], v[182:185], v[230:233], v[10:13]
	s_setprio 0
	s_setprio 1
	v_mfma_f32_16x16x32_bf16 v[54:57], v[186:189], v[202:205], v[54:57]
	v_mfma_f32_16x16x32_bf16 v[50:53], v[194:197], v[202:205], v[50:53]
	v_mfma_f32_16x16x32_bf16 v[38:41], v[186:189], v[210:213], v[38:41]
	v_mfma_f32_16x16x32_bf16 v[34:37], v[194:197], v[210:213], v[34:37]
	v_mfma_f32_16x16x32_bf16 v[22:25], v[186:189], v[218:221], v[22:25]
	v_mfma_f32_16x16x32_bf16 v[18:21], v[194:197], v[218:221], v[18:21]
	v_mfma_f32_16x16x32_bf16 v[6:9], v[186:189], v[226:229], v[6:9]
	v_mfma_f32_16x16x32_bf16 v[2:5], v[194:197], v[226:229], v[2:5]
	v_mfma_f32_16x16x32_bf16 v[54:57], v[190:193], v[206:209], v[54:57]
	v_mfma_f32_16x16x32_bf16 v[50:53], v[198:201], v[206:209], v[50:53]
	v_mfma_f32_16x16x32_bf16 v[38:41], v[190:193], v[214:217], v[38:41]
	v_mfma_f32_16x16x32_bf16 v[34:37], v[198:201], v[214:217], v[34:37]
	v_mfma_f32_16x16x32_bf16 v[22:25], v[190:193], v[222:225], v[22:25]
	v_mfma_f32_16x16x32_bf16 v[18:21], v[198:201], v[222:225], v[18:21]
	s_setprio 2
	s_barrier
	v_mfma_f32_16x16x32_bf16 v[6:9], v[190:193], v[230:233], v[6:9]
	v_mfma_f32_16x16x32_bf16 v[2:5], v[198:201], v[230:233], v[2:5]
	s_setprio 0
	s_add_i32 s21, 0, 0x18000
	v_add_u32_e32 v153, s21, v147
	s_add_i32 s23, 0, 0x1c000
	ds_read_b128 v[130:133], v153
	ds_read_b128 v[134:137], v153 offset:1024
	ds_read_b128 v[164:167], v153 offset:2048
	ds_read_b128 v[182:185], v153 offset:3072
	v_add_u32_e32 v153, s23, v147
	ds_read_b128 v[186:189], v153
	ds_read_b128 v[190:193], v153 offset:1024
	ds_read_b128 v[194:197], v153 offset:2048
	ds_read_b128 v[198:201], v153 offset:3072
	s_add_u32 s44, s44, 0x80000
	s_addc_u32 s45, s45, 0
	s_mov_b32 m0, s49
	v_lshl_add_u64 v[240:241], s[44:45], 0, v[138:139]
	ds_read_b128 v[202:205], v180 offset:32768
	ds_read_b128 v[206:209], v180 offset:33792
	ds_read_b128 v[210:213], v180 offset:34816
	ds_read_b128 v[214:217], v180 offset:35840
	ds_read_b128 v[218:221], v180 offset:36864
	ds_read_b128 v[222:225], v180 offset:37888
	ds_read_b128 v[226:229], v180 offset:38912
	ds_read_b128 v[230:233], v180 offset:39936
	global_load_lds_dwordx4 v[240:241], off
	s_mov_b32 m0, s50
	v_lshl_add_u64 v[240:241], s[44:45], 0, v[140:141]
	global_load_lds_dwordx4 v[240:241], off
	s_waitcnt vmcnt(8)
	s_waitcnt lgkmcnt(0)
	s_barrier
	s_setprio 1
	s_waitcnt lgkmcnt(0)
	v_mfma_f32_16x16x32_bf16 v[126:129], v[130:133], v[202:205], v[126:129]
	v_mfma_f32_16x16x32_bf16 v[122:125], v[164:167], v[202:205], v[122:125]
	v_mfma_f32_16x16x32_bf16 v[110:113], v[130:133], v[210:213], v[110:113]
	v_mfma_f32_16x16x32_bf16 v[106:109], v[164:167], v[210:213], v[106:109]
	v_mfma_f32_16x16x32_bf16 v[94:97], v[130:133], v[218:221], v[94:97]
	v_mfma_f32_16x16x32_bf16 v[90:93], v[164:167], v[218:221], v[90:93]
	v_mfma_f32_16x16x32_bf16 v[78:81], v[130:133], v[226:229], v[78:81]
	v_mfma_f32_16x16x32_bf16 v[74:77], v[164:167], v[226:229], v[74:77]
	v_mfma_f32_16x16x32_bf16 v[126:129], v[134:137], v[206:209], v[126:129]
	v_mfma_f32_16x16x32_bf16 v[122:125], v[182:185], v[206:209], v[122:125]
	v_mfma_f32_16x16x32_bf16 v[110:113], v[134:137], v[214:217], v[110:113]
	v_mfma_f32_16x16x32_bf16 v[106:109], v[182:185], v[214:217], v[106:109]
	v_mfma_f32_16x16x32_bf16 v[94:97], v[134:137], v[222:225], v[94:97]
	v_mfma_f32_16x16x32_bf16 v[90:93], v[182:185], v[222:225], v[90:93]
	v_mfma_f32_16x16x32_bf16 v[78:81], v[134:137], v[230:233], v[78:81]
	v_mfma_f32_16x16x32_bf16 v[74:77], v[182:185], v[230:233], v[74:77]
	s_setprio 0
	s_setprio 1
	v_mfma_f32_16x16x32_bf16 v[118:121], v[186:189], v[202:205], v[118:121]
	v_mfma_f32_16x16x32_bf16 v[114:117], v[194:197], v[202:205], v[114:117]
	v_mfma_f32_16x16x32_bf16 v[102:105], v[186:189], v[210:213], v[102:105]
	v_mfma_f32_16x16x32_bf16 v[98:101], v[194:197], v[210:213], v[98:101]
	v_mfma_f32_16x16x32_bf16 v[86:89], v[186:189], v[218:221], v[86:89]
	v_mfma_f32_16x16x32_bf16 v[82:85], v[194:197], v[218:221], v[82:85]
	v_mfma_f32_16x16x32_bf16 v[70:73], v[186:189], v[226:229], v[70:73]
	v_mfma_f32_16x16x32_bf16 v[66:69], v[194:197], v[226:229], v[66:69]
	v_mfma_f32_16x16x32_bf16 v[118:121], v[190:193], v[206:209], v[118:121]
	v_mfma_f32_16x16x32_bf16 v[114:117], v[198:201], v[206:209], v[114:117]
	v_mfma_f32_16x16x32_bf16 v[102:105], v[190:193], v[214:217], v[102:105]
	v_mfma_f32_16x16x32_bf16 v[98:101], v[198:201], v[214:217], v[98:101]
	v_mfma_f32_16x16x32_bf16 v[86:89], v[190:193], v[222:225], v[86:89]
	v_mfma_f32_16x16x32_bf16 v[82:85], v[198:201], v[222:225], v[82:85]
	s_setprio 2
	s_barrier
	v_mfma_f32_16x16x32_bf16 v[70:73], v[190:193], v[230:233], v[70:73]
	v_mfma_f32_16x16x32_bf16 v[66:69], v[198:201], v[230:233], v[66:69]
	s_setprio 0
	s_add_i32 s21, s21, s46
	v_lshl_add_u64 v[168:169], v[168:169], 0, s[6:7]
	s_mov_b32 m0, s21
	ds_read_b128 v[202:205], v180 offset:49152
	ds_read_b128 v[206:209], v180 offset:50176
	ds_read_b128 v[210:213], v180 offset:51200
	ds_read_b128 v[214:217], v180 offset:52224
	ds_read_b128 v[218:221], v180 offset:53248
	ds_read_b128 v[222:225], v180 offset:54272
	ds_read_b128 v[226:229], v180 offset:55296
	ds_read_b128 v[230:233], v180 offset:56320
	global_load_lds_dwordx4 v[168:169], off
	s_add_i32 m0, s21, 0x2000
	s_add_u32 s42, s42, 0x80080
	v_lshl_add_u64 v[168:169], v[234:235], 0, s[6:7]
	s_addc_u32 s43, s43, 0
	s_add_i32 s21, s23, s46
	global_load_lds_dwordx4 v[168:169], off
	s_mov_b32 m0, s21
	v_lshl_add_u64 v[168:169], s[42:43], 0, v[162:163]
	global_load_lds_dwordx4 v[168:169], off
	s_add_i32 m0, s21, 0x2000
	v_lshl_add_u64 v[168:169], s[42:43], 0, v[142:143]
	global_load_lds_dwordx4 v[168:169], off
	s_mov_b32 m0, s51
	v_lshl_add_u64 v[168:169], v[236:237], 0, s[6:7]
	global_load_lds_dwordx4 v[168:169], off
	s_mov_b32 m0, s52
	v_lshl_add_u64 v[168:169], v[238:239], 0, s[6:7]
	global_load_lds_dwordx4 v[168:169], off
	s_waitcnt vmcnt(8)
	s_waitcnt lgkmcnt(0)
	s_barrier
	s_setprio 1
	s_waitcnt lgkmcnt(0)
	v_mfma_f32_16x16x32_bf16 v[62:65], v[130:133], v[202:205], v[62:65]
	v_mfma_f32_16x16x32_bf16 v[58:61], v[164:167], v[202:205], v[58:61]
	v_mfma_f32_16x16x32_bf16 v[46:49], v[130:133], v[210:213], v[46:49]
	v_mfma_f32_16x16x32_bf16 v[42:45], v[164:167], v[210:213], v[42:45]
	v_mfma_f32_16x16x32_bf16 v[30:33], v[130:133], v[218:221], v[30:33]
	v_mfma_f32_16x16x32_bf16 v[26:29], v[164:167], v[218:221], v[26:29]
	v_mfma_f32_16x16x32_bf16 v[14:17], v[130:133], v[226:229], v[14:17]
	v_mfma_f32_16x16x32_bf16 v[10:13], v[164:167], v[226:229], v[10:13]
	v_mfma_f32_16x16x32_bf16 v[62:65], v[134:137], v[206:209], v[62:65]
	v_mfma_f32_16x16x32_bf16 v[58:61], v[182:185], v[206:209], v[58:61]
	v_mfma_f32_16x16x32_bf16 v[46:49], v[134:137], v[214:217], v[46:49]
	v_mfma_f32_16x16x32_bf16 v[42:45], v[182:185], v[214:217], v[42:45]
	v_mfma_f32_16x16x32_bf16 v[30:33], v[134:137], v[222:225], v[30:33]
	v_mfma_f32_16x16x32_bf16 v[26:29], v[182:185], v[222:225], v[26:29]
	v_mfma_f32_16x16x32_bf16 v[14:17], v[134:137], v[230:233], v[14:17]
	v_mfma_f32_16x16x32_bf16 v[10:13], v[182:185], v[230:233], v[10:13]
	s_setprio 0
	s_setprio 1
	v_mfma_f32_16x16x32_bf16 v[54:57], v[186:189], v[202:205], v[54:57]
	v_mfma_f32_16x16x32_bf16 v[50:53], v[194:197], v[202:205], v[50:53]
	v_mfma_f32_16x16x32_bf16 v[38:41], v[186:189], v[210:213], v[38:41]
	v_mfma_f32_16x16x32_bf16 v[34:37], v[194:197], v[210:213], v[34:37]
	v_mfma_f32_16x16x32_bf16 v[22:25], v[186:189], v[218:221], v[22:25]
	v_mfma_f32_16x16x32_bf16 v[18:21], v[194:197], v[218:221], v[18:21]
	v_mfma_f32_16x16x32_bf16 v[6:9], v[186:189], v[226:229], v[6:9]
	v_mfma_f32_16x16x32_bf16 v[2:5], v[194:197], v[226:229], v[2:5]
	v_mfma_f32_16x16x32_bf16 v[54:57], v[190:193], v[206:209], v[54:57]
	v_mfma_f32_16x16x32_bf16 v[50:53], v[198:201], v[206:209], v[50:53]
	v_mfma_f32_16x16x32_bf16 v[38:41], v[190:193], v[214:217], v[38:41]
	v_mfma_f32_16x16x32_bf16 v[34:37], v[198:201], v[214:217], v[34:37]
	v_mfma_f32_16x16x32_bf16 v[22:25], v[190:193], v[222:225], v[22:25]
	v_mfma_f32_16x16x32_bf16 v[18:21], v[198:201], v[222:225], v[18:21]
	s_setprio 2
	s_barrier
	v_mfma_f32_16x16x32_bf16 v[6:9], v[190:193], v[230:233], v[6:9]
	v_mfma_f32_16x16x32_bf16 v[2:5], v[198:201], v[230:233], v[2:5]
	s_setprio 0
	s_add_i32 s20, s20, 2
	s_add_u32 s36, s36, 0x100
	s_addc_u32 s37, s37, 0
	s_add_u32 s13, s13, 0x100
	s_addc_u32 s19, s19, 0
	s_cmp_gt_u32 s20, 29
	s_cbranch_scc0 .LBB0_1294
	s_and_b64 vcc, exec, s[2:3]
	s_cbranch_vccz .LBB0_1297
	s_barrier

.LBB0_1620:
	s_ashr_i32 s19, s18, 31
	s_lshl_b64 s[28:29], s[18:19], 18
	v_readlane_b32 s5, v245, 24
	s_add_u32 s28, s5, s28
	v_readlane_b32 s5, v245, 26
	s_addc_u32 s29, s5, s29
	s_and_b64 s[34:35], s[22:23], exec
	s_cselect_b32 s8, s29, s43
	s_cselect_b32 s19, s28, s42
	s_ashr_i32 s5, s4, 31
	s_lshl_b64 s[34:35], s[4:5], 18
	s_add_u32 s34, s11, s34
	s_addc_u32 s35, s13, s35
	s_and_b64 s[46:47], s[22:23], exec
	s_cselect_b32 s5, s35, s45
	s_cselect_b32 s21, s34, s44
	s_add_u32 s42, s42, 0x20080
	s_addc_u32 s43, s43, 0
	s_add_u32 s39, s44, 0x100
	s_addc_u32 s50, s45, 0
	s_mov_b32 s51, -2
	s_waitcnt vmcnt(0) lgkmcnt(0)
	s_add_u32 s44, s42, 0xfffe0080
	s_addc_u32 s45, s43, -1
	s_add_i32 s52, 0, 0x10000
	s_cmp_eq_u32 s51, 4
	s_cselect_b32 s47, s8, s45
	s_cselect_b32 s46, s19, s44
	v_add_u32_e32 v154, s52, v145
	s_cselect_b32 s45, s5, s50
	s_cselect_b32 s44, s21, s39
	s_add_i32 s54, 0, 0x14000
	ds_read_b128 v[130:133], v154
	ds_read_b128 v[134:137], v154 offset:1024
	ds_read_b128 v[150:153], v154 offset:2048
	ds_read_b128 v[158:161], v154 offset:3072
	v_add_u32_e32 v154, s54, v145
	ds_read_b128 v[164:167], v154
	ds_read_b128 v[180:183], v154 offset:1024
	ds_read_b128 v[184:187], v154 offset:2048
	ds_read_b128 v[188:191], v154 offset:3072
	v_lshl_add_u64 v[154:155], s[42:43], 0, v[146:147]
	s_add_i32 m0, s20, 0xc000
	ds_read_b128 v[192:195], v157
	ds_read_b128 v[196:199], v157 offset:1024
	ds_read_b128 v[200:203], v157 offset:2048
	ds_read_b128 v[204:207], v157 offset:3072
	ds_read_b128 v[208:211], v157 offset:4096
	ds_read_b128 v[212:215], v157 offset:5120
	ds_read_b128 v[216:219], v157 offset:6144
	ds_read_b128 v[220:223], v157 offset:7168
	global_load_lds_dwordx4 v[154:155], off
	s_add_i32 m0, s20, 0xe000
	v_lshl_add_u64 v[154:155], s[42:43], 0, v[148:149]
	global_load_lds_dwordx4 v[154:155], off
	s_waitcnt vmcnt(8)
	s_waitcnt lgkmcnt(0)
	s_barrier
	s_setprio 1
	s_waitcnt lgkmcnt(0)
	v_mfma_f32_16x16x32_bf16 v[126:129], v[130:133], v[192:195], 0
	v_mfma_f32_16x16x32_bf16 v[122:125], v[150:153], v[192:195], 0
	v_mfma_f32_16x16x32_bf16 v[110:113], v[130:133], v[200:203], 0
	v_mfma_f32_16x16x32_bf16 v[106:109], v[150:153], v[200:203], 0
	v_mfma_f32_16x16x32_bf16 v[94:97], v[130:133], v[208:211], 0
	v_mfma_f32_16x16x32_bf16 v[90:93], v[150:153], v[208:211], 0
	v_mfma_f32_16x16x32_bf16 v[78:81], v[130:133], v[216:219], 0
	v_mfma_f32_16x16x32_bf16 v[74:77], v[150:153], v[216:219], 0
	v_mfma_f32_16x16x32_bf16 v[126:129], v[134:137], v[196:199], v[126:129]
	v_mfma_f32_16x16x32_bf16 v[122:125], v[158:161], v[196:199], v[122:125]
	v_mfma_f32_16x16x32_bf16 v[110:113], v[134:137], v[204:207], v[110:113]
	v_mfma_f32_16x16x32_bf16 v[106:109], v[158:161], v[204:207], v[106:109]
	v_mfma_f32_16x16x32_bf16 v[94:97], v[134:137], v[212:215], v[94:97]
	v_mfma_f32_16x16x32_bf16 v[90:93], v[158:161], v[212:215], v[90:93]
	v_mfma_f32_16x16x32_bf16 v[78:81], v[134:137], v[220:223], v[78:81]
	v_mfma_f32_16x16x32_bf16 v[74:77], v[158:161], v[220:223], v[74:77]
	s_setprio 0
	s_setprio 1
	v_mfma_f32_16x16x32_bf16 v[118:121], v[164:167], v[192:195], 0
	v_mfma_f32_16x16x32_bf16 v[114:117], v[184:187], v[192:195], 0
	v_mfma_f32_16x16x32_bf16 v[102:105], v[164:167], v[200:203], 0
	v_mfma_f32_16x16x32_bf16 v[98:101], v[184:187], v[200:203], 0
	v_mfma_f32_16x16x32_bf16 v[86:89], v[164:167], v[208:211], 0
	v_mfma_f32_16x16x32_bf16 v[82:85], v[184:187], v[208:211], 0
	v_mfma_f32_16x16x32_bf16 v[70:73], v[164:167], v[216:219], 0
	v_mfma_f32_16x16x32_bf16 v[66:69], v[184:187], v[216:219], 0
	v_mfma_f32_16x16x32_bf16 v[118:121], v[180:183], v[196:199], v[118:121]
	v_mfma_f32_16x16x32_bf16 v[114:117], v[188:191], v[196:199], v[114:117]
	v_mfma_f32_16x16x32_bf16 v[102:105], v[180:183], v[204:207], v[102:105]
	v_mfma_f32_16x16x32_bf16 v[98:101], v[188:191], v[204:207], v[98:101]
	v_mfma_f32_16x16x32_bf16 v[86:89], v[180:183], v[212:215], v[86:89]
	v_mfma_f32_16x16x32_bf16 v[82:85], v[188:191], v[212:215], v[82:85]
	s_setprio 2
	s_barrier
	v_mfma_f32_16x16x32_bf16 v[70:73], v[180:183], v[220:223], v[70:73]
	v_mfma_f32_16x16x32_bf16 v[66:69], v[188:191], v[220:223], v[66:69]
	s_setprio 0
	s_add_i32 s52, s52, s9
	v_lshl_add_u64 v[154:155], s[44:45], 0, v[162:163]
	s_mov_b32 m0, s52
	ds_read_b128 v[192:195], v157 offset:16384
	ds_read_b128 v[196:199], v157 offset:17408
	ds_read_b128 v[200:203], v157 offset:18432
	ds_read_b128 v[204:207], v157 offset:19456
	ds_read_b128 v[208:211], v157 offset:20480
	ds_read_b128 v[212:215], v157 offset:21504
	ds_read_b128 v[216:219], v157 offset:22528
	ds_read_b128 v[220:223], v157 offset:23552
	global_load_lds_dwordx4 v[154:155], off
	s_add_i32 m0, s52, 0x2000
	s_add_u32 s52, s44, 0x20000
	v_lshl_add_u64 v[168:169], s[44:45], 0, v[142:143]
	s_addc_u32 s53, s45, 0
	s_add_i32 s54, s54, s9
	global_load_lds_dwordx4 v[168:169], off
	v_lshl_add_u64 v[224:225], s[52:53], 0, v[162:163]
	s_mov_b32 m0, s54
	v_lshl_add_u64 v[226:227], s[46:47], 0, v[140:141]
	global_load_lds_dwordx4 v[224:225], off
	s_add_i32 m0, s54, 0x2000
	v_lshl_add_u64 v[224:225], s[52:53], 0, v[142:143]
	global_load_lds_dwordx4 v[224:225], off
	s_mov_b32 m0, s20
	v_lshl_add_u64 v[224:225], s[46:47], 0, v[138:139]
	global_load_lds_dwordx4 v[224:225], off
	s_mov_b32 m0, s25
	s_nop 0
	global_load_lds_dwordx4 v[226:227], off
	s_waitcnt vmcnt(8)
	s_waitcnt lgkmcnt(0)
	s_barrier
	s_setprio 1
	s_waitcnt lgkmcnt(0)
	v_mfma_f32_16x16x32_bf16 v[62:65], v[130:133], v[192:195], 0
	v_mfma_f32_16x16x32_bf16 v[58:61], v[150:153], v[192:195], 0
	v_mfma_f32_16x16x32_bf16 v[46:49], v[130:133], v[200:203], 0
	v_mfma_f32_16x16x32_bf16 v[42:45], v[150:153], v[200:203], 0
	v_mfma_f32_16x16x32_bf16 v[30:33], v[130:133], v[208:211], 0
	v_mfma_f32_16x16x32_bf16 v[26:29], v[150:153], v[208:211], 0
	v_mfma_f32_16x16x32_bf16 v[14:17], v[130:133], v[216:219], 0
	v_mfma_f32_16x16x32_bf16 v[10:13], v[150:153], v[216:219], 0
	v_mfma_f32_16x16x32_bf16 v[62:65], v[134:137], v[196:199], v[62:65]
	v_mfma_f32_16x16x32_bf16 v[58:61], v[158:161], v[196:199], v[58:61]
	v_mfma_f32_16x16x32_bf16 v[46:49], v[134:137], v[204:207], v[46:49]
	v_mfma_f32_16x16x32_bf16 v[42:45], v[158:161], v[204:207], v[42:45]
	v_mfma_f32_16x16x32_bf16 v[30:33], v[134:137], v[212:215], v[30:33]
	v_mfma_f32_16x16x32_bf16 v[26:29], v[158:161], v[212:215], v[26:29]
	v_mfma_f32_16x16x32_bf16 v[14:17], v[134:137], v[220:223], v[14:17]
	v_mfma_f32_16x16x32_bf16 v[10:13], v[158:161], v[220:223], v[10:13]
	s_setprio 0
	s_setprio 1
	v_mfma_f32_16x16x32_bf16 v[54:57], v[164:167], v[192:195], 0
	v_mfma_f32_16x16x32_bf16 v[50:53], v[184:187], v[192:195], 0
	v_mfma_f32_16x16x32_bf16 v[38:41], v[164:167], v[200:203], 0
	v_mfma_f32_16x16x32_bf16 v[34:37], v[184:187], v[200:203], 0
	v_mfma_f32_16x16x32_bf16 v[22:25], v[164:167], v[208:211], 0
	v_mfma_f32_16x16x32_bf16 v[18:21], v[184:187], v[208:211], 0
	v_mfma_f32_16x16x32_bf16 v[6:9], v[164:167], v[216:219], 0
	v_mfma_f32_16x16x32_bf16 v[2:5], v[184:187], v[216:219], 0
	v_mfma_f32_16x16x32_bf16 v[54:57], v[180:183], v[196:199], v[54:57]
	v_mfma_f32_16x16x32_bf16 v[50:53], v[188:191], v[196:199], v[50:53]
	v_mfma_f32_16x16x32_bf16 v[38:41], v[180:183], v[204:207], v[38:41]
	v_mfma_f32_16x16x32_bf16 v[34:37], v[188:191], v[204:207], v[34:37]
	v_mfma_f32_16x16x32_bf16 v[22:25], v[180:183], v[212:215], v[22:25]
	v_mfma_f32_16x16x32_bf16 v[18:21], v[188:191], v[212:215], v[18:21]
	s_setprio 2
	s_barrier
	v_mfma_f32_16x16x32_bf16 v[6:9], v[180:183], v[220:223], v[6:9]
	v_mfma_f32_16x16x32_bf16 v[2:5], v[188:191], v[220:223], v[2:5]
	s_setprio 0
	s_add_i32 s52, 0, 0x18000
	s_add_i32 s53, 0, 0x1c000
	v_add_u32_e32 v158, s52, v145
	v_add_u32_e32 v179, s53, v145
	ds_read_b128 v[130:133], v158
	ds_read_b128 v[134:137], v158 offset:1024
	ds_read_b128 v[150:153], v158 offset:2048
	ds_read_b128 v[158:161], v158 offset:3072
	ds_read_b128 v[164:167], v179
	ds_read_b128 v[180:183], v179 offset:1024
	ds_read_b128 v[184:187], v179 offset:2048
	ds_read_b128 v[188:191], v179 offset:3072
	s_add_u32 s46, s46, 0x20000
	s_addc_u32 s47, s47, 0
	s_mov_b32 m0, s26
	v_lshl_add_u64 v[228:229], s[46:47], 0, v[138:139]
	ds_read_b128 v[192:195], v157 offset:32768
	ds_read_b128 v[196:199], v157 offset:33792
	ds_read_b128 v[200:203], v157 offset:34816
	ds_read_b128 v[204:207], v157 offset:35840
	ds_read_b128 v[208:211], v157 offset:36864
	ds_read_b128 v[212:215], v157 offset:37888
	ds_read_b128 v[216:219], v157 offset:38912
	ds_read_b128 v[220:223], v157 offset:39936
	global_load_lds_dwordx4 v[228:229], off
	s_mov_b32 m0, s27
	v_lshl_add_u64 v[228:229], s[46:47], 0, v[140:141]
	global_load_lds_dwordx4 v[228:229], off
	s_waitcnt vmcnt(8)
	s_waitcnt lgkmcnt(0)
	s_barrier
	s_setprio 1
	s_waitcnt lgkmcnt(0)
	v_mfma_f32_16x16x32_bf16 v[126:129], v[130:133], v[192:195], v[126:129]
	v_mfma_f32_16x16x32_bf16 v[122:125], v[150:153], v[192:195], v[122:125]
	v_mfma_f32_16x16x32_bf16 v[110:113], v[130:133], v[200:203], v[110:113]
	v_mfma_f32_16x16x32_bf16 v[106:109], v[150:153], v[200:203], v[106:109]
	v_mfma_f32_16x16x32_bf16 v[94:97], v[130:133], v[208:211], v[94:97]
	v_mfma_f32_16x16x32_bf16 v[90:93], v[150:153], v[208:211], v[90:93]
	v_mfma_f32_16x16x32_bf16 v[78:81], v[130:133], v[216:219], v[78:81]
	v_mfma_f32_16x16x32_bf16 v[74:77], v[150:153], v[216:219], v[74:77]
	v_mfma_f32_16x16x32_bf16 v[126:129], v[134:137], v[196:199], v[126:129]
	v_mfma_f32_16x16x32_bf16 v[122:125], v[158:161], v[196:199], v[122:125]
	v_mfma_f32_16x16x32_bf16 v[110:113], v[134:137], v[204:207], v[110:113]
	v_mfma_f32_16x16x32_bf16 v[106:109], v[158:161], v[204:207], v[106:109]
	v_mfma_f32_16x16x32_bf16 v[94:97], v[134:137], v[212:215], v[94:97]
	v_mfma_f32_16x16x32_bf16 v[90:93], v[158:161], v[212:215], v[90:93]
	v_mfma_f32_16x16x32_bf16 v[78:81], v[134:137], v[220:223], v[78:81]
	v_mfma_f32_16x16x32_bf16 v[74:77], v[158:161], v[220:223], v[74:77]
	s_setprio 0
	s_setprio 1
	v_mfma_f32_16x16x32_bf16 v[118:121], v[164:167], v[192:195], v[118:121]
	v_mfma_f32_16x16x32_bf16 v[114:117], v[184:187], v[192:195], v[114:117]
	v_mfma_f32_16x16x32_bf16 v[102:105], v[164:167], v[200:203], v[102:105]
	v_mfma_f32_16x16x32_bf16 v[98:101], v[184:187], v[200:203], v[98:101]
	v_mfma_f32_16x16x32_bf16 v[86:89], v[164:167], v[208:211], v[86:89]
	v_mfma_f32_16x16x32_bf16 v[82:85], v[184:187], v[208:211], v[82:85]
	v_mfma_f32_16x16x32_bf16 v[70:73], v[164:167], v[216:219], v[70:73]
	v_mfma_f32_16x16x32_bf16 v[66:69], v[184:187], v[216:219], v[66:69]
	v_mfma_f32_16x16x32_bf16 v[118:121], v[180:183], v[196:199], v[118:121]
	v_mfma_f32_16x16x32_bf16 v[114:117], v[188:191], v[196:199], v[114:117]
	v_mfma_f32_16x16x32_bf16 v[102:105], v[180:183], v[204:207], v[102:105]
	v_mfma_f32_16x16x32_bf16 v[98:101], v[188:191], v[204:207], v[98:101]
	v_mfma_f32_16x16x32_bf16 v[86:89], v[180:183], v[212:215], v[86:89]
	v_mfma_f32_16x16x32_bf16 v[82:85], v[188:191], v[212:215], v[82:85]
	s_setprio 2
	s_barrier
	v_mfma_f32_16x16x32_bf16 v[70:73], v[180:183], v[220:223], v[70:73]
	v_mfma_f32_16x16x32_bf16 v[66:69], v[188:191], v[220:223], v[66:69]
	s_setprio 0
	s_add_i32 s46, s52, s9
	v_lshl_add_u64 v[154:155], v[154:155], 0, s[6:7]
	s_mov_b32 m0, s46
	ds_read_b128 v[192:195], v157 offset:49152
	ds_read_b128 v[196:199], v157 offset:50176
	ds_read_b128 v[200:203], v157 offset:51200
	ds_read_b128 v[204:207], v157 offset:52224
	ds_read_b128 v[208:211], v157 offset:53248
	ds_read_b128 v[212:215], v157 offset:54272
	ds_read_b128 v[216:219], v157 offset:55296
	ds_read_b128 v[220:223], v157 offset:56320
	global_load_lds_dwordx4 v[154:155], off
	s_add_i32 m0, s46, 0x2000
	s_add_u32 s44, s44, 0x20080
	v_lshl_add_u64 v[154:155], v[168:169], 0, s[6:7]
	s_addc_u32 s45, s45, 0
	s_add_i32 s46, s53, s9
	global_load_lds_dwordx4 v[154:155], off
	s_mov_b32 m0, s46
	v_lshl_add_u64 v[154:155], s[44:45], 0, v[162:163]
	global_load_lds_dwordx4 v[154:155], off
	s_add_i32 m0, s46, 0x2000
	v_lshl_add_u64 v[154:155], s[44:45], 0, v[142:143]
	global_load_lds_dwordx4 v[154:155], off
	s_mov_b32 m0, s41
	v_lshl_add_u64 v[154:155], v[224:225], 0, s[6:7]
	global_load_lds_dwordx4 v[154:155], off
	s_mov_b32 m0, s48
	v_lshl_add_u64 v[154:155], v[226:227], 0, s[6:7]
	global_load_lds_dwordx4 v[154:155], off
	s_waitcnt vmcnt(8)
	s_waitcnt lgkmcnt(0)
	s_barrier
	s_setprio 1
	s_waitcnt lgkmcnt(0)
	v_mfma_f32_16x16x32_bf16 v[62:65], v[130:133], v[192:195], v[62:65]
	v_mfma_f32_16x16x32_bf16 v[58:61], v[150:153], v[192:195], v[58:61]
	v_mfma_f32_16x16x32_bf16 v[46:49], v[130:133], v[200:203], v[46:49]
	v_mfma_f32_16x16x32_bf16 v[42:45], v[150:153], v[200:203], v[42:45]
	v_mfma_f32_16x16x32_bf16 v[30:33], v[130:133], v[208:211], v[30:33]
	v_mfma_f32_16x16x32_bf16 v[26:29], v[150:153], v[208:211], v[26:29]
	v_mfma_f32_16x16x32_bf16 v[14:17], v[130:133], v[216:219], v[14:17]
	v_mfma_f32_16x16x32_bf16 v[10:13], v[150:153], v[216:219], v[10:13]
	v_mfma_f32_16x16x32_bf16 v[62:65], v[134:137], v[196:199], v[62:65]
	v_mfma_f32_16x16x32_bf16 v[58:61], v[158:161], v[196:199], v[58:61]
	v_mfma_f32_16x16x32_bf16 v[46:49], v[134:137], v[204:207], v[46:49]
	v_mfma_f32_16x16x32_bf16 v[42:45], v[158:161], v[204:207], v[42:45]
	v_mfma_f32_16x16x32_bf16 v[30:33], v[134:137], v[212:215], v[30:33]
	v_mfma_f32_16x16x32_bf16 v[26:29], v[158:161], v[212:215], v[26:29]
	v_mfma_f32_16x16x32_bf16 v[14:17], v[134:137], v[220:223], v[14:17]
	v_mfma_f32_16x16x32_bf16 v[10:13], v[158:161], v[220:223], v[10:13]
	s_setprio 0
	s_setprio 1
	v_mfma_f32_16x16x32_bf16 v[54:57], v[164:167], v[192:195], v[54:57]
	v_mfma_f32_16x16x32_bf16 v[50:53], v[184:187], v[192:195], v[50:53]
	v_mfma_f32_16x16x32_bf16 v[38:41], v[164:167], v[200:203], v[38:41]
	v_mfma_f32_16x16x32_bf16 v[34:37], v[184:187], v[200:203], v[34:37]
	v_mfma_f32_16x16x32_bf16 v[22:25], v[164:167], v[208:211], v[22:25]
	v_mfma_f32_16x16x32_bf16 v[18:21], v[184:187], v[208:211], v[18:21]
	v_mfma_f32_16x16x32_bf16 v[6:9], v[164:167], v[216:219], v[6:9]
	v_mfma_f32_16x16x32_bf16 v[2:5], v[184:187], v[216:219], v[2:5]
	v_mfma_f32_16x16x32_bf16 v[54:57], v[180:183], v[196:199], v[54:57]
	v_mfma_f32_16x16x32_bf16 v[50:53], v[188:191], v[196:199], v[50:53]
	v_mfma_f32_16x16x32_bf16 v[38:41], v[180:183], v[204:207], v[38:41]
	v_mfma_f32_16x16x32_bf16 v[34:37], v[188:191], v[204:207], v[34:37]
	v_mfma_f32_16x16x32_bf16 v[22:25], v[180:183], v[212:215], v[22:25]
	v_mfma_f32_16x16x32_bf16 v[18:21], v[188:191], v[212:215], v[18:21]
	s_setprio 2
	s_barrier
	v_mfma_f32_16x16x32_bf16 v[6:9], v[180:183], v[220:223], v[6:9]
	v_mfma_f32_16x16x32_bf16 v[2:5], v[188:191], v[220:223], v[2:5]
	s_setprio 0
	s_add_i32 s51, s51, 2
	s_add_u32 s42, s42, 0x100
	s_addc_u32 s43, s43, 0
	s_add_u32 s39, s39, 0x100
	s_addc_u32 s50, s50, 0
	s_cmp_gt_u32 s51, 5
.LBB0_1621:
	s_add_u32 s44, s42, 0xfffe0080
	s_addc_u32 s45, s43, -1
	s_add_i32 s52, 0, 0x10000
	s_cmp_eq_u32 s51, 4
	s_cselect_b32 s47, s8, s45
	s_cselect_b32 s46, s19, s44
	v_add_u32_e32 v154, s52, v145
	s_cselect_b32 s45, s5, s50
	s_cselect_b32 s44, s21, s39
	s_add_i32 s54, 0, 0x14000
	ds_read_b128 v[130:133], v154
	ds_read_b128 v[134:137], v154 offset:1024
	ds_read_b128 v[150:153], v154 offset:2048
	ds_read_b128 v[158:161], v154 offset:3072
	v_add_u32_e32 v154, s54, v145
	ds_read_b128 v[164:167], v154
	ds_read_b128 v[180:183], v154 offset:1024
	ds_read_b128 v[184:187], v154 offset:2048
	ds_read_b128 v[188:191], v154 offset:3072
	v_lshl_add_u64 v[154:155], s[42:43], 0, v[146:147]
	s_add_i32 m0, s20, 0xc000
	ds_read_b128 v[192:195], v157
	ds_read_b128 v[196:199], v157 offset:1024
	ds_read_b128 v[200:203], v157 offset:2048
	ds_read_b128 v[204:207], v157 offset:3072
	ds_read_b128 v[208:211], v157 offset:4096
	ds_read_b128 v[212:215], v157 offset:5120
	ds_read_b128 v[216:219], v157 offset:6144
	ds_read_b128 v[220:223], v157 offset:7168
	global_load_lds_dwordx4 v[154:155], off
	s_add_i32 m0, s20, 0xe000
	v_lshl_add_u64 v[154:155], s[42:43], 0, v[148:149]
	global_load_lds_dwordx4 v[154:155], off
	s_waitcnt vmcnt(8)
	s_waitcnt lgkmcnt(0)
	s_barrier
	s_setprio 1
	s_waitcnt lgkmcnt(0)
	v_mfma_f32_16x16x32_bf16 v[126:129], v[130:133], v[192:195], v[126:129]
	v_mfma_f32_16x16x32_bf16 v[122:125], v[150:153], v[192:195], v[122:125]
	v_mfma_f32_16x16x32_bf16 v[110:113], v[130:133], v[200:203], v[110:113]
	v_mfma_f32_16x16x32_bf16 v[106:109], v[150:153], v[200:203], v[106:109]
	v_mfma_f32_16x16x32_bf16 v[94:97], v[130:133], v[208:211], v[94:97]
	v_mfma_f32_16x16x32_bf16 v[90:93], v[150:153], v[208:211], v[90:93]
	v_mfma_f32_16x16x32_bf16 v[78:81], v[130:133], v[216:219], v[78:81]
	v_mfma_f32_16x16x32_bf16 v[74:77], v[150:153], v[216:219], v[74:77]
	v_mfma_f32_16x16x32_bf16 v[126:129], v[134:137], v[196:199], v[126:129]
	v_mfma_f32_16x16x32_bf16 v[122:125], v[158:161], v[196:199], v[122:125]
	v_mfma_f32_16x16x32_bf16 v[110:113], v[134:137], v[204:207], v[110:113]
	v_mfma_f32_16x16x32_bf16 v[106:109], v[158:161], v[204:207], v[106:109]
	v_mfma_f32_16x16x32_bf16 v[94:97], v[134:137], v[212:215], v[94:97]
	v_mfma_f32_16x16x32_bf16 v[90:93], v[158:161], v[212:215], v[90:93]
	v_mfma_f32_16x16x32_bf16 v[78:81], v[134:137], v[220:223], v[78:81]
	v_mfma_f32_16x16x32_bf16 v[74:77], v[158:161], v[220:223], v[74:77]
	s_setprio 0
	s_setprio 1
	v_mfma_f32_16x16x32_bf16 v[118:121], v[164:167], v[192:195], v[118:121]
	v_mfma_f32_16x16x32_bf16 v[114:117], v[184:187], v[192:195], v[114:117]
	v_mfma_f32_16x16x32_bf16 v[102:105], v[164:167], v[200:203], v[102:105]
	v_mfma_f32_16x16x32_bf16 v[98:101], v[184:187], v[200:203], v[98:101]
	v_mfma_f32_16x16x32_bf16 v[86:89], v[164:167], v[208:211], v[86:89]
	v_mfma_f32_16x16x32_bf16 v[82:85], v[184:187], v[208:211], v[82:85]
	v_mfma_f32_16x16x32_bf16 v[70:73], v[164:167], v[216:219], v[70:73]
	v_mfma_f32_16x16x32_bf16 v[66:69], v[184:187], v[216:219], v[66:69]
	v_mfma_f32_16x16x32_bf16 v[118:121], v[180:183], v[196:199], v[118:121]
	v_mfma_f32_16x16x32_bf16 v[114:117], v[188:191], v[196:199], v[114:117]
	v_mfma_f32_16x16x32_bf16 v[102:105], v[180:183], v[204:207], v[102:105]
	v_mfma_f32_16x16x32_bf16 v[98:101], v[188:191], v[204:207], v[98:101]
	v_mfma_f32_16x16x32_bf16 v[86:89], v[180:183], v[212:215], v[86:89]
	v_mfma_f32_16x16x32_bf16 v[82:85], v[188:191], v[212:215], v[82:85]
	s_setprio 2
	s_barrier
	v_mfma_f32_16x16x32_bf16 v[70:73], v[180:183], v[220:223], v[70:73]
	v_mfma_f32_16x16x32_bf16 v[66:69], v[188:191], v[220:223], v[66:69]
	s_setprio 0
	s_add_i32 s52, s52, s9
	v_lshl_add_u64 v[154:155], s[44:45], 0, v[162:163]
	s_mov_b32 m0, s52
	ds_read_b128 v[192:195], v157 offset:16384
	ds_read_b128 v[196:199], v157 offset:17408
	ds_read_b128 v[200:203], v157 offset:18432
	ds_read_b128 v[204:207], v157 offset:19456
	ds_read_b128 v[208:211], v157 offset:20480
	ds_read_b128 v[212:215], v157 offset:21504
	ds_read_b128 v[216:219], v157 offset:22528
	ds_read_b128 v[220:223], v157 offset:23552
	global_load_lds_dwordx4 v[154:155], off
	s_add_i32 m0, s52, 0x2000
	s_add_u32 s52, s44, 0x20000
	v_lshl_add_u64 v[168:169], s[44:45], 0, v[142:143]
	s_addc_u32 s53, s45, 0
	s_add_i32 s54, s54, s9
	global_load_lds_dwordx4 v[168:169], off
	v_lshl_add_u64 v[224:225], s[52:53], 0, v[162:163]
	s_mov_b32 m0, s54
	v_lshl_add_u64 v[226:227], s[46:47], 0, v[140:141]
	global_load_lds_dwordx4 v[224:225], off
	s_add_i32 m0, s54, 0x2000
	v_lshl_add_u64 v[224:225], s[52:53], 0, v[142:143]
	global_load_lds_dwordx4 v[224:225], off
	s_mov_b32 m0, s20
	v_lshl_add_u64 v[224:225], s[46:47], 0, v[138:139]
	global_load_lds_dwordx4 v[224:225], off
	s_mov_b32 m0, s25
	s_nop 0
	global_load_lds_dwordx4 v[226:227], off
	s_waitcnt vmcnt(8)
	s_waitcnt lgkmcnt(0)
	s_barrier
	s_setprio 1
	s_waitcnt lgkmcnt(0)
	v_mfma_f32_16x16x32_bf16 v[62:65], v[130:133], v[192:195], v[62:65]
	v_mfma_f32_16x16x32_bf16 v[58:61], v[150:153], v[192:195], v[58:61]
	v_mfma_f32_16x16x32_bf16 v[46:49], v[130:133], v[200:203], v[46:49]
	v_mfma_f32_16x16x32_bf16 v[42:45], v[150:153], v[200:203], v[42:45]
	v_mfma_f32_16x16x32_bf16 v[30:33], v[130:133], v[208:211], v[30:33]
	v_mfma_f32_16x16x32_bf16 v[26:29], v[150:153], v[208:211], v[26:29]
	v_mfma_f32_16x16x32_bf16 v[14:17], v[130:133], v[216:219], v[14:17]
	v_mfma_f32_16x16x32_bf16 v[10:13], v[150:153], v[216:219], v[10:13]
	v_mfma_f32_16x16x32_bf16 v[62:65], v[134:137], v[196:199], v[62:65]
	v_mfma_f32_16x16x32_bf16 v[58:61], v[158:161], v[196:199], v[58:61]
	v_mfma_f32_16x16x32_bf16 v[46:49], v[134:137], v[204:207], v[46:49]
	v_mfma_f32_16x16x32_bf16 v[42:45], v[158:161], v[204:207], v[42:45]
	v_mfma_f32_16x16x32_bf16 v[30:33], v[134:137], v[212:215], v[30:33]
	v_mfma_f32_16x16x32_bf16 v[26:29], v[158:161], v[212:215], v[26:29]
	v_mfma_f32_16x16x32_bf16 v[14:17], v[134:137], v[220:223], v[14:17]
	v_mfma_f32_16x16x32_bf16 v[10:13], v[158:161], v[220:223], v[10:13]
	s_setprio 0
	s_setprio 1
	v_mfma_f32_16x16x32_bf16 v[54:57], v[164:167], v[192:195], v[54:57]
	v_mfma_f32_16x16x32_bf16 v[50:53], v[184:187], v[192:195], v[50:53]
	v_mfma_f32_16x16x32_bf16 v[38:41], v[164:167], v[200:203], v[38:41]
	v_mfma_f32_16x16x32_bf16 v[34:37], v[184:187], v[200:203], v[34:37]
	v_mfma_f32_16x16x32_bf16 v[22:25], v[164:167], v[208:211], v[22:25]
	v_mfma_f32_16x16x32_bf16 v[18:21], v[184:187], v[208:211], v[18:21]
	v_mfma_f32_16x16x32_bf16 v[6:9], v[164:167], v[216:219], v[6:9]
	v_mfma_f32_16x16x32_bf16 v[2:5], v[184:187], v[216:219], v[2:5]
	v_mfma_f32_16x16x32_bf16 v[54:57], v[180:183], v[196:199], v[54:57]
	v_mfma_f32_16x16x32_bf16 v[50:53], v[188:191], v[196:199], v[50:53]
	v_mfma_f32_16x16x32_bf16 v[38:41], v[180:183], v[204:207], v[38:41]
	v_mfma_f32_16x16x32_bf16 v[34:37], v[188:191], v[204:207], v[34:37]
	v_mfma_f32_16x16x32_bf16 v[22:25], v[180:183], v[212:215], v[22:25]
	v_mfma_f32_16x16x32_bf16 v[18:21], v[188:191], v[212:215], v[18:21]
	s_setprio 2
	s_barrier
	v_mfma_f32_16x16x32_bf16 v[6:9], v[180:183], v[220:223], v[6:9]
	v_mfma_f32_16x16x32_bf16 v[2:5], v[188:191], v[220:223], v[2:5]
	s_setprio 0
	s_add_i32 s52, 0, 0x18000
	s_add_i32 s53, 0, 0x1c000
	v_add_u32_e32 v158, s52, v145
	v_add_u32_e32 v179, s53, v145
	ds_read_b128 v[130:133], v158
	ds_read_b128 v[134:137], v158 offset:1024
	ds_read_b128 v[150:153], v158 offset:2048
	ds_read_b128 v[158:161], v158 offset:3072
	ds_read_b128 v[164:167], v179
	ds_read_b128 v[180:183], v179 offset:1024
	ds_read_b128 v[184:187], v179 offset:2048
	ds_read_b128 v[188:191], v179 offset:3072
	s_add_u32 s46, s46, 0x20000
	s_addc_u32 s47, s47, 0
	s_mov_b32 m0, s26
	v_lshl_add_u64 v[228:229], s[46:47], 0, v[138:139]
	ds_read_b128 v[192:195], v157 offset:32768
	ds_read_b128 v[196:199], v157 offset:33792
	ds_read_b128 v[200:203], v157 offset:34816
	ds_read_b128 v[204:207], v157 offset:35840
	ds_read_b128 v[208:211], v157 offset:36864
	ds_read_b128 v[212:215], v157 offset:37888
	ds_read_b128 v[216:219], v157 offset:38912
	ds_read_b128 v[220:223], v157 offset:39936
	global_load_lds_dwordx4 v[228:229], off
	s_mov_b32 m0, s27
	v_lshl_add_u64 v[228:229], s[46:47], 0, v[140:141]
	global_load_lds_dwordx4 v[228:229], off
	s_waitcnt vmcnt(8)
	s_waitcnt lgkmcnt(0)
	s_barrier
	s_setprio 1
	s_waitcnt lgkmcnt(0)
	v_mfma_f32_16x16x32_bf16 v[126:129], v[130:133], v[192:195], v[126:129]
	v_mfma_f32_16x16x32_bf16 v[122:125], v[150:153], v[192:195], v[122:125]
	v_mfma_f32_16x16x32_bf16 v[110:113], v[130:133], v[200:203], v[110:113]
	v_mfma_f32_16x16x32_bf16 v[106:109], v[150:153], v[200:203], v[106:109]
	v_mfma_f32_16x16x32_bf16 v[94:97], v[130:133], v[208:211], v[94:97]
	v_mfma_f32_16x16x32_bf16 v[90:93], v[150:153], v[208:211], v[90:93]
	v_mfma_f32_16x16x32_bf16 v[78:81], v[130:133], v[216:219], v[78:81]
	v_mfma_f32_16x16x32_bf16 v[74:77], v[150:153], v[216:219], v[74:77]
	v_mfma_f32_16x16x32_bf16 v[126:129], v[134:137], v[196:199], v[126:129]
	v_mfma_f32_16x16x32_bf16 v[122:125], v[158:161], v[196:199], v[122:125]
	v_mfma_f32_16x16x32_bf16 v[110:113], v[134:137], v[204:207], v[110:113]
	v_mfma_f32_16x16x32_bf16 v[106:109], v[158:161], v[204:207], v[106:109]
	v_mfma_f32_16x16x32_bf16 v[94:97], v[134:137], v[212:215], v[94:97]
	v_mfma_f32_16x16x32_bf16 v[90:93], v[158:161], v[212:215], v[90:93]
	v_mfma_f32_16x16x32_bf16 v[78:81], v[134:137], v[220:223], v[78:81]
	v_mfma_f32_16x16x32_bf16 v[74:77], v[158:161], v[220:223], v[74:77]
	s_setprio 0
	s_setprio 1
	v_mfma_f32_16x16x32_bf16 v[118:121], v[164:167], v[192:195], v[118:121]
	v_mfma_f32_16x16x32_bf16 v[114:117], v[184:187], v[192:195], v[114:117]
	v_mfma_f32_16x16x32_bf16 v[102:105], v[164:167], v[200:203], v[102:105]
	v_mfma_f32_16x16x32_bf16 v[98:101], v[184:187], v[200:203], v[98:101]
	v_mfma_f32_16x16x32_bf16 v[86:89], v[164:167], v[208:211], v[86:89]
	v_mfma_f32_16x16x32_bf16 v[82:85], v[184:187], v[208:211], v[82:85]
	v_mfma_f32_16x16x32_bf16 v[70:73], v[164:167], v[216:219], v[70:73]
	v_mfma_f32_16x16x32_bf16 v[66:69], v[184:187], v[216:219], v[66:69]
	v_mfma_f32_16x16x32_bf16 v[118:121], v[180:183], v[196:199], v[118:121]
	v_mfma_f32_16x16x32_bf16 v[114:117], v[188:191], v[196:199], v[114:117]
	v_mfma_f32_16x16x32_bf16 v[102:105], v[180:183], v[204:207], v[102:105]
	v_mfma_f32_16x16x32_bf16 v[98:101], v[188:191], v[204:207], v[98:101]
	v_mfma_f32_16x16x32_bf16 v[86:89], v[180:183], v[212:215], v[86:89]
	v_mfma_f32_16x16x32_bf16 v[82:85], v[188:191], v[212:215], v[82:85]
	s_setprio 2
	s_barrier
	v_mfma_f32_16x16x32_bf16 v[70:73], v[180:183], v[220:223], v[70:73]
	v_mfma_f32_16x16x32_bf16 v[66:69], v[188:191], v[220:223], v[66:69]
	s_setprio 0
	s_add_i32 s46, s52, s9
	v_lshl_add_u64 v[154:155], v[154:155], 0, s[6:7]
	s_mov_b32 m0, s46
	ds_read_b128 v[192:195], v157 offset:49152
	ds_read_b128 v[196:199], v157 offset:50176
	ds_read_b128 v[200:203], v157 offset:51200
	ds_read_b128 v[204:207], v157 offset:52224
	ds_read_b128 v[208:211], v157 offset:53248
	ds_read_b128 v[212:215], v157 offset:54272
	ds_read_b128 v[216:219], v157 offset:55296
	ds_read_b128 v[220:223], v157 offset:56320
	global_load_lds_dwordx4 v[154:155], off
	s_add_i32 m0, s46, 0x2000
	s_add_u32 s44, s44, 0x20080
	v_lshl_add_u64 v[154:155], v[168:169], 0, s[6:7]
	s_addc_u32 s45, s45, 0
	s_add_i32 s46, s53, s9
	global_load_lds_dwordx4 v[154:155], off
	s_mov_b32 m0, s46
	v_lshl_add_u64 v[154:155], s[44:45], 0, v[162:163]
	global_load_lds_dwordx4 v[154:155], off
	s_add_i32 m0, s46, 0x2000
	v_lshl_add_u64 v[154:155], s[44:45], 0, v[142:143]
	global_load_lds_dwordx4 v[154:155], off
	s_mov_b32 m0, s41
	v_lshl_add_u64 v[154:155], v[224:225], 0, s[6:7]
	global_load_lds_dwordx4 v[154:155], off
	s_mov_b32 m0, s48
	v_lshl_add_u64 v[154:155], v[226:227], 0, s[6:7]
	global_load_lds_dwordx4 v[154:155], off
	s_waitcnt vmcnt(8)
	s_waitcnt lgkmcnt(0)
	s_barrier
	s_setprio 1
	s_waitcnt lgkmcnt(0)
	v_mfma_f32_16x16x32_bf16 v[62:65], v[130:133], v[192:195], v[62:65]
	v_mfma_f32_16x16x32_bf16 v[58:61], v[150:153], v[192:195], v[58:61]
	v_mfma_f32_16x16x32_bf16 v[46:49], v[130:133], v[200:203], v[46:49]
	v_mfma_f32_16x16x32_bf16 v[42:45], v[150:153], v[200:203], v[42:45]
	v_mfma_f32_16x16x32_bf16 v[30:33], v[130:133], v[208:211], v[30:33]
	v_mfma_f32_16x16x32_bf16 v[26:29], v[150:153], v[208:211], v[26:29]
	v_mfma_f32_16x16x32_bf16 v[14:17], v[130:133], v[216:219], v[14:17]
	v_mfma_f32_16x16x32_bf16 v[10:13], v[150:153], v[216:219], v[10:13]
	v_mfma_f32_16x16x32_bf16 v[62:65], v[134:137], v[196:199], v[62:65]
	v_mfma_f32_16x16x32_bf16 v[58:61], v[158:161], v[196:199], v[58:61]
	v_mfma_f32_16x16x32_bf16 v[46:49], v[134:137], v[204:207], v[46:49]
	v_mfma_f32_16x16x32_bf16 v[42:45], v[158:161], v[204:207], v[42:45]
	v_mfma_f32_16x16x32_bf16 v[30:33], v[134:137], v[212:215], v[30:33]
	v_mfma_f32_16x16x32_bf16 v[26:29], v[158:161], v[212:215], v[26:29]
	v_mfma_f32_16x16x32_bf16 v[14:17], v[134:137], v[220:223], v[14:17]
	v_mfma_f32_16x16x32_bf16 v[10:13], v[158:161], v[220:223], v[10:13]
	s_setprio 0
	s_setprio 1
	v_mfma_f32_16x16x32_bf16 v[54:57], v[164:167], v[192:195], v[54:57]
	v_mfma_f32_16x16x32_bf16 v[50:53], v[184:187], v[192:195], v[50:53]
	v_mfma_f32_16x16x32_bf16 v[38:41], v[164:167], v[200:203], v[38:41]
	v_mfma_f32_16x16x32_bf16 v[34:37], v[184:187], v[200:203], v[34:37]
	v_mfma_f32_16x16x32_bf16 v[22:25], v[164:167], v[208:211], v[22:25]
	v_mfma_f32_16x16x32_bf16 v[18:21], v[184:187], v[208:211], v[18:21]
	v_mfma_f32_16x16x32_bf16 v[6:9], v[164:167], v[216:219], v[6:9]
	v_mfma_f32_16x16x32_bf16 v[2:5], v[184:187], v[216:219], v[2:5]
	v_mfma_f32_16x16x32_bf16 v[54:57], v[180:183], v[196:199], v[54:57]
	v_mfma_f32_16x16x32_bf16 v[50:53], v[188:191], v[196:199], v[50:53]
	v_mfma_f32_16x16x32_bf16 v[38:41], v[180:183], v[204:207], v[38:41]
	v_mfma_f32_16x16x32_bf16 v[34:37], v[188:191], v[204:207], v[34:37]
	v_mfma_f32_16x16x32_bf16 v[22:25], v[180:183], v[212:215], v[22:25]
	v_mfma_f32_16x16x32_bf16 v[18:21], v[188:191], v[212:215], v[18:21]
	s_setprio 2
	s_barrier
	v_mfma_f32_16x16x32_bf16 v[6:9], v[180:183], v[220:223], v[6:9]
	v_mfma_f32_16x16x32_bf16 v[2:5], v[188:191], v[220:223], v[2:5]
	s_setprio 0
	s_add_i32 s51, s51, 2
	s_add_u32 s42, s42, 0x100
	s_addc_u32 s43, s43, 0
	s_add_u32 s39, s39, 0x100
	s_addc_u32 s50, s50, 0
	s_cmp_gt_u32 s51, 5
	s_cbranch_scc0 .LBB0_1621
	s_and_b64 vcc, exec, s[2:3]
	s_cbranch_vccz .LBB0_1624
	s_barrier

.LBB0_1797:
	s_ashr_i32 s19, s18, 31
	s_lshl_b64 s[20:21], s[18:19], 20
	v_readlane_b32 s5, v243, 17
	s_add_u32 s28, s5, s20
	v_readlane_b32 s5, v243, 18
	s_addc_u32 s29, s5, s21
	s_and_b64 s[20:21], s[34:35], exec
	s_cselect_b32 s11, s29, s23
	s_cselect_b32 s13, s28, s22
	s_ashr_i32 s5, s4, 31
	s_lshl_b64 s[20:21], s[4:5], 20
	s_add_u32 s38, s25, s20
	s_addc_u32 s39, s27, s21
	s_and_b64 s[20:21], s[34:35], exec
	s_cselect_b32 s5, s39, s41
	s_cselect_b32 s19, s38, s40
	s_add_u32 s22, s22, 0x80080
	s_addc_u32 s23, s23, 0
	s_add_u32 s20, s40, 0x100
	s_addc_u32 s21, s41, 0
	s_mov_b32 s26, -2
	s_add_u32 s40, s22, 0xfff80080
	s_addc_u32 s41, s23, -1
	s_add_i32 s52, 0, 0x10000
	s_cmp_eq_u32 s26, 28
	s_cselect_b32 s43, s11, s41
	s_cselect_b32 s42, s13, s40
	v_add_u32_e32 v147, s52, v141
	s_cselect_b32 s41, s5, s21
	s_cselect_b32 s40, s19, s20
	s_add_i32 s54, 0, 0x14000
	ds_read_b128 v[152:155], v147
	ds_read_b128 v[164:167], v147 offset:1024
	ds_read_b128 v[180:183], v147 offset:2048
	ds_read_b128 v[184:187], v147 offset:3072
	v_add_u32_e32 v147, s54, v141
	ds_read_b128 v[188:191], v147
	ds_read_b128 v[192:195], v147 offset:1024
	ds_read_b128 v[196:199], v147 offset:2048
	ds_read_b128 v[200:203], v147 offset:3072
	v_lshl_add_u64 v[160:161], s[22:23], 0, v[136:137]
	s_add_i32 m0, s45, 0xc000
	ds_read_b128 v[204:207], v145
	ds_read_b128 v[208:211], v145 offset:1024
	ds_read_b128 v[212:215], v145 offset:2048
	ds_read_b128 v[216:219], v145 offset:3072
	ds_read_b128 v[220:223], v145 offset:4096
	ds_read_b128 v[224:227], v145 offset:5120
	ds_read_b128 v[228:231], v145 offset:6144
	ds_read_b128 v[232:235], v145 offset:7168
	global_load_lds_dwordx4 v[160:161], off
	s_add_i32 m0, s45, 0xe000
	v_lshl_add_u64 v[160:161], s[22:23], 0, v[138:139]
	global_load_lds_dwordx4 v[160:161], off
	s_nop 0
	s_waitcnt lgkmcnt(0)
	s_barrier
	s_setprio 1
	s_waitcnt lgkmcnt(0)
	v_mfma_f32_16x16x32_bf16 v[126:129], v[152:155], v[204:207], 0
	v_mfma_f32_16x16x32_bf16 v[122:125], v[180:183], v[204:207], 0
	v_mfma_f32_16x16x32_bf16 v[110:113], v[152:155], v[212:215], 0
	v_mfma_f32_16x16x32_bf16 v[106:109], v[180:183], v[212:215], 0
	v_mfma_f32_16x16x32_bf16 v[94:97], v[152:155], v[220:223], 0
	v_mfma_f32_16x16x32_bf16 v[90:93], v[180:183], v[220:223], 0
	v_mfma_f32_16x16x32_bf16 v[78:81], v[152:155], v[228:231], 0
	v_mfma_f32_16x16x32_bf16 v[74:77], v[180:183], v[228:231], 0
	v_mfma_f32_16x16x32_bf16 v[126:129], v[164:167], v[208:211], v[126:129]
	v_mfma_f32_16x16x32_bf16 v[122:125], v[184:187], v[208:211], v[122:125]
	v_mfma_f32_16x16x32_bf16 v[110:113], v[164:167], v[216:219], v[110:113]
	v_mfma_f32_16x16x32_bf16 v[106:109], v[184:187], v[216:219], v[106:109]
	v_mfma_f32_16x16x32_bf16 v[94:97], v[164:167], v[224:227], v[94:97]
	v_mfma_f32_16x16x32_bf16 v[90:93], v[184:187], v[224:227], v[90:93]
	v_mfma_f32_16x16x32_bf16 v[78:81], v[164:167], v[232:235], v[78:81]
	v_mfma_f32_16x16x32_bf16 v[74:77], v[184:187], v[232:235], v[74:77]
	s_setprio 0
	s_setprio 1
	v_mfma_f32_16x16x32_bf16 v[118:121], v[188:191], v[204:207], 0
	v_mfma_f32_16x16x32_bf16 v[114:117], v[196:199], v[204:207], 0
	v_mfma_f32_16x16x32_bf16 v[102:105], v[188:191], v[212:215], 0
	v_mfma_f32_16x16x32_bf16 v[98:101], v[196:199], v[212:215], 0
	v_mfma_f32_16x16x32_bf16 v[86:89], v[188:191], v[220:223], 0
	v_mfma_f32_16x16x32_bf16 v[82:85], v[196:199], v[220:223], 0
	v_mfma_f32_16x16x32_bf16 v[70:73], v[188:191], v[228:231], 0
	v_mfma_f32_16x16x32_bf16 v[66:69], v[196:199], v[228:231], 0
	v_mfma_f32_16x16x32_bf16 v[118:121], v[192:195], v[208:211], v[118:121]
	v_mfma_f32_16x16x32_bf16 v[114:117], v[200:203], v[208:211], v[114:117]
	v_mfma_f32_16x16x32_bf16 v[102:105], v[192:195], v[216:219], v[102:105]
	v_mfma_f32_16x16x32_bf16 v[98:101], v[200:203], v[216:219], v[98:101]
	v_mfma_f32_16x16x32_bf16 v[86:89], v[192:195], v[224:227], v[86:89]
	v_mfma_f32_16x16x32_bf16 v[82:85], v[200:203], v[224:227], v[82:85]
	s_setprio 2
	s_barrier
	v_mfma_f32_16x16x32_bf16 v[70:73], v[192:195], v[232:235], v[70:73]
	v_mfma_f32_16x16x32_bf16 v[66:69], v[200:203], v[232:235], v[66:69]
	s_setprio 0
	s_add_i32 s52, s52, s44
	v_lshl_add_u64 v[160:161], s[40:41], 0, v[162:163]
	s_mov_b32 m0, s52
	ds_read_b128 v[204:207], v145 offset:16384
	ds_read_b128 v[208:211], v145 offset:17408
	ds_read_b128 v[212:215], v145 offset:18432
	ds_read_b128 v[216:219], v145 offset:19456
	ds_read_b128 v[220:223], v145 offset:20480
	ds_read_b128 v[224:227], v145 offset:21504
	ds_read_b128 v[228:231], v145 offset:22528
	ds_read_b128 v[232:235], v145 offset:23552
	global_load_lds_dwordx4 v[160:161], off
	s_add_i32 m0, s52, 0x2000
	s_add_u32 s52, s40, 0x80000
	v_lshl_add_u64 v[168:169], s[40:41], 0, v[130:131]
	s_addc_u32 s53, s41, 0
	s_add_i32 s54, s54, s44
	global_load_lds_dwordx4 v[168:169], off
	v_lshl_add_u64 v[236:237], s[52:53], 0, v[162:163]
	s_mov_b32 m0, s54
	v_lshl_add_u64 v[238:239], s[42:43], 0, v[132:133]
	global_load_lds_dwordx4 v[236:237], off
	s_add_i32 m0, s54, 0x2000
	v_lshl_add_u64 v[236:237], s[52:53], 0, v[130:131]
	global_load_lds_dwordx4 v[236:237], off
	s_mov_b32 m0, s45
	v_lshl_add_u64 v[236:237], s[42:43], 0, v[134:135]
	global_load_lds_dwordx4 v[236:237], off
	s_mov_b32 m0, s46
	s_nop 0
	global_load_lds_dwordx4 v[238:239], off
	s_cmp_eq_u32 s51, 1
	s_cbranch_scc0 .Lg5_later_tile
	s_waitcnt vmcnt(8)
.Lg5_later_tile:
	s_waitcnt lgkmcnt(0)
	s_barrier
	s_setprio 1
	s_waitcnt lgkmcnt(0)
	v_mfma_f32_16x16x32_bf16 v[62:65], v[152:155], v[204:207], 0
	v_mfma_f32_16x16x32_bf16 v[58:61], v[180:183], v[204:207], 0
	v_mfma_f32_16x16x32_bf16 v[46:49], v[152:155], v[212:215], 0
	v_mfma_f32_16x16x32_bf16 v[42:45], v[180:183], v[212:215], 0
	v_mfma_f32_16x16x32_bf16 v[30:33], v[152:155], v[220:223], 0
	v_mfma_f32_16x16x32_bf16 v[26:29], v[180:183], v[220:223], 0
	v_mfma_f32_16x16x32_bf16 v[14:17], v[152:155], v[228:231], 0
	v_mfma_f32_16x16x32_bf16 v[10:13], v[180:183], v[228:231], 0
	v_mfma_f32_16x16x32_bf16 v[62:65], v[164:167], v[208:211], v[62:65]
	v_mfma_f32_16x16x32_bf16 v[58:61], v[184:187], v[208:211], v[58:61]
	v_mfma_f32_16x16x32_bf16 v[46:49], v[164:167], v[216:219], v[46:49]
	v_mfma_f32_16x16x32_bf16 v[42:45], v[184:187], v[216:219], v[42:45]
	v_mfma_f32_16x16x32_bf16 v[30:33], v[164:167], v[224:227], v[30:33]
	v_mfma_f32_16x16x32_bf16 v[26:29], v[184:187], v[224:227], v[26:29]
	v_mfma_f32_16x16x32_bf16 v[14:17], v[164:167], v[232:235], v[14:17]
	v_mfma_f32_16x16x32_bf16 v[10:13], v[184:187], v[232:235], v[10:13]
	s_setprio 0
	s_setprio 1
	v_mfma_f32_16x16x32_bf16 v[54:57], v[188:191], v[204:207], 0
	v_mfma_f32_16x16x32_bf16 v[50:53], v[196:199], v[204:207], 0
	v_mfma_f32_16x16x32_bf16 v[38:41], v[188:191], v[212:215], 0
	v_mfma_f32_16x16x32_bf16 v[34:37], v[196:199], v[212:215], 0
	v_mfma_f32_16x16x32_bf16 v[22:25], v[188:191], v[220:223], 0
	v_mfma_f32_16x16x32_bf16 v[18:21], v[196:199], v[220:223], 0
	v_mfma_f32_16x16x32_bf16 v[6:9], v[188:191], v[228:231], 0
	v_mfma_f32_16x16x32_bf16 v[2:5], v[196:199], v[228:231], 0
	v_mfma_f32_16x16x32_bf16 v[54:57], v[192:195], v[208:211], v[54:57]
	v_mfma_f32_16x16x32_bf16 v[50:53], v[200:203], v[208:211], v[50:53]
	v_mfma_f32_16x16x32_bf16 v[38:41], v[192:195], v[216:219], v[38:41]
	v_mfma_f32_16x16x32_bf16 v[34:37], v[200:203], v[216:219], v[34:37]
	v_mfma_f32_16x16x32_bf16 v[22:25], v[192:195], v[224:227], v[22:25]
	v_mfma_f32_16x16x32_bf16 v[18:21], v[200:203], v[224:227], v[18:21]
	s_setprio 2
	s_barrier
	v_mfma_f32_16x16x32_bf16 v[6:9], v[192:195], v[232:235], v[6:9]
	v_mfma_f32_16x16x32_bf16 v[2:5], v[200:203], v[232:235], v[2:5]
	s_setprio 0
	s_add_i32 s52, 0, 0x18000
	v_add_u32_e32 v147, s52, v141
	s_add_i32 s53, 0, 0x1c000
	ds_read_b128 v[152:155], v147
	ds_read_b128 v[164:167], v147 offset:1024
	ds_read_b128 v[180:183], v147 offset:2048
	ds_read_b128 v[184:187], v147 offset:3072
	v_add_u32_e32 v147, s53, v141
	ds_read_b128 v[188:191], v147
	ds_read_b128 v[192:195], v147 offset:1024
	ds_read_b128 v[196:199], v147 offset:2048
	ds_read_b128 v[200:203], v147 offset:3072
	s_add_u32 s42, s42, 0x80000
	s_addc_u32 s43, s43, 0
	s_mov_b32 m0, s47
	v_lshl_add_u64 v[240:241], s[42:43], 0, v[134:135]
	ds_read_b128 v[204:207], v145 offset:32768
	ds_read_b128 v[208:211], v145 offset:33792
	ds_read_b128 v[212:215], v145 offset:34816
	ds_read_b128 v[216:219], v145 offset:35840
	ds_read_b128 v[220:223], v145 offset:36864
	ds_read_b128 v[224:227], v145 offset:37888
	ds_read_b128 v[228:231], v145 offset:38912
	ds_read_b128 v[232:235], v145 offset:39936
	global_load_lds_dwordx4 v[240:241], off
	s_mov_b32 m0, s48
	v_lshl_add_u64 v[240:241], s[42:43], 0, v[132:133]
	global_load_lds_dwordx4 v[240:241], off
	s_waitcnt vmcnt(8)
	s_waitcnt lgkmcnt(0)
	s_barrier
	s_setprio 1
	s_waitcnt lgkmcnt(0)
	v_mfma_f32_16x16x32_bf16 v[126:129], v[152:155], v[204:207], v[126:129]
	v_mfma_f32_16x16x32_bf16 v[122:125], v[180:183], v[204:207], v[122:125]
	v_mfma_f32_16x16x32_bf16 v[110:113], v[152:155], v[212:215], v[110:113]
	v_mfma_f32_16x16x32_bf16 v[106:109], v[180:183], v[212:215], v[106:109]
	v_mfma_f32_16x16x32_bf16 v[94:97], v[152:155], v[220:223], v[94:97]
	v_mfma_f32_16x16x32_bf16 v[90:93], v[180:183], v[220:223], v[90:93]
	v_mfma_f32_16x16x32_bf16 v[78:81], v[152:155], v[228:231], v[78:81]
	v_mfma_f32_16x16x32_bf16 v[74:77], v[180:183], v[228:231], v[74:77]
	v_mfma_f32_16x16x32_bf16 v[126:129], v[164:167], v[208:211], v[126:129]
	v_mfma_f32_16x16x32_bf16 v[122:125], v[184:187], v[208:211], v[122:125]
	v_mfma_f32_16x16x32_bf16 v[110:113], v[164:167], v[216:219], v[110:113]
	v_mfma_f32_16x16x32_bf16 v[106:109], v[184:187], v[216:219], v[106:109]
	v_mfma_f32_16x16x32_bf16 v[94:97], v[164:167], v[224:227], v[94:97]
	v_mfma_f32_16x16x32_bf16 v[90:93], v[184:187], v[224:227], v[90:93]
	v_mfma_f32_16x16x32_bf16 v[78:81], v[164:167], v[232:235], v[78:81]
	v_mfma_f32_16x16x32_bf16 v[74:77], v[184:187], v[232:235], v[74:77]
	s_setprio 0
	s_setprio 1
	v_mfma_f32_16x16x32_bf16 v[118:121], v[188:191], v[204:207], v[118:121]
	v_mfma_f32_16x16x32_bf16 v[114:117], v[196:199], v[204:207], v[114:117]
	v_mfma_f32_16x16x32_bf16 v[102:105], v[188:191], v[212:215], v[102:105]
	v_mfma_f32_16x16x32_bf16 v[98:101], v[196:199], v[212:215], v[98:101]
	v_mfma_f32_16x16x32_bf16 v[86:89], v[188:191], v[220:223], v[86:89]
	v_mfma_f32_16x16x32_bf16 v[82:85], v[196:199], v[220:223], v[82:85]
	v_mfma_f32_16x16x32_bf16 v[70:73], v[188:191], v[228:231], v[70:73]
	v_mfma_f32_16x16x32_bf16 v[66:69], v[196:199], v[228:231], v[66:69]
	v_mfma_f32_16x16x32_bf16 v[118:121], v[192:195], v[208:211], v[118:121]
	v_mfma_f32_16x16x32_bf16 v[114:117], v[200:203], v[208:211], v[114:117]
	v_mfma_f32_16x16x32_bf16 v[102:105], v[192:195], v[216:219], v[102:105]
	v_mfma_f32_16x16x32_bf16 v[98:101], v[200:203], v[216:219], v[98:101]
	v_mfma_f32_16x16x32_bf16 v[86:89], v[192:195], v[224:227], v[86:89]
	v_mfma_f32_16x16x32_bf16 v[82:85], v[200:203], v[224:227], v[82:85]
	s_setprio 2
	s_barrier
	v_mfma_f32_16x16x32_bf16 v[70:73], v[192:195], v[232:235], v[70:73]
	v_mfma_f32_16x16x32_bf16 v[66:69], v[200:203], v[232:235], v[66:69]
	s_setprio 0
	s_add_i32 s42, s52, s44
	v_lshl_add_u64 v[160:161], v[160:161], 0, s[6:7]
	s_mov_b32 m0, s42
	ds_read_b128 v[204:207], v145 offset:49152
	ds_read_b128 v[208:211], v145 offset:50176
	ds_read_b128 v[212:215], v145 offset:51200
	ds_read_b128 v[216:219], v145 offset:52224
	ds_read_b128 v[220:223], v145 offset:53248
	ds_read_b128 v[224:227], v145 offset:54272
	ds_read_b128 v[228:231], v145 offset:55296
	ds_read_b128 v[232:235], v145 offset:56320
	global_load_lds_dwordx4 v[160:161], off
	s_add_i32 m0, s42, 0x2000
	s_add_u32 s40, s40, 0x80080
	v_lshl_add_u64 v[160:161], v[168:169], 0, s[6:7]
	s_addc_u32 s41, s41, 0
	s_add_i32 s42, s53, s44
	global_load_lds_dwordx4 v[160:161], off
	s_mov_b32 m0, s42
	v_lshl_add_u64 v[160:161], s[40:41], 0, v[162:163]
	global_load_lds_dwordx4 v[160:161], off
	s_add_i32 m0, s42, 0x2000
	v_lshl_add_u64 v[160:161], s[40:41], 0, v[130:131]
	global_load_lds_dwordx4 v[160:161], off
	s_mov_b32 m0, s49
	v_lshl_add_u64 v[160:161], v[236:237], 0, s[6:7]
	global_load_lds_dwordx4 v[160:161], off
	s_mov_b32 m0, s50
	v_lshl_add_u64 v[160:161], v[238:239], 0, s[6:7]
	global_load_lds_dwordx4 v[160:161], off
	s_waitcnt vmcnt(8)
	s_waitcnt lgkmcnt(0)
	s_barrier
	s_setprio 1
	s_waitcnt lgkmcnt(0)
	v_mfma_f32_16x16x32_bf16 v[62:65], v[152:155], v[204:207], v[62:65]
	v_mfma_f32_16x16x32_bf16 v[58:61], v[180:183], v[204:207], v[58:61]
	v_mfma_f32_16x16x32_bf16 v[46:49], v[152:155], v[212:215], v[46:49]
	v_mfma_f32_16x16x32_bf16 v[42:45], v[180:183], v[212:215], v[42:45]
	v_mfma_f32_16x16x32_bf16 v[30:33], v[152:155], v[220:223], v[30:33]
	v_mfma_f32_16x16x32_bf16 v[26:29], v[180:183], v[220:223], v[26:29]
	v_mfma_f32_16x16x32_bf16 v[14:17], v[152:155], v[228:231], v[14:17]
	v_mfma_f32_16x16x32_bf16 v[10:13], v[180:183], v[228:231], v[10:13]
	v_mfma_f32_16x16x32_bf16 v[62:65], v[164:167], v[208:211], v[62:65]
	v_mfma_f32_16x16x32_bf16 v[58:61], v[184:187], v[208:211], v[58:61]
	v_mfma_f32_16x16x32_bf16 v[46:49], v[164:167], v[216:219], v[46:49]
	v_mfma_f32_16x16x32_bf16 v[42:45], v[184:187], v[216:219], v[42:45]
	v_mfma_f32_16x16x32_bf16 v[30:33], v[164:167], v[224:227], v[30:33]
	v_mfma_f32_16x16x32_bf16 v[26:29], v[184:187], v[224:227], v[26:29]
	v_mfma_f32_16x16x32_bf16 v[14:17], v[164:167], v[232:235], v[14:17]
	v_mfma_f32_16x16x32_bf16 v[10:13], v[184:187], v[232:235], v[10:13]
	s_setprio 0
	s_setprio 1
	v_mfma_f32_16x16x32_bf16 v[54:57], v[188:191], v[204:207], v[54:57]
	v_mfma_f32_16x16x32_bf16 v[50:53], v[196:199], v[204:207], v[50:53]
	v_mfma_f32_16x16x32_bf16 v[38:41], v[188:191], v[212:215], v[38:41]
	v_mfma_f32_16x16x32_bf16 v[34:37], v[196:199], v[212:215], v[34:37]
	v_mfma_f32_16x16x32_bf16 v[22:25], v[188:191], v[220:223], v[22:25]
	v_mfma_f32_16x16x32_bf16 v[18:21], v[196:199], v[220:223], v[18:21]
	v_mfma_f32_16x16x32_bf16 v[6:9], v[188:191], v[228:231], v[6:9]
	v_mfma_f32_16x16x32_bf16 v[2:5], v[196:199], v[228:231], v[2:5]
	v_mfma_f32_16x16x32_bf16 v[54:57], v[192:195], v[208:211], v[54:57]
	v_mfma_f32_16x16x32_bf16 v[50:53], v[200:203], v[208:211], v[50:53]
	v_mfma_f32_16x16x32_bf16 v[38:41], v[192:195], v[216:219], v[38:41]
	v_mfma_f32_16x16x32_bf16 v[34:37], v[200:203], v[216:219], v[34:37]
	v_mfma_f32_16x16x32_bf16 v[22:25], v[192:195], v[224:227], v[22:25]
	v_mfma_f32_16x16x32_bf16 v[18:21], v[200:203], v[224:227], v[18:21]
	s_setprio 2
	s_barrier
	v_mfma_f32_16x16x32_bf16 v[6:9], v[192:195], v[232:235], v[6:9]
	v_mfma_f32_16x16x32_bf16 v[2:5], v[200:203], v[232:235], v[2:5]
	s_setprio 0
	s_add_i32 s26, s26, 2
	s_add_u32 s22, s22, 0x100
	s_addc_u32 s23, s23, 0
	s_add_u32 s20, s20, 0x100
	s_addc_u32 s21, s21, 0
	s_cmp_gt_u32 s26, 29
.LBB0_1798:
	s_add_u32 s40, s22, 0xfff80080
	s_addc_u32 s41, s23, -1
	s_add_i32 s52, 0, 0x10000
	s_cmp_eq_u32 s26, 28
	s_cselect_b32 s43, s11, s41
	s_cselect_b32 s42, s13, s40
	v_add_u32_e32 v147, s52, v141
	s_cselect_b32 s41, s5, s21
	s_cselect_b32 s40, s19, s20
	s_add_i32 s54, 0, 0x14000
	ds_read_b128 v[152:155], v147
	ds_read_b128 v[164:167], v147 offset:1024
	ds_read_b128 v[180:183], v147 offset:2048
	ds_read_b128 v[184:187], v147 offset:3072
	v_add_u32_e32 v147, s54, v141
	ds_read_b128 v[188:191], v147
	ds_read_b128 v[192:195], v147 offset:1024
	ds_read_b128 v[196:199], v147 offset:2048
	ds_read_b128 v[200:203], v147 offset:3072
	v_lshl_add_u64 v[160:161], s[22:23], 0, v[136:137]
	s_add_i32 m0, s45, 0xc000
	ds_read_b128 v[204:207], v145
	ds_read_b128 v[208:211], v145 offset:1024
	ds_read_b128 v[212:215], v145 offset:2048
	ds_read_b128 v[216:219], v145 offset:3072
	ds_read_b128 v[220:223], v145 offset:4096
	ds_read_b128 v[224:227], v145 offset:5120
	ds_read_b128 v[228:231], v145 offset:6144
	ds_read_b128 v[232:235], v145 offset:7168
	global_load_lds_dwordx4 v[160:161], off
	s_add_i32 m0, s45, 0xe000
	v_lshl_add_u64 v[160:161], s[22:23], 0, v[138:139]
	global_load_lds_dwordx4 v[160:161], off
	s_waitcnt vmcnt(8)
	s_waitcnt lgkmcnt(0)
	s_barrier
	s_setprio 1
	s_waitcnt lgkmcnt(0)
	v_mfma_f32_16x16x32_bf16 v[126:129], v[152:155], v[204:207], v[126:129]
	v_mfma_f32_16x16x32_bf16 v[122:125], v[180:183], v[204:207], v[122:125]
	v_mfma_f32_16x16x32_bf16 v[110:113], v[152:155], v[212:215], v[110:113]
	v_mfma_f32_16x16x32_bf16 v[106:109], v[180:183], v[212:215], v[106:109]
	v_mfma_f32_16x16x32_bf16 v[94:97], v[152:155], v[220:223], v[94:97]
	v_mfma_f32_16x16x32_bf16 v[90:93], v[180:183], v[220:223], v[90:93]
	v_mfma_f32_16x16x32_bf16 v[78:81], v[152:155], v[228:231], v[78:81]
	v_mfma_f32_16x16x32_bf16 v[74:77], v[180:183], v[228:231], v[74:77]
	v_mfma_f32_16x16x32_bf16 v[126:129], v[164:167], v[208:211], v[126:129]
	v_mfma_f32_16x16x32_bf16 v[122:125], v[184:187], v[208:211], v[122:125]
	v_mfma_f32_16x16x32_bf16 v[110:113], v[164:167], v[216:219], v[110:113]
	v_mfma_f32_16x16x32_bf16 v[106:109], v[184:187], v[216:219], v[106:109]
	v_mfma_f32_16x16x32_bf16 v[94:97], v[164:167], v[224:227], v[94:97]
	v_mfma_f32_16x16x32_bf16 v[90:93], v[184:187], v[224:227], v[90:93]
	v_mfma_f32_16x16x32_bf16 v[78:81], v[164:167], v[232:235], v[78:81]
	v_mfma_f32_16x16x32_bf16 v[74:77], v[184:187], v[232:235], v[74:77]
	s_setprio 0
	s_setprio 1
	v_mfma_f32_16x16x32_bf16 v[118:121], v[188:191], v[204:207], v[118:121]
	v_mfma_f32_16x16x32_bf16 v[114:117], v[196:199], v[204:207], v[114:117]
	v_mfma_f32_16x16x32_bf16 v[102:105], v[188:191], v[212:215], v[102:105]
	v_mfma_f32_16x16x32_bf16 v[98:101], v[196:199], v[212:215], v[98:101]
	v_mfma_f32_16x16x32_bf16 v[86:89], v[188:191], v[220:223], v[86:89]
	v_mfma_f32_16x16x32_bf16 v[82:85], v[196:199], v[220:223], v[82:85]
	v_mfma_f32_16x16x32_bf16 v[70:73], v[188:191], v[228:231], v[70:73]
	v_mfma_f32_16x16x32_bf16 v[66:69], v[196:199], v[228:231], v[66:69]
	v_mfma_f32_16x16x32_bf16 v[118:121], v[192:195], v[208:211], v[118:121]
	v_mfma_f32_16x16x32_bf16 v[114:117], v[200:203], v[208:211], v[114:117]
	v_mfma_f32_16x16x32_bf16 v[102:105], v[192:195], v[216:219], v[102:105]
	v_mfma_f32_16x16x32_bf16 v[98:101], v[200:203], v[216:219], v[98:101]
	v_mfma_f32_16x16x32_bf16 v[86:89], v[192:195], v[224:227], v[86:89]
	v_mfma_f32_16x16x32_bf16 v[82:85], v[200:203], v[224:227], v[82:85]
	s_setprio 2
	s_barrier
	v_mfma_f32_16x16x32_bf16 v[70:73], v[192:195], v[232:235], v[70:73]
	v_mfma_f32_16x16x32_bf16 v[66:69], v[200:203], v[232:235], v[66:69]
	s_setprio 0
	s_add_i32 s52, s52, s44
	v_lshl_add_u64 v[160:161], s[40:41], 0, v[162:163]
	s_mov_b32 m0, s52
	ds_read_b128 v[204:207], v145 offset:16384
	ds_read_b128 v[208:211], v145 offset:17408
	ds_read_b128 v[212:215], v145 offset:18432
	ds_read_b128 v[216:219], v145 offset:19456
	ds_read_b128 v[220:223], v145 offset:20480
	ds_read_b128 v[224:227], v145 offset:21504
	ds_read_b128 v[228:231], v145 offset:22528
	ds_read_b128 v[232:235], v145 offset:23552
	global_load_lds_dwordx4 v[160:161], off
	s_add_i32 m0, s52, 0x2000
	s_add_u32 s52, s40, 0x80000
	v_lshl_add_u64 v[168:169], s[40:41], 0, v[130:131]
	s_addc_u32 s53, s41, 0
	s_add_i32 s54, s54, s44
	global_load_lds_dwordx4 v[168:169], off
	v_lshl_add_u64 v[236:237], s[52:53], 0, v[162:163]
	s_mov_b32 m0, s54
	v_lshl_add_u64 v[238:239], s[42:43], 0, v[132:133]
	global_load_lds_dwordx4 v[236:237], off
	s_add_i32 m0, s54, 0x2000
	v_lshl_add_u64 v[236:237], s[52:53], 0, v[130:131]
	global_load_lds_dwordx4 v[236:237], off
	s_mov_b32 m0, s45
	v_lshl_add_u64 v[236:237], s[42:43], 0, v[134:135]
	global_load_lds_dwordx4 v[236:237], off
	s_mov_b32 m0, s46
	s_nop 0
	global_load_lds_dwordx4 v[238:239], off
	s_waitcnt vmcnt(8)
	s_waitcnt lgkmcnt(0)
	s_barrier
	s_setprio 1
	s_waitcnt lgkmcnt(0)
	v_mfma_f32_16x16x32_bf16 v[62:65], v[152:155], v[204:207], v[62:65]
	v_mfma_f32_16x16x32_bf16 v[58:61], v[180:183], v[204:207], v[58:61]
	v_mfma_f32_16x16x32_bf16 v[46:49], v[152:155], v[212:215], v[46:49]
	v_mfma_f32_16x16x32_bf16 v[42:45], v[180:183], v[212:215], v[42:45]
	v_mfma_f32_16x16x32_bf16 v[30:33], v[152:155], v[220:223], v[30:33]
	v_mfma_f32_16x16x32_bf16 v[26:29], v[180:183], v[220:223], v[26:29]
	v_mfma_f32_16x16x32_bf16 v[14:17], v[152:155], v[228:231], v[14:17]
	v_mfma_f32_16x16x32_bf16 v[10:13], v[180:183], v[228:231], v[10:13]
	v_mfma_f32_16x16x32_bf16 v[62:65], v[164:167], v[208:211], v[62:65]
	v_mfma_f32_16x16x32_bf16 v[58:61], v[184:187], v[208:211], v[58:61]
	v_mfma_f32_16x16x32_bf16 v[46:49], v[164:167], v[216:219], v[46:49]
	v_mfma_f32_16x16x32_bf16 v[42:45], v[184:187], v[216:219], v[42:45]
	v_mfma_f32_16x16x32_bf16 v[30:33], v[164:167], v[224:227], v[30:33]
	v_mfma_f32_16x16x32_bf16 v[26:29], v[184:187], v[224:227], v[26:29]
	v_mfma_f32_16x16x32_bf16 v[14:17], v[164:167], v[232:235], v[14:17]
	v_mfma_f32_16x16x32_bf16 v[10:13], v[184:187], v[232:235], v[10:13]
	s_setprio 0
	s_setprio 1
	v_mfma_f32_16x16x32_bf16 v[54:57], v[188:191], v[204:207], v[54:57]
	v_mfma_f32_16x16x32_bf16 v[50:53], v[196:199], v[204:207], v[50:53]
	v_mfma_f32_16x16x32_bf16 v[38:41], v[188:191], v[212:215], v[38:41]
	v_mfma_f32_16x16x32_bf16 v[34:37], v[196:199], v[212:215], v[34:37]
	v_mfma_f32_16x16x32_bf16 v[22:25], v[188:191], v[220:223], v[22:25]
	v_mfma_f32_16x16x32_bf16 v[18:21], v[196:199], v[220:223], v[18:21]
	v_mfma_f32_16x16x32_bf16 v[6:9], v[188:191], v[228:231], v[6:9]
	v_mfma_f32_16x16x32_bf16 v[2:5], v[196:199], v[228:231], v[2:5]
	v_mfma_f32_16x16x32_bf16 v[54:57], v[192:195], v[208:211], v[54:57]
	v_mfma_f32_16x16x32_bf16 v[50:53], v[200:203], v[208:211], v[50:53]
	v_mfma_f32_16x16x32_bf16 v[38:41], v[192:195], v[216:219], v[38:41]
	v_mfma_f32_16x16x32_bf16 v[34:37], v[200:203], v[216:219], v[34:37]
	v_mfma_f32_16x16x32_bf16 v[22:25], v[192:195], v[224:227], v[22:25]
	v_mfma_f32_16x16x32_bf16 v[18:21], v[200:203], v[224:227], v[18:21]
	s_setprio 2
	s_barrier
	v_mfma_f32_16x16x32_bf16 v[6:9], v[192:195], v[232:235], v[6:9]
	v_mfma_f32_16x16x32_bf16 v[2:5], v[200:203], v[232:235], v[2:5]
	s_setprio 0
	s_add_i32 s52, 0, 0x18000
	v_add_u32_e32 v147, s52, v141
	s_add_i32 s53, 0, 0x1c000
	ds_read_b128 v[152:155], v147
	ds_read_b128 v[164:167], v147 offset:1024
	ds_read_b128 v[180:183], v147 offset:2048
	ds_read_b128 v[184:187], v147 offset:3072
	v_add_u32_e32 v147, s53, v141
	ds_read_b128 v[188:191], v147
	ds_read_b128 v[192:195], v147 offset:1024
	ds_read_b128 v[196:199], v147 offset:2048
	ds_read_b128 v[200:203], v147 offset:3072
	s_add_u32 s42, s42, 0x80000
	s_addc_u32 s43, s43, 0
	s_mov_b32 m0, s47
	v_lshl_add_u64 v[240:241], s[42:43], 0, v[134:135]
	ds_read_b128 v[204:207], v145 offset:32768
	ds_read_b128 v[208:211], v145 offset:33792
	ds_read_b128 v[212:215], v145 offset:34816
	ds_read_b128 v[216:219], v145 offset:35840
	ds_read_b128 v[220:223], v145 offset:36864
	ds_read_b128 v[224:227], v145 offset:37888
	ds_read_b128 v[228:231], v145 offset:38912
	ds_read_b128 v[232:235], v145 offset:39936
	global_load_lds_dwordx4 v[240:241], off
	s_mov_b32 m0, s48
	v_lshl_add_u64 v[240:241], s[42:43], 0, v[132:133]
	global_load_lds_dwordx4 v[240:241], off
	s_waitcnt vmcnt(8)
	s_waitcnt lgkmcnt(0)
	s_barrier
	s_setprio 1
	s_waitcnt lgkmcnt(0)
	v_mfma_f32_16x16x32_bf16 v[126:129], v[152:155], v[204:207], v[126:129]
	v_mfma_f32_16x16x32_bf16 v[122:125], v[180:183], v[204:207], v[122:125]
	v_mfma_f32_16x16x32_bf16 v[110:113], v[152:155], v[212:215], v[110:113]
	v_mfma_f32_16x16x32_bf16 v[106:109], v[180:183], v[212:215], v[106:109]
	v_mfma_f32_16x16x32_bf16 v[94:97], v[152:155], v[220:223], v[94:97]
	v_mfma_f32_16x16x32_bf16 v[90:93], v[180:183], v[220:223], v[90:93]
	v_mfma_f32_16x16x32_bf16 v[78:81], v[152:155], v[228:231], v[78:81]
	v_mfma_f32_16x16x32_bf16 v[74:77], v[180:183], v[228:231], v[74:77]
	v_mfma_f32_16x16x32_bf16 v[126:129], v[164:167], v[208:211], v[126:129]
	v_mfma_f32_16x16x32_bf16 v[122:125], v[184:187], v[208:211], v[122:125]
	v_mfma_f32_16x16x32_bf16 v[110:113], v[164:167], v[216:219], v[110:113]
	v_mfma_f32_16x16x32_bf16 v[106:109], v[184:187], v[216:219], v[106:109]
	v_mfma_f32_16x16x32_bf16 v[94:97], v[164:167], v[224:227], v[94:97]
	v_mfma_f32_16x16x32_bf16 v[90:93], v[184:187], v[224:227], v[90:93]
	v_mfma_f32_16x16x32_bf16 v[78:81], v[164:167], v[232:235], v[78:81]
	v_mfma_f32_16x16x32_bf16 v[74:77], v[184:187], v[232:235], v[74:77]
	s_setprio 0
	s_setprio 1
	v_mfma_f32_16x16x32_bf16 v[118:121], v[188:191], v[204:207], v[118:121]
	v_mfma_f32_16x16x32_bf16 v[114:117], v[196:199], v[204:207], v[114:117]
	v_mfma_f32_16x16x32_bf16 v[102:105], v[188:191], v[212:215], v[102:105]
	v_mfma_f32_16x16x32_bf16 v[98:101], v[196:199], v[212:215], v[98:101]
	v_mfma_f32_16x16x32_bf16 v[86:89], v[188:191], v[220:223], v[86:89]
	v_mfma_f32_16x16x32_bf16 v[82:85], v[196:199], v[220:223], v[82:85]
	v_mfma_f32_16x16x32_bf16 v[70:73], v[188:191], v[228:231], v[70:73]
	v_mfma_f32_16x16x32_bf16 v[66:69], v[196:199], v[228:231], v[66:69]
	v_mfma_f32_16x16x32_bf16 v[118:121], v[192:195], v[208:211], v[118:121]
	v_mfma_f32_16x16x32_bf16 v[114:117], v[200:203], v[208:211], v[114:117]
	v_mfma_f32_16x16x32_bf16 v[102:105], v[192:195], v[216:219], v[102:105]
	v_mfma_f32_16x16x32_bf16 v[98:101], v[200:203], v[216:219], v[98:101]
	v_mfma_f32_16x16x32_bf16 v[86:89], v[192:195], v[224:227], v[86:89]
	v_mfma_f32_16x16x32_bf16 v[82:85], v[200:203], v[224:227], v[82:85]
	s_setprio 2
	s_barrier
	v_mfma_f32_16x16x32_bf16 v[70:73], v[192:195], v[232:235], v[70:73]
	v_mfma_f32_16x16x32_bf16 v[66:69], v[200:203], v[232:235], v[66:69]
	s_setprio 0
	s_add_i32 s42, s52, s44
	v_lshl_add_u64 v[160:161], v[160:161], 0, s[6:7]
	s_mov_b32 m0, s42
	ds_read_b128 v[204:207], v145 offset:49152
	ds_read_b128 v[208:211], v145 offset:50176
	ds_read_b128 v[212:215], v145 offset:51200
	ds_read_b128 v[216:219], v145 offset:52224
	ds_read_b128 v[220:223], v145 offset:53248
	ds_read_b128 v[224:227], v145 offset:54272
	ds_read_b128 v[228:231], v145 offset:55296
	ds_read_b128 v[232:235], v145 offset:56320
	global_load_lds_dwordx4 v[160:161], off
	s_add_i32 m0, s42, 0x2000
	s_add_u32 s40, s40, 0x80080
	v_lshl_add_u64 v[160:161], v[168:169], 0, s[6:7]
	s_addc_u32 s41, s41, 0
	s_add_i32 s42, s53, s44
	global_load_lds_dwordx4 v[160:161], off
	s_mov_b32 m0, s42
	v_lshl_add_u64 v[160:161], s[40:41], 0, v[162:163]
	global_load_lds_dwordx4 v[160:161], off
	s_add_i32 m0, s42, 0x2000
	v_lshl_add_u64 v[160:161], s[40:41], 0, v[130:131]
	global_load_lds_dwordx4 v[160:161], off
	s_mov_b32 m0, s49
	v_lshl_add_u64 v[160:161], v[236:237], 0, s[6:7]
	global_load_lds_dwordx4 v[160:161], off
	s_mov_b32 m0, s50
	v_lshl_add_u64 v[160:161], v[238:239], 0, s[6:7]
	global_load_lds_dwordx4 v[160:161], off
	s_waitcnt vmcnt(8)
	s_waitcnt lgkmcnt(0)
	s_barrier
	s_setprio 1
	s_waitcnt lgkmcnt(0)
	v_mfma_f32_16x16x32_bf16 v[62:65], v[152:155], v[204:207], v[62:65]
	v_mfma_f32_16x16x32_bf16 v[58:61], v[180:183], v[204:207], v[58:61]
	v_mfma_f32_16x16x32_bf16 v[46:49], v[152:155], v[212:215], v[46:49]
	v_mfma_f32_16x16x32_bf16 v[42:45], v[180:183], v[212:215], v[42:45]
	v_mfma_f32_16x16x32_bf16 v[30:33], v[152:155], v[220:223], v[30:33]
	v_mfma_f32_16x16x32_bf16 v[26:29], v[180:183], v[220:223], v[26:29]
	v_mfma_f32_16x16x32_bf16 v[14:17], v[152:155], v[228:231], v[14:17]
	v_mfma_f32_16x16x32_bf16 v[10:13], v[180:183], v[228:231], v[10:13]
	v_mfma_f32_16x16x32_bf16 v[62:65], v[164:167], v[208:211], v[62:65]
	v_mfma_f32_16x16x32_bf16 v[58:61], v[184:187], v[208:211], v[58:61]
	v_mfma_f32_16x16x32_bf16 v[46:49], v[164:167], v[216:219], v[46:49]
	v_mfma_f32_16x16x32_bf16 v[42:45], v[184:187], v[216:219], v[42:45]
	v_mfma_f32_16x16x32_bf16 v[30:33], v[164:167], v[224:227], v[30:33]
	v_mfma_f32_16x16x32_bf16 v[26:29], v[184:187], v[224:227], v[26:29]
	v_mfma_f32_16x16x32_bf16 v[14:17], v[164:167], v[232:235], v[14:17]
	v_mfma_f32_16x16x32_bf16 v[10:13], v[184:187], v[232:235], v[10:13]
	s_setprio 0
	s_setprio 1
	v_mfma_f32_16x16x32_bf16 v[54:57], v[188:191], v[204:207], v[54:57]
	v_mfma_f32_16x16x32_bf16 v[50:53], v[196:199], v[204:207], v[50:53]
	v_mfma_f32_16x16x32_bf16 v[38:41], v[188:191], v[212:215], v[38:41]
	v_mfma_f32_16x16x32_bf16 v[34:37], v[196:199], v[212:215], v[34:37]
	v_mfma_f32_16x16x32_bf16 v[22:25], v[188:191], v[220:223], v[22:25]
	v_mfma_f32_16x16x32_bf16 v[18:21], v[196:199], v[220:223], v[18:21]
	v_mfma_f32_16x16x32_bf16 v[6:9], v[188:191], v[228:231], v[6:9]
	v_mfma_f32_16x16x32_bf16 v[2:5], v[196:199], v[228:231], v[2:5]
	v_mfma_f32_16x16x32_bf16 v[54:57], v[192:195], v[208:211], v[54:57]
	v_mfma_f32_16x16x32_bf16 v[50:53], v[200:203], v[208:211], v[50:53]
	v_mfma_f32_16x16x32_bf16 v[38:41], v[192:195], v[216:219], v[38:41]
	v_mfma_f32_16x16x32_bf16 v[34:37], v[200:203], v[216:219], v[34:37]
	v_mfma_f32_16x16x32_bf16 v[22:25], v[192:195], v[224:227], v[22:25]
	v_mfma_f32_16x16x32_bf16 v[18:21], v[200:203], v[224:227], v[18:21]
	s_setprio 2
	s_barrier
	v_mfma_f32_16x16x32_bf16 v[6:9], v[192:195], v[232:235], v[6:9]
	v_mfma_f32_16x16x32_bf16 v[2:5], v[200:203], v[232:235], v[2:5]
	s_setprio 0
	s_add_i32 s26, s26, 2
	s_add_u32 s22, s22, 0x100
	s_addc_u32 s23, s23, 0
	s_add_u32 s20, s20, 0x100
	s_addc_u32 s21, s21, 0
	s_cmp_gt_u32 s26, 29
	s_cbranch_scc0 .LBB0_1798
	s_and_b64 vcc, exec, s[2:3]
	s_cbranch_vccz .LBB0_1801
	s_barrier

.LBB0_1873:
	s_add_u32 s45, s28, 0x100
	s_addc_u32 s46, s29, 0
	s_mov_b32 s47, -2
	s_waitcnt vmcnt(0) lgkmcnt(0)
	s_add_u32 s28, s22, 0x100
	s_addc_u32 s29, s23, 0
	s_add_i32 s48, 0, 0x10000
	s_cmpk_eq_i32 s47, 0x54
	s_cselect_b32 s39, s5, s29
	s_cselect_b32 s38, s4, s28
	v_add_u32_e32 v154, s48, v145
	s_cselect_b32 s35, s19, s46
	s_cselect_b32 s34, s18, s45
	s_add_i32 s49, 0, 0x14000
	ds_read_b128 v[130:133], v154
	ds_read_b128 v[134:137], v154 offset:1024
	ds_read_b128 v[150:153], v154 offset:2048
	ds_read_b128 v[158:161], v154 offset:3072
	v_add_u32_e32 v154, s49, v145
	ds_read_b128 v[164:167], v154
	ds_read_b128 v[180:183], v154 offset:1024
	ds_read_b128 v[184:187], v154 offset:2048
	ds_read_b128 v[188:191], v154 offset:3072
	v_lshl_add_u64 v[154:155], s[22:23], 0, v[146:147]
	s_add_i32 m0, s20, 0xc000
	ds_read_b128 v[192:195], v157
	ds_read_b128 v[196:199], v157 offset:1024
	ds_read_b128 v[200:203], v157 offset:2048
	ds_read_b128 v[204:207], v157 offset:3072
	ds_read_b128 v[208:211], v157 offset:4096
	ds_read_b128 v[212:215], v157 offset:5120
	ds_read_b128 v[216:219], v157 offset:6144
	ds_read_b128 v[220:223], v157 offset:7168
	global_load_lds_dwordx4 v[154:155], off
	s_add_i32 m0, s20, 0xe000
	v_lshl_add_u64 v[154:155], s[22:23], 0, v[148:149]
	global_load_lds_dwordx4 v[154:155], off
	s_waitcnt vmcnt(8)
	s_waitcnt lgkmcnt(0)
	s_barrier
	s_setprio 1
	s_waitcnt lgkmcnt(0)
	v_mfma_f32_16x16x32_bf16 v[126:129], v[130:133], v[192:195], 0
	v_mfma_f32_16x16x32_bf16 v[122:125], v[150:153], v[192:195], 0
	v_mfma_f32_16x16x32_bf16 v[110:113], v[130:133], v[200:203], 0
	v_mfma_f32_16x16x32_bf16 v[106:109], v[150:153], v[200:203], 0
	v_mfma_f32_16x16x32_bf16 v[94:97], v[130:133], v[208:211], 0
	v_mfma_f32_16x16x32_bf16 v[90:93], v[150:153], v[208:211], 0
	v_mfma_f32_16x16x32_bf16 v[78:81], v[130:133], v[216:219], 0
	v_mfma_f32_16x16x32_bf16 v[74:77], v[150:153], v[216:219], 0
	v_mfma_f32_16x16x32_bf16 v[126:129], v[134:137], v[196:199], v[126:129]
	v_mfma_f32_16x16x32_bf16 v[122:125], v[158:161], v[196:199], v[122:125]
	v_mfma_f32_16x16x32_bf16 v[110:113], v[134:137], v[204:207], v[110:113]
	v_mfma_f32_16x16x32_bf16 v[106:109], v[158:161], v[204:207], v[106:109]
	v_mfma_f32_16x16x32_bf16 v[94:97], v[134:137], v[212:215], v[94:97]
	v_mfma_f32_16x16x32_bf16 v[90:93], v[158:161], v[212:215], v[90:93]
	v_mfma_f32_16x16x32_bf16 v[78:81], v[134:137], v[220:223], v[78:81]
	v_mfma_f32_16x16x32_bf16 v[74:77], v[158:161], v[220:223], v[74:77]
	s_setprio 0
	s_setprio 1
	v_mfma_f32_16x16x32_bf16 v[118:121], v[164:167], v[192:195], 0
	v_mfma_f32_16x16x32_bf16 v[114:117], v[184:187], v[192:195], 0
	v_mfma_f32_16x16x32_bf16 v[102:105], v[164:167], v[200:203], 0
	v_mfma_f32_16x16x32_bf16 v[98:101], v[184:187], v[200:203], 0
	v_mfma_f32_16x16x32_bf16 v[86:89], v[164:167], v[208:211], 0
	v_mfma_f32_16x16x32_bf16 v[82:85], v[184:187], v[208:211], 0
	v_mfma_f32_16x16x32_bf16 v[70:73], v[164:167], v[216:219], 0
	v_mfma_f32_16x16x32_bf16 v[66:69], v[184:187], v[216:219], 0
	v_mfma_f32_16x16x32_bf16 v[118:121], v[180:183], v[196:199], v[118:121]
	v_mfma_f32_16x16x32_bf16 v[114:117], v[188:191], v[196:199], v[114:117]
	v_mfma_f32_16x16x32_bf16 v[102:105], v[180:183], v[204:207], v[102:105]
	v_mfma_f32_16x16x32_bf16 v[98:101], v[188:191], v[204:207], v[98:101]
	v_mfma_f32_16x16x32_bf16 v[86:89], v[180:183], v[212:215], v[86:89]
	v_mfma_f32_16x16x32_bf16 v[82:85], v[188:191], v[212:215], v[82:85]
	s_setprio 2
	s_barrier
	v_mfma_f32_16x16x32_bf16 v[70:73], v[180:183], v[220:223], v[70:73]
	v_mfma_f32_16x16x32_bf16 v[66:69], v[188:191], v[220:223], v[66:69]
	s_setprio 0
	s_add_i32 s22, s48, s9
	v_lshl_add_u64 v[154:155], s[34:35], 0, v[162:163]
	s_mov_b32 m0, s22
	ds_read_b128 v[192:195], v157 offset:16384
	ds_read_b128 v[196:199], v157 offset:17408
	ds_read_b128 v[200:203], v157 offset:18432
	ds_read_b128 v[204:207], v157 offset:19456
	ds_read_b128 v[208:211], v157 offset:20480
	ds_read_b128 v[212:215], v157 offset:21504
	ds_read_b128 v[216:219], v157 offset:22528
	ds_read_b128 v[220:223], v157 offset:23552
	global_load_lds_dwordx4 v[154:155], off
	s_add_i32 m0, s22, 0x2000
	s_add_u32 s22, s34, 0x160000
	v_lshl_add_u64 v[168:169], s[34:35], 0, v[142:143]
	s_addc_u32 s23, s35, 0
	s_add_i32 s48, s49, s9
	global_load_lds_dwordx4 v[168:169], off
	v_lshl_add_u64 v[224:225], s[22:23], 0, v[162:163]
	s_mov_b32 m0, s48
	v_lshl_add_u64 v[226:227], s[38:39], 0, v[140:141]
	global_load_lds_dwordx4 v[224:225], off
	s_add_i32 m0, s48, 0x2000
	v_lshl_add_u64 v[224:225], s[22:23], 0, v[142:143]
	global_load_lds_dwordx4 v[224:225], off
	s_mov_b32 m0, s20
	v_lshl_add_u64 v[224:225], s[38:39], 0, v[138:139]
	global_load_lds_dwordx4 v[224:225], off
	s_mov_b32 m0, s25
	s_nop 0
	global_load_lds_dwordx4 v[226:227], off
	s_waitcnt vmcnt(8)
	s_waitcnt lgkmcnt(0)
	s_barrier
	s_setprio 1
	s_waitcnt lgkmcnt(0)
	v_mfma_f32_16x16x32_bf16 v[62:65], v[130:133], v[192:195], 0
	v_mfma_f32_16x16x32_bf16 v[58:61], v[150:153], v[192:195], 0
	v_mfma_f32_16x16x32_bf16 v[46:49], v[130:133], v[200:203], 0
	v_mfma_f32_16x16x32_bf16 v[42:45], v[150:153], v[200:203], 0
	v_mfma_f32_16x16x32_bf16 v[30:33], v[130:133], v[208:211], 0
	v_mfma_f32_16x16x32_bf16 v[26:29], v[150:153], v[208:211], 0
	v_mfma_f32_16x16x32_bf16 v[14:17], v[130:133], v[216:219], 0
	v_mfma_f32_16x16x32_bf16 v[10:13], v[150:153], v[216:219], 0
	v_mfma_f32_16x16x32_bf16 v[62:65], v[134:137], v[196:199], v[62:65]
	v_mfma_f32_16x16x32_bf16 v[58:61], v[158:161], v[196:199], v[58:61]
	v_mfma_f32_16x16x32_bf16 v[46:49], v[134:137], v[204:207], v[46:49]
	v_mfma_f32_16x16x32_bf16 v[42:45], v[158:161], v[204:207], v[42:45]
	v_mfma_f32_16x16x32_bf16 v[30:33], v[134:137], v[212:215], v[30:33]
	v_mfma_f32_16x16x32_bf16 v[26:29], v[158:161], v[212:215], v[26:29]
	v_mfma_f32_16x16x32_bf16 v[14:17], v[134:137], v[220:223], v[14:17]
	v_mfma_f32_16x16x32_bf16 v[10:13], v[158:161], v[220:223], v[10:13]
	s_setprio 0
	s_setprio 1
	v_mfma_f32_16x16x32_bf16 v[54:57], v[164:167], v[192:195], 0
	v_mfma_f32_16x16x32_bf16 v[50:53], v[184:187], v[192:195], 0
	v_mfma_f32_16x16x32_bf16 v[38:41], v[164:167], v[200:203], 0
	v_mfma_f32_16x16x32_bf16 v[34:37], v[184:187], v[200:203], 0
	v_mfma_f32_16x16x32_bf16 v[22:25], v[164:167], v[208:211], 0
	v_mfma_f32_16x16x32_bf16 v[18:21], v[184:187], v[208:211], 0
	v_mfma_f32_16x16x32_bf16 v[6:9], v[164:167], v[216:219], 0
	v_mfma_f32_16x16x32_bf16 v[2:5], v[184:187], v[216:219], 0
	v_mfma_f32_16x16x32_bf16 v[54:57], v[180:183], v[196:199], v[54:57]
	v_mfma_f32_16x16x32_bf16 v[50:53], v[188:191], v[196:199], v[50:53]
	v_mfma_f32_16x16x32_bf16 v[38:41], v[180:183], v[204:207], v[38:41]
	v_mfma_f32_16x16x32_bf16 v[34:37], v[188:191], v[204:207], v[34:37]
	v_mfma_f32_16x16x32_bf16 v[22:25], v[180:183], v[212:215], v[22:25]
	v_mfma_f32_16x16x32_bf16 v[18:21], v[188:191], v[212:215], v[18:21]
	s_setprio 2
	s_barrier
	v_mfma_f32_16x16x32_bf16 v[6:9], v[180:183], v[220:223], v[6:9]
	v_mfma_f32_16x16x32_bf16 v[2:5], v[188:191], v[220:223], v[2:5]
	s_setprio 0
	s_add_i32 s48, 0, 0x18000
	s_add_i32 s49, 0, 0x1c000
	v_add_u32_e32 v158, s48, v145
	v_add_u32_e32 v179, s49, v145
	ds_read_b128 v[130:133], v158
	ds_read_b128 v[134:137], v158 offset:1024
	ds_read_b128 v[150:153], v158 offset:2048
	ds_read_b128 v[158:161], v158 offset:3072
	ds_read_b128 v[164:167], v179
	ds_read_b128 v[180:183], v179 offset:1024
	ds_read_b128 v[184:187], v179 offset:2048
	ds_read_b128 v[188:191], v179 offset:3072
	s_add_u32 s22, s38, 0x160000
	s_addc_u32 s23, s39, 0
	s_mov_b32 m0, s26
	v_lshl_add_u64 v[228:229], s[22:23], 0, v[138:139]
	ds_read_b128 v[192:195], v157 offset:32768
	ds_read_b128 v[196:199], v157 offset:33792
	ds_read_b128 v[200:203], v157 offset:34816
	ds_read_b128 v[204:207], v157 offset:35840
	ds_read_b128 v[208:211], v157 offset:36864
	ds_read_b128 v[212:215], v157 offset:37888
	ds_read_b128 v[216:219], v157 offset:38912
	ds_read_b128 v[220:223], v157 offset:39936
	global_load_lds_dwordx4 v[228:229], off
	s_mov_b32 m0, s27
	v_lshl_add_u64 v[228:229], s[22:23], 0, v[140:141]
	global_load_lds_dwordx4 v[228:229], off
	s_waitcnt vmcnt(8)
	s_waitcnt lgkmcnt(0)
	s_barrier
	s_setprio 1
	s_waitcnt lgkmcnt(0)
	v_mfma_f32_16x16x32_bf16 v[126:129], v[130:133], v[192:195], v[126:129]
	v_mfma_f32_16x16x32_bf16 v[122:125], v[150:153], v[192:195], v[122:125]
	v_mfma_f32_16x16x32_bf16 v[110:113], v[130:133], v[200:203], v[110:113]
	v_mfma_f32_16x16x32_bf16 v[106:109], v[150:153], v[200:203], v[106:109]
	v_mfma_f32_16x16x32_bf16 v[94:97], v[130:133], v[208:211], v[94:97]
	v_mfma_f32_16x16x32_bf16 v[90:93], v[150:153], v[208:211], v[90:93]
	v_mfma_f32_16x16x32_bf16 v[78:81], v[130:133], v[216:219], v[78:81]
	v_mfma_f32_16x16x32_bf16 v[74:77], v[150:153], v[216:219], v[74:77]
	v_mfma_f32_16x16x32_bf16 v[126:129], v[134:137], v[196:199], v[126:129]
	v_mfma_f32_16x16x32_bf16 v[122:125], v[158:161], v[196:199], v[122:125]
	v_mfma_f32_16x16x32_bf16 v[110:113], v[134:137], v[204:207], v[110:113]
	v_mfma_f32_16x16x32_bf16 v[106:109], v[158:161], v[204:207], v[106:109]
	v_mfma_f32_16x16x32_bf16 v[94:97], v[134:137], v[212:215], v[94:97]
	v_mfma_f32_16x16x32_bf16 v[90:93], v[158:161], v[212:215], v[90:93]
	v_mfma_f32_16x16x32_bf16 v[78:81], v[134:137], v[220:223], v[78:81]
	v_mfma_f32_16x16x32_bf16 v[74:77], v[158:161], v[220:223], v[74:77]
	s_setprio 0
	s_setprio 1
	v_mfma_f32_16x16x32_bf16 v[118:121], v[164:167], v[192:195], v[118:121]
	v_mfma_f32_16x16x32_bf16 v[114:117], v[184:187], v[192:195], v[114:117]
	v_mfma_f32_16x16x32_bf16 v[102:105], v[164:167], v[200:203], v[102:105]
	v_mfma_f32_16x16x32_bf16 v[98:101], v[184:187], v[200:203], v[98:101]
	v_mfma_f32_16x16x32_bf16 v[86:89], v[164:167], v[208:211], v[86:89]
	v_mfma_f32_16x16x32_bf16 v[82:85], v[184:187], v[208:211], v[82:85]
	v_mfma_f32_16x16x32_bf16 v[70:73], v[164:167], v[216:219], v[70:73]
	v_mfma_f32_16x16x32_bf16 v[66:69], v[184:187], v[216:219], v[66:69]
	v_mfma_f32_16x16x32_bf16 v[118:121], v[180:183], v[196:199], v[118:121]
	v_mfma_f32_16x16x32_bf16 v[114:117], v[188:191], v[196:199], v[114:117]
	v_mfma_f32_16x16x32_bf16 v[102:105], v[180:183], v[204:207], v[102:105]
	v_mfma_f32_16x16x32_bf16 v[98:101], v[188:191], v[204:207], v[98:101]
	v_mfma_f32_16x16x32_bf16 v[86:89], v[180:183], v[212:215], v[86:89]
	v_mfma_f32_16x16x32_bf16 v[82:85], v[188:191], v[212:215], v[82:85]
	s_setprio 2
	s_barrier
	v_mfma_f32_16x16x32_bf16 v[70:73], v[180:183], v[220:223], v[70:73]
	v_mfma_f32_16x16x32_bf16 v[66:69], v[188:191], v[220:223], v[66:69]
	s_setprio 0
	s_add_i32 s22, s48, s9
	v_lshl_add_u64 v[154:155], v[154:155], 0, s[6:7]
	s_mov_b32 m0, s22
	ds_read_b128 v[192:195], v157 offset:49152
	ds_read_b128 v[196:199], v157 offset:50176
	ds_read_b128 v[200:203], v157 offset:51200
	ds_read_b128 v[204:207], v157 offset:52224
	ds_read_b128 v[208:211], v157 offset:53248
	ds_read_b128 v[212:215], v157 offset:54272
	ds_read_b128 v[216:219], v157 offset:55296
	ds_read_b128 v[220:223], v157 offset:56320
	global_load_lds_dwordx4 v[154:155], off
	s_add_i32 m0, s22, 0x2000
	s_add_u32 s22, s34, 0x160080
	v_lshl_add_u64 v[154:155], v[168:169], 0, s[6:7]
	s_addc_u32 s23, s35, 0
	s_add_i32 s34, s49, s9
	global_load_lds_dwordx4 v[154:155], off
	s_mov_b32 m0, s34
	v_lshl_add_u64 v[154:155], s[22:23], 0, v[162:163]
	global_load_lds_dwordx4 v[154:155], off
	s_add_i32 m0, s34, 0x2000
	v_lshl_add_u64 v[154:155], s[22:23], 0, v[142:143]
	global_load_lds_dwordx4 v[154:155], off
	s_mov_b32 m0, s40
	v_lshl_add_u64 v[154:155], v[224:225], 0, s[6:7]
	global_load_lds_dwordx4 v[154:155], off
	s_mov_b32 m0, s41
	v_lshl_add_u64 v[154:155], v[226:227], 0, s[6:7]
	global_load_lds_dwordx4 v[154:155], off
	s_waitcnt vmcnt(8)
	s_waitcnt lgkmcnt(0)
	s_barrier
	s_setprio 1
	s_waitcnt lgkmcnt(0)
	v_mfma_f32_16x16x32_bf16 v[62:65], v[130:133], v[192:195], v[62:65]
	v_mfma_f32_16x16x32_bf16 v[58:61], v[150:153], v[192:195], v[58:61]
	v_mfma_f32_16x16x32_bf16 v[46:49], v[130:133], v[200:203], v[46:49]
	v_mfma_f32_16x16x32_bf16 v[42:45], v[150:153], v[200:203], v[42:45]
	v_mfma_f32_16x16x32_bf16 v[30:33], v[130:133], v[208:211], v[30:33]
	v_mfma_f32_16x16x32_bf16 v[26:29], v[150:153], v[208:211], v[26:29]
	v_mfma_f32_16x16x32_bf16 v[14:17], v[130:133], v[216:219], v[14:17]
	v_mfma_f32_16x16x32_bf16 v[10:13], v[150:153], v[216:219], v[10:13]
	v_mfma_f32_16x16x32_bf16 v[62:65], v[134:137], v[196:199], v[62:65]
	v_mfma_f32_16x16x32_bf16 v[58:61], v[158:161], v[196:199], v[58:61]
	v_mfma_f32_16x16x32_bf16 v[46:49], v[134:137], v[204:207], v[46:49]
	v_mfma_f32_16x16x32_bf16 v[42:45], v[158:161], v[204:207], v[42:45]
	v_mfma_f32_16x16x32_bf16 v[30:33], v[134:137], v[212:215], v[30:33]
	v_mfma_f32_16x16x32_bf16 v[26:29], v[158:161], v[212:215], v[26:29]
	v_mfma_f32_16x16x32_bf16 v[14:17], v[134:137], v[220:223], v[14:17]
	v_mfma_f32_16x16x32_bf16 v[10:13], v[158:161], v[220:223], v[10:13]
	s_setprio 0
	s_setprio 1
	v_mfma_f32_16x16x32_bf16 v[54:57], v[164:167], v[192:195], v[54:57]
	v_mfma_f32_16x16x32_bf16 v[50:53], v[184:187], v[192:195], v[50:53]
	v_mfma_f32_16x16x32_bf16 v[38:41], v[164:167], v[200:203], v[38:41]
	v_mfma_f32_16x16x32_bf16 v[34:37], v[184:187], v[200:203], v[34:37]
	v_mfma_f32_16x16x32_bf16 v[22:25], v[164:167], v[208:211], v[22:25]
	v_mfma_f32_16x16x32_bf16 v[18:21], v[184:187], v[208:211], v[18:21]
	v_mfma_f32_16x16x32_bf16 v[6:9], v[164:167], v[216:219], v[6:9]
	v_mfma_f32_16x16x32_bf16 v[2:5], v[184:187], v[216:219], v[2:5]
	v_mfma_f32_16x16x32_bf16 v[54:57], v[180:183], v[196:199], v[54:57]
	v_mfma_f32_16x16x32_bf16 v[50:53], v[188:191], v[196:199], v[50:53]
	v_mfma_f32_16x16x32_bf16 v[38:41], v[180:183], v[204:207], v[38:41]
	v_mfma_f32_16x16x32_bf16 v[34:37], v[188:191], v[204:207], v[34:37]
	v_mfma_f32_16x16x32_bf16 v[22:25], v[180:183], v[212:215], v[22:25]
	v_mfma_f32_16x16x32_bf16 v[18:21], v[188:191], v[212:215], v[18:21]
	s_setprio 2
	s_barrier
	v_mfma_f32_16x16x32_bf16 v[6:9], v[180:183], v[220:223], v[6:9]
	v_mfma_f32_16x16x32_bf16 v[2:5], v[188:191], v[220:223], v[2:5]
	s_setprio 0
	s_add_i32 s47, s47, 2
	s_add_u32 s45, s45, 0x100
	s_addc_u32 s46, s46, 0
	s_cmpk_gt_u32 s47, 0x55
	s_mov_b64 s[22:23], s[28:29]
.LBB0_1874:
	s_add_u32 s28, s22, 0x100
	s_addc_u32 s29, s23, 0
	s_add_i32 s48, 0, 0x10000
	s_cmpk_eq_i32 s47, 0x54
	s_cselect_b32 s39, s5, s29
	s_cselect_b32 s38, s4, s28
	v_add_u32_e32 v154, s48, v145
	s_cselect_b32 s35, s19, s46
	s_cselect_b32 s34, s18, s45
	s_add_i32 s49, 0, 0x14000
	ds_read_b128 v[130:133], v154
	ds_read_b128 v[134:137], v154 offset:1024
	ds_read_b128 v[150:153], v154 offset:2048
	ds_read_b128 v[158:161], v154 offset:3072
	v_add_u32_e32 v154, s49, v145
	ds_read_b128 v[164:167], v154
	ds_read_b128 v[180:183], v154 offset:1024
	ds_read_b128 v[184:187], v154 offset:2048
	ds_read_b128 v[188:191], v154 offset:3072
	v_lshl_add_u64 v[154:155], s[22:23], 0, v[146:147]
	s_add_i32 m0, s20, 0xc000
	ds_read_b128 v[192:195], v157
	ds_read_b128 v[196:199], v157 offset:1024
	ds_read_b128 v[200:203], v157 offset:2048
	ds_read_b128 v[204:207], v157 offset:3072
	ds_read_b128 v[208:211], v157 offset:4096
	ds_read_b128 v[212:215], v157 offset:5120
	ds_read_b128 v[216:219], v157 offset:6144
	ds_read_b128 v[220:223], v157 offset:7168
	global_load_lds_dwordx4 v[154:155], off
	s_add_i32 m0, s20, 0xe000
	v_lshl_add_u64 v[154:155], s[22:23], 0, v[148:149]
	global_load_lds_dwordx4 v[154:155], off
	s_waitcnt vmcnt(8)
	s_waitcnt lgkmcnt(0)
	s_barrier
	s_setprio 1
	s_waitcnt lgkmcnt(0)
	v_mfma_f32_16x16x32_bf16 v[126:129], v[130:133], v[192:195], v[126:129]
	v_mfma_f32_16x16x32_bf16 v[122:125], v[150:153], v[192:195], v[122:125]
	v_mfma_f32_16x16x32_bf16 v[110:113], v[130:133], v[200:203], v[110:113]
	v_mfma_f32_16x16x32_bf16 v[106:109], v[150:153], v[200:203], v[106:109]
	v_mfma_f32_16x16x32_bf16 v[94:97], v[130:133], v[208:211], v[94:97]
	v_mfma_f32_16x16x32_bf16 v[90:93], v[150:153], v[208:211], v[90:93]
	v_mfma_f32_16x16x32_bf16 v[78:81], v[130:133], v[216:219], v[78:81]
	v_mfma_f32_16x16x32_bf16 v[74:77], v[150:153], v[216:219], v[74:77]
	v_mfma_f32_16x16x32_bf16 v[126:129], v[134:137], v[196:199], v[126:129]
	v_mfma_f32_16x16x32_bf16 v[122:125], v[158:161], v[196:199], v[122:125]
	v_mfma_f32_16x16x32_bf16 v[110:113], v[134:137], v[204:207], v[110:113]
	v_mfma_f32_16x16x32_bf16 v[106:109], v[158:161], v[204:207], v[106:109]
	v_mfma_f32_16x16x32_bf16 v[94:97], v[134:137], v[212:215], v[94:97]
	v_mfma_f32_16x16x32_bf16 v[90:93], v[158:161], v[212:215], v[90:93]
	v_mfma_f32_16x16x32_bf16 v[78:81], v[134:137], v[220:223], v[78:81]
	v_mfma_f32_16x16x32_bf16 v[74:77], v[158:161], v[220:223], v[74:77]
	s_setprio 0
	s_setprio 1
	v_mfma_f32_16x16x32_bf16 v[118:121], v[164:167], v[192:195], v[118:121]
	v_mfma_f32_16x16x32_bf16 v[114:117], v[184:187], v[192:195], v[114:117]
	v_mfma_f32_16x16x32_bf16 v[102:105], v[164:167], v[200:203], v[102:105]
	v_mfma_f32_16x16x32_bf16 v[98:101], v[184:187], v[200:203], v[98:101]
	v_mfma_f32_16x16x32_bf16 v[86:89], v[164:167], v[208:211], v[86:89]
	v_mfma_f32_16x16x32_bf16 v[82:85], v[184:187], v[208:211], v[82:85]
	v_mfma_f32_16x16x32_bf16 v[70:73], v[164:167], v[216:219], v[70:73]
	v_mfma_f32_16x16x32_bf16 v[66:69], v[184:187], v[216:219], v[66:69]
	v_mfma_f32_16x16x32_bf16 v[118:121], v[180:183], v[196:199], v[118:121]
	v_mfma_f32_16x16x32_bf16 v[114:117], v[188:191], v[196:199], v[114:117]
	v_mfma_f32_16x16x32_bf16 v[102:105], v[180:183], v[204:207], v[102:105]
	v_mfma_f32_16x16x32_bf16 v[98:101], v[188:191], v[204:207], v[98:101]
	v_mfma_f32_16x16x32_bf16 v[86:89], v[180:183], v[212:215], v[86:89]
	v_mfma_f32_16x16x32_bf16 v[82:85], v[188:191], v[212:215], v[82:85]
	s_setprio 2
	s_barrier
	v_mfma_f32_16x16x32_bf16 v[70:73], v[180:183], v[220:223], v[70:73]
	v_mfma_f32_16x16x32_bf16 v[66:69], v[188:191], v[220:223], v[66:69]
	s_setprio 0
	s_add_i32 s22, s48, s9
	v_lshl_add_u64 v[154:155], s[34:35], 0, v[162:163]
	s_mov_b32 m0, s22
	ds_read_b128 v[192:195], v157 offset:16384
	ds_read_b128 v[196:199], v157 offset:17408
	ds_read_b128 v[200:203], v157 offset:18432
	ds_read_b128 v[204:207], v157 offset:19456
	ds_read_b128 v[208:211], v157 offset:20480
	ds_read_b128 v[212:215], v157 offset:21504
	ds_read_b128 v[216:219], v157 offset:22528
	ds_read_b128 v[220:223], v157 offset:23552
	global_load_lds_dwordx4 v[154:155], off
	s_add_i32 m0, s22, 0x2000
	s_add_u32 s22, s34, 0x160000
	v_lshl_add_u64 v[168:169], s[34:35], 0, v[142:143]
	s_addc_u32 s23, s35, 0
	s_add_i32 s48, s49, s9
	global_load_lds_dwordx4 v[168:169], off
	v_lshl_add_u64 v[224:225], s[22:23], 0, v[162:163]
	s_mov_b32 m0, s48
	v_lshl_add_u64 v[226:227], s[38:39], 0, v[140:141]
	global_load_lds_dwordx4 v[224:225], off
	s_add_i32 m0, s48, 0x2000
	v_lshl_add_u64 v[224:225], s[22:23], 0, v[142:143]
	global_load_lds_dwordx4 v[224:225], off
	s_mov_b32 m0, s20
	v_lshl_add_u64 v[224:225], s[38:39], 0, v[138:139]
	global_load_lds_dwordx4 v[224:225], off
	s_mov_b32 m0, s25
	s_nop 0
	global_load_lds_dwordx4 v[226:227], off
	s_waitcnt vmcnt(8)
	s_waitcnt lgkmcnt(0)
	s_barrier
	s_setprio 1
	s_waitcnt lgkmcnt(0)
	v_mfma_f32_16x16x32_bf16 v[62:65], v[130:133], v[192:195], v[62:65]
	v_mfma_f32_16x16x32_bf16 v[58:61], v[150:153], v[192:195], v[58:61]
	v_mfma_f32_16x16x32_bf16 v[46:49], v[130:133], v[200:203], v[46:49]
	v_mfma_f32_16x16x32_bf16 v[42:45], v[150:153], v[200:203], v[42:45]
	v_mfma_f32_16x16x32_bf16 v[30:33], v[130:133], v[208:211], v[30:33]
	v_mfma_f32_16x16x32_bf16 v[26:29], v[150:153], v[208:211], v[26:29]
	v_mfma_f32_16x16x32_bf16 v[14:17], v[130:133], v[216:219], v[14:17]
	v_mfma_f32_16x16x32_bf16 v[10:13], v[150:153], v[216:219], v[10:13]
	v_mfma_f32_16x16x32_bf16 v[62:65], v[134:137], v[196:199], v[62:65]
	v_mfma_f32_16x16x32_bf16 v[58:61], v[158:161], v[196:199], v[58:61]
	v_mfma_f32_16x16x32_bf16 v[46:49], v[134:137], v[204:207], v[46:49]
	v_mfma_f32_16x16x32_bf16 v[42:45], v[158:161], v[204:207], v[42:45]
	v_mfma_f32_16x16x32_bf16 v[30:33], v[134:137], v[212:215], v[30:33]
	v_mfma_f32_16x16x32_bf16 v[26:29], v[158:161], v[212:215], v[26:29]
	v_mfma_f32_16x16x32_bf16 v[14:17], v[134:137], v[220:223], v[14:17]
	v_mfma_f32_16x16x32_bf16 v[10:13], v[158:161], v[220:223], v[10:13]
	s_setprio 0
	s_setprio 1
	v_mfma_f32_16x16x32_bf16 v[54:57], v[164:167], v[192:195], v[54:57]
	v_mfma_f32_16x16x32_bf16 v[50:53], v[184:187], v[192:195], v[50:53]
	v_mfma_f32_16x16x32_bf16 v[38:41], v[164:167], v[200:203], v[38:41]
	v_mfma_f32_16x16x32_bf16 v[34:37], v[184:187], v[200:203], v[34:37]
	v_mfma_f32_16x16x32_bf16 v[22:25], v[164:167], v[208:211], v[22:25]
	v_mfma_f32_16x16x32_bf16 v[18:21], v[184:187], v[208:211], v[18:21]
	v_mfma_f32_16x16x32_bf16 v[6:9], v[164:167], v[216:219], v[6:9]
	v_mfma_f32_16x16x32_bf16 v[2:5], v[184:187], v[216:219], v[2:5]
	v_mfma_f32_16x16x32_bf16 v[54:57], v[180:183], v[196:199], v[54:57]
	v_mfma_f32_16x16x32_bf16 v[50:53], v[188:191], v[196:199], v[50:53]
	v_mfma_f32_16x16x32_bf16 v[38:41], v[180:183], v[204:207], v[38:41]
	v_mfma_f32_16x16x32_bf16 v[34:37], v[188:191], v[204:207], v[34:37]
	v_mfma_f32_16x16x32_bf16 v[22:25], v[180:183], v[212:215], v[22:25]
	v_mfma_f32_16x16x32_bf16 v[18:21], v[188:191], v[212:215], v[18:21]
	s_setprio 2
	s_barrier
	v_mfma_f32_16x16x32_bf16 v[6:9], v[180:183], v[220:223], v[6:9]
	v_mfma_f32_16x16x32_bf16 v[2:5], v[188:191], v[220:223], v[2:5]
	s_setprio 0
	s_add_i32 s48, 0, 0x18000
	s_add_i32 s49, 0, 0x1c000
	v_add_u32_e32 v158, s48, v145
	v_add_u32_e32 v179, s49, v145
	ds_read_b128 v[130:133], v158
	ds_read_b128 v[134:137], v158 offset:1024
	ds_read_b128 v[150:153], v158 offset:2048
	ds_read_b128 v[158:161], v158 offset:3072
	ds_read_b128 v[164:167], v179
	ds_read_b128 v[180:183], v179 offset:1024
	ds_read_b128 v[184:187], v179 offset:2048
	ds_read_b128 v[188:191], v179 offset:3072
	s_add_u32 s22, s38, 0x160000
	s_addc_u32 s23, s39, 0
	s_mov_b32 m0, s26
	v_lshl_add_u64 v[228:229], s[22:23], 0, v[138:139]
	ds_read_b128 v[192:195], v157 offset:32768
	ds_read_b128 v[196:199], v157 offset:33792
	ds_read_b128 v[200:203], v157 offset:34816
	ds_read_b128 v[204:207], v157 offset:35840
	ds_read_b128 v[208:211], v157 offset:36864
	ds_read_b128 v[212:215], v157 offset:37888
	ds_read_b128 v[216:219], v157 offset:38912
	ds_read_b128 v[220:223], v157 offset:39936
	global_load_lds_dwordx4 v[228:229], off
	s_mov_b32 m0, s27
	v_lshl_add_u64 v[228:229], s[22:23], 0, v[140:141]
	global_load_lds_dwordx4 v[228:229], off
	s_waitcnt vmcnt(8)
	s_waitcnt lgkmcnt(0)
	s_barrier
	s_setprio 1
	s_waitcnt lgkmcnt(0)
	v_mfma_f32_16x16x32_bf16 v[126:129], v[130:133], v[192:195], v[126:129]
	v_mfma_f32_16x16x32_bf16 v[122:125], v[150:153], v[192:195], v[122:125]
	v_mfma_f32_16x16x32_bf16 v[110:113], v[130:133], v[200:203], v[110:113]
	v_mfma_f32_16x16x32_bf16 v[106:109], v[150:153], v[200:203], v[106:109]
	v_mfma_f32_16x16x32_bf16 v[94:97], v[130:133], v[208:211], v[94:97]
	v_mfma_f32_16x16x32_bf16 v[90:93], v[150:153], v[208:211], v[90:93]
	v_mfma_f32_16x16x32_bf16 v[78:81], v[130:133], v[216:219], v[78:81]
	v_mfma_f32_16x16x32_bf16 v[74:77], v[150:153], v[216:219], v[74:77]
	v_mfma_f32_16x16x32_bf16 v[126:129], v[134:137], v[196:199], v[126:129]
	v_mfma_f32_16x16x32_bf16 v[122:125], v[158:161], v[196:199], v[122:125]
	v_mfma_f32_16x16x32_bf16 v[110:113], v[134:137], v[204:207], v[110:113]
	v_mfma_f32_16x16x32_bf16 v[106:109], v[158:161], v[204:207], v[106:109]
	v_mfma_f32_16x16x32_bf16 v[94:97], v[134:137], v[212:215], v[94:97]
	v_mfma_f32_16x16x32_bf16 v[90:93], v[158:161], v[212:215], v[90:93]
	v_mfma_f32_16x16x32_bf16 v[78:81], v[134:137], v[220:223], v[78:81]
	v_mfma_f32_16x16x32_bf16 v[74:77], v[158:161], v[220:223], v[74:77]
	s_setprio 0
	s_setprio 1
	v_mfma_f32_16x16x32_bf16 v[118:121], v[164:167], v[192:195], v[118:121]
	v_mfma_f32_16x16x32_bf16 v[114:117], v[184:187], v[192:195], v[114:117]
	v_mfma_f32_16x16x32_bf16 v[102:105], v[164:167], v[200:203], v[102:105]
	v_mfma_f32_16x16x32_bf16 v[98:101], v[184:187], v[200:203], v[98:101]
	v_mfma_f32_16x16x32_bf16 v[86:89], v[164:167], v[208:211], v[86:89]
	v_mfma_f32_16x16x32_bf16 v[82:85], v[184:187], v[208:211], v[82:85]
	v_mfma_f32_16x16x32_bf16 v[70:73], v[164:167], v[216:219], v[70:73]
	v_mfma_f32_16x16x32_bf16 v[66:69], v[184:187], v[216:219], v[66:69]
	v_mfma_f32_16x16x32_bf16 v[118:121], v[180:183], v[196:199], v[118:121]
	v_mfma_f32_16x16x32_bf16 v[114:117], v[188:191], v[196:199], v[114:117]
	v_mfma_f32_16x16x32_bf16 v[102:105], v[180:183], v[204:207], v[102:105]
	v_mfma_f32_16x16x32_bf16 v[98:101], v[188:191], v[204:207], v[98:101]
	v_mfma_f32_16x16x32_bf16 v[86:89], v[180:183], v[212:215], v[86:89]
	v_mfma_f32_16x16x32_bf16 v[82:85], v[188:191], v[212:215], v[82:85]
	s_setprio 2
	s_barrier
	v_mfma_f32_16x16x32_bf16 v[70:73], v[180:183], v[220:223], v[70:73]
	v_mfma_f32_16x16x32_bf16 v[66:69], v[188:191], v[220:223], v[66:69]
	s_setprio 0
	s_add_i32 s22, s48, s9
	v_lshl_add_u64 v[154:155], v[154:155], 0, s[6:7]
	s_mov_b32 m0, s22
	ds_read_b128 v[192:195], v157 offset:49152
	ds_read_b128 v[196:199], v157 offset:50176
	ds_read_b128 v[200:203], v157 offset:51200
	ds_read_b128 v[204:207], v157 offset:52224
	ds_read_b128 v[208:211], v157 offset:53248
	ds_read_b128 v[212:215], v157 offset:54272
	ds_read_b128 v[216:219], v157 offset:55296
	ds_read_b128 v[220:223], v157 offset:56320
	global_load_lds_dwordx4 v[154:155], off
	s_add_i32 m0, s22, 0x2000
	s_add_u32 s22, s34, 0x160080
	v_lshl_add_u64 v[154:155], v[168:169], 0, s[6:7]
	s_addc_u32 s23, s35, 0
	s_add_i32 s34, s49, s9
	global_load_lds_dwordx4 v[154:155], off
	s_mov_b32 m0, s34
	v_lshl_add_u64 v[154:155], s[22:23], 0, v[162:163]
	global_load_lds_dwordx4 v[154:155], off
	s_add_i32 m0, s34, 0x2000
	v_lshl_add_u64 v[154:155], s[22:23], 0, v[142:143]
	global_load_lds_dwordx4 v[154:155], off
	s_mov_b32 m0, s40
	v_lshl_add_u64 v[154:155], v[224:225], 0, s[6:7]
	global_load_lds_dwordx4 v[154:155], off
	s_mov_b32 m0, s41
	v_lshl_add_u64 v[154:155], v[226:227], 0, s[6:7]
	global_load_lds_dwordx4 v[154:155], off
	s_waitcnt vmcnt(8)
	s_waitcnt lgkmcnt(0)
	s_barrier
	s_setprio 1
	s_waitcnt lgkmcnt(0)
	v_mfma_f32_16x16x32_bf16 v[62:65], v[130:133], v[192:195], v[62:65]
	v_mfma_f32_16x16x32_bf16 v[58:61], v[150:153], v[192:195], v[58:61]
	v_mfma_f32_16x16x32_bf16 v[46:49], v[130:133], v[200:203], v[46:49]
	v_mfma_f32_16x16x32_bf16 v[42:45], v[150:153], v[200:203], v[42:45]
	v_mfma_f32_16x16x32_bf16 v[30:33], v[130:133], v[208:211], v[30:33]
	v_mfma_f32_16x16x32_bf16 v[26:29], v[150:153], v[208:211], v[26:29]
	v_mfma_f32_16x16x32_bf16 v[14:17], v[130:133], v[216:219], v[14:17]
	v_mfma_f32_16x16x32_bf16 v[10:13], v[150:153], v[216:219], v[10:13]
	v_mfma_f32_16x16x32_bf16 v[62:65], v[134:137], v[196:199], v[62:65]
	v_mfma_f32_16x16x32_bf16 v[58:61], v[158:161], v[196:199], v[58:61]
	v_mfma_f32_16x16x32_bf16 v[46:49], v[134:137], v[204:207], v[46:49]
	v_mfma_f32_16x16x32_bf16 v[42:45], v[158:161], v[204:207], v[42:45]
	v_mfma_f32_16x16x32_bf16 v[30:33], v[134:137], v[212:215], v[30:33]
	v_mfma_f32_16x16x32_bf16 v[26:29], v[158:161], v[212:215], v[26:29]
	v_mfma_f32_16x16x32_bf16 v[14:17], v[134:137], v[220:223], v[14:17]
	v_mfma_f32_16x16x32_bf16 v[10:13], v[158:161], v[220:223], v[10:13]
	s_setprio 0
	s_setprio 1
	v_mfma_f32_16x16x32_bf16 v[54:57], v[164:167], v[192:195], v[54:57]
	v_mfma_f32_16x16x32_bf16 v[50:53], v[184:187], v[192:195], v[50:53]
	v_mfma_f32_16x16x32_bf16 v[38:41], v[164:167], v[200:203], v[38:41]
	v_mfma_f32_16x16x32_bf16 v[34:37], v[184:187], v[200:203], v[34:37]
	v_mfma_f32_16x16x32_bf16 v[22:25], v[164:167], v[208:211], v[22:25]
	v_mfma_f32_16x16x32_bf16 v[18:21], v[184:187], v[208:211], v[18:21]
	v_mfma_f32_16x16x32_bf16 v[6:9], v[164:167], v[216:219], v[6:9]
	v_mfma_f32_16x16x32_bf16 v[2:5], v[184:187], v[216:219], v[2:5]
	v_mfma_f32_16x16x32_bf16 v[54:57], v[180:183], v[196:199], v[54:57]
	v_mfma_f32_16x16x32_bf16 v[50:53], v[188:191], v[196:199], v[50:53]
	v_mfma_f32_16x16x32_bf16 v[38:41], v[180:183], v[204:207], v[38:41]
	v_mfma_f32_16x16x32_bf16 v[34:37], v[188:191], v[204:207], v[34:37]
	v_mfma_f32_16x16x32_bf16 v[22:25], v[180:183], v[212:215], v[22:25]
	v_mfma_f32_16x16x32_bf16 v[18:21], v[188:191], v[212:215], v[18:21]
	s_setprio 2
	s_barrier
	v_mfma_f32_16x16x32_bf16 v[6:9], v[180:183], v[220:223], v[6:9]
	v_mfma_f32_16x16x32_bf16 v[2:5], v[188:191], v[220:223], v[2:5]
	s_setprio 0
	s_add_i32 s47, s47, 2
	s_add_u32 s45, s45, 0x100
	s_addc_u32 s46, s46, 0
	s_cmpk_gt_u32 s47, 0x55
	s_mov_b64 s[22:23], s[28:29]
	s_cbranch_scc0 .LBB0_1874
	s_and_b64 vcc, exec, s[2:3]
	s_cbranch_vccz .LBB0_1877
	s_barrier
